# 8-phase GEMM loops: M0 for LDS-DMA pieces written early (before the fragment reads / right after the previous piece), wait-state nops dropped
# baseline (speedup 1.0000x reference)
; DI int opaque_tid() { int t = threadIdx.x; asm volatile("" : "+v"(t)); return t; }
; template <bool SWAP>
; DI void gemm_mainloop(f32x16 (&acc)[4][2], const u16* __restrict__ A, int lda, int rlo, int rhi,
;                       const u16* __restrict__ B, int ldb, int K, char* lds, const u16* zero_line) {
;   const int tid = opaque_tid(), lane = tid & 63, w = tid >> 6;
;   const int wm = w >> 2, wn = w & 3;
;   const int h = lane >> 5, r = lane & 31;
;   const int lr = tid >> 3, lc = tid & 7;
; #pragma unroll
;   for (int mi = 0; mi < 4; ++mi)
; #pragma unroll
;     for (int ni = 0; ni < 2; ++ni)
; #pragma unroll
;       for (int i = 0; i < 16; ++i) acc[mi][ni][i] = 0.f;
;   const int gch = (lc ^ ((lr >> 1) & 7)) * 8;
;   const u16* ap = A + (ptrdiff_t)lr * lda + gch;
;   const u16* bp = B + (ptrdiff_t)lr * ldb + gch;
;   const int nk = K >> 6;
;   typedef __attribute__((address_space(3))) unsigned lds_u32;
;   auto glds = [&](int kt, int st) {
;     char* as_ = lds + st * 65536 + tid * 16;
; #pragma unroll
;     for (int i = 0; i < 4; ++i) {
;       const int rr = lr + 64 * i;
;       const u16* srca = (rr >= rlo && rr < rhi) ? (ap + (ptrdiff_t)(64 * i) * lda + kt * 64) : (zero_line + lc * 8);
;       __builtin_amdgcn_global_load_lds((const unsigned*)srca, (lds_u32*)(as_ + i * 8192), 16, 0, 0);
;       __builtin_amdgcn_global_load_lds((const unsigned*)(bp + (ptrdiff_t)(64 * i) * ldb + kt * 64), (lds_u32*)(as_ + 32768 + i * 8192), 16, 0, 0);
;     }
;   };
; template <int EPI>
; DI void phase_gemm(const Params& p, const GemmArgs& ga, char* lds) {
;     ...
;   for (int it = 0; it * (int)gridDim.x < total; ++it) {
;     const int lt = logical_index(it);
;     if (lt >= total) continue;
;     int mt, nt;
;     tile_mn(lt, Mt, ga.Nt, mt, nt);
;     int bb, tokbase, S, pos0, rlo = 0, rhi = 256;
;     if (EPI == EPI_UP) {
;       bb = 0; tokbase = 0; S = NTOK;
;       pos0 = 254 * mt - 1;
;       rlo = (mt == 0) ? 1 : 0;
;       rhi = NTOK - pos0; if (rhi > 256) rhi = 256;
;     } else {
;       seq_of_token(mt * 256, bb, tokbase, S);
;       pos0 = mt * 256 - tokbase;
;     }
;     const u16* A = ga.A + (ptrdiff_t)(tokbase + pos0) * ga.lda;
;     const u16* B = ga.Bt + (size_t)(nt * 256) * ga.K;
.LBB0_56:
	s_add_i32 s30, s10, s25
	s_cmpk_gt_i32 s30, 0x10ab
	s_cbranch_scc1 .LBB0_55
	s_mul_hi_i32 s10, s30, 0x2e8ba2e9
	s_lshr_b32 s11, s10, 31
	s_ashr_i32 s10, s10, 5
	s_add_i32 s31, s10, s11
	s_lshl_b32 s10, s31, 3
	s_sub_i32 s11, 0xc2, s10
	s_min_u32 s11, s11, 8
	v_cvt_f32_ubyte0_e32 v0, s11
	v_rcp_iflag_f32_e32 v0, v0
	s_sub_i32 s15, 0, s11
	s_mul_i32 s12, s31, 0xffffff50
	s_add_i32 s12, s12, s30
	v_mul_f32_e32 v0, 0x4f7ffffe, v0
	v_cvt_u32_f32_e32 v0, v0
	s_abs_i32 s14, s12
	s_ashr_i32 s13, s12, 31
	s_waitcnt vmcnt(5)
	v_mov_b32_e32 v13, v204
	v_readfirstlane_b32 s16, v0
	s_mul_i32 s15, s15, s16
	s_mul_hi_u32 s15, s16, s15
	s_add_i32 s16, s16, s15
	s_mul_hi_u32 s15, s14, s16
	s_mul_i32 s16, s15, s11
	s_sub_i32 s14, s14, s16
	s_add_i32 s16, s15, 1
	s_sub_i32 s17, s14, s11
	s_cmp_ge_u32 s14, s11
	s_cselect_b32 s15, s16, s15
	s_cselect_b32 s14, s17, s14
	s_add_i32 s16, s15, 1
	s_cmp_ge_u32 s14, s11
	s_cselect_b32 s14, s16, s15
	s_xor_b32 s14, s14, s13
	s_sub_i32 s28, s14, s13
	s_mul_i32 s34, s28, s11
	s_add_i32 s14, s12, s10
	s_sub_i32 s27, s14, s34
	s_mulk_i32 s27, 0xfe
	s_lshl_b32 s10, s28, 8
	s_add_i32 s20, s27, -1
	s_ashr_i32 s11, s10, 31
	s_ashr_i32 s21, s20, 31
	s_lshl_b64 s[22:23], s[10:11], 11
	v_readlane_b32 s10, v253, 17
	v_readlane_b32 s11, v253, 18
	s_add_u32 s10, s10, s22
	s_addc_u32 s11, s11, s23
	s_lshl_b64 s[12:13], s[20:21], 11
	s_add_u32 s12, s90, s12
	v_ashrrev_i32_e32 v2, 3, v13
	s_waitcnt vmcnt(4)
	v_lshrrev_b32_e32 v15, 1, v2
	s_addc_u32 s13, s91, s13
	s_sub_i32 s15, 0xc001, s27
	v_xor_b32_e32 v0, v15, v13
	v_ashrrev_i32_e32 v3, 31, v2
	s_min_i32 s18, s15, 0x100
	v_lshlrev_b64 v[4:5], 11, v[2:3]
	v_lshlrev_b32_e32 v0, 4, v0
	s_cmp_eq_u32 s14, s34
	v_and_b32_e32 v10, 31, v13
	v_lshl_add_u64 v[6:7], s[12:13], 0, v[4:5]
	v_and_b32_e32 v0, 0x70, v0
	v_lshl_add_u64 v[8:9], s[10:11], 0, v[4:5]
	v_lshrrev_b32_e32 v16, 1, v13
	s_cselect_b64 s[14:15], -1, 0
	v_lshl_add_u64 v[6:7], v[6:7], 0, v[0:1]
	v_lshl_add_u64 v[8:9], v[8:9], 0, v[0:1]
	v_and_or_b32 v0, v16, s51, v10
	v_cndmask_b32_e64 v12, 0, 1, s[14:15]
	v_lshlrev_b32_e32 v175, 7, v0
	v_lshlrev_b32_e32 v0, 7, v13
	v_lshlrev_b32_e32 v177, 4, v13
	v_and_b32_e32 v176, 0x6f80, v0
	v_cmp_ge_i32_e64 s[10:11], v2, v12
	v_cmp_gt_i32_e64 s[12:13], s18, v2
	v_and_b32_e32 v0, 0x70, v177
	v_add_u32_e32 v178, 0x8000, v177
	v_lshl_add_u64 v[158:159], s[80:81], 0, v[0:1]
	s_and_b64 s[10:11], s[10:11], s[12:13]
	v_readfirstlane_b32 s12, v177
	v_cndmask_b32_e64 v11, v159, v7, s[10:11]
	v_cndmask_b32_e64 v10, v158, v6, s[10:11]
	s_mov_b32 m0, s12
	v_readfirstlane_b32 s12, v178
	v_add_u32_e32 v0, 64, v2
	s_barrier
	s_mov_b32 m0, s12
	v_cmp_ge_i32_e64 s[12:13], v0, v12
	v_cmp_gt_i32_e64 s[14:15], s18, v0
	s_mov_b64 s[16:17], 0x20000
	v_add_u32_e32 v0, 0x2000, v177
	v_lshl_add_u64 v[10:11], v[6:7], 0, s[16:17]
	s_and_b64 s[12:13], s[12:13], s[14:15]
	v_readfirstlane_b32 s14, v0
	v_add_u32_e32 v179, 0xa000, v177
	v_cndmask_b32_e64 v11, v159, v11, s[12:13]
	v_cndmask_b32_e64 v10, v158, v10, s[12:13]
	s_mov_b32 m0, s14
	v_readfirstlane_b32 s14, v179
	v_add_u32_e32 v3, 0x80, v2
	v_lshl_add_u64 v[10:11], v[8:9], 0, s[16:17]
	s_mov_b32 m0, s14
	v_cmp_ge_i32_e64 s[14:15], v3, v12
	v_cmp_gt_i32_e64 s[16:17], s18, v3
	s_mov_b64 s[38:39], 0x40000
	v_add_u32_e32 v180, 0x4000, v177
	v_lshl_add_u64 v[10:11], v[6:7], 0, s[38:39]
	s_and_b64 s[14:15], s[14:15], s[16:17]
	v_readfirstlane_b32 s16, v180
	v_add_u32_e32 v181, 0xc000, v177
	v_cndmask_b32_e64 v11, v159, v11, s[14:15]
	v_cndmask_b32_e64 v10, v158, v10, s[14:15]
	s_mov_b32 m0, s16
	v_readfirstlane_b32 s16, v181
	v_add_u32_e32 v2, 0xc0, v2
	v_lshl_add_u64 v[10:11], v[8:9], 0, s[38:39]
	s_mov_b32 m0, s16
	v_cmp_ge_i32_e64 s[16:17], v2, v12
	v_cmp_gt_i32_e64 s[18:19], s18, v2
	s_mov_b64 s[38:39], 0x60000
	v_add_u32_e32 v182, 0x6000, v177
	v_lshl_add_u64 v[2:3], v[6:7], 0, s[38:39]
	s_and_b64 s[16:17], s[16:17], s[18:19]
	v_readfirstlane_b32 s18, v182
	v_add_u32_e32 v183, 0xe000, v177
	v_cndmask_b32_e64 v3, v159, v3, s[16:17]
	v_cndmask_b32_e64 v2, v158, v2, s[16:17]
	s_mov_b32 m0, s18
	v_readfirstlane_b32 s18, v183
	v_lshl_add_u64 v[2:3], v[8:9], 0, s[38:39]
	s_mov_b32 m0, s18
	s_sub_i32 s18, s30, s34
	s_mulk_i32 s31, 0xa8
	v_bfe_u32 v14, v13, 5, 1
	s_sub_i32 s18, s18, s31
	v_bfe_u32 v17, v13, 1, 3
	v_bitop3_b32 v2, v16, v14, 7 bitop3:0x6c
	s_mulk_i32 s18, 0xfe
	v_lshlrev_b32_e32 v185, 4, v2
	v_bitop3_b32 v2, v14, v17, 2 bitop3:0x36
	s_add_i32 s18, s18, -2
	v_lshlrev_b32_e32 v186, 4, v2
	v_bitop3_b32 v2, v14, v17, 4 bitop3:0x36
	s_ashr_i32 s19, s18, 31
	v_lshlrev_b32_e32 v187, 4, v2
	v_bitop3_b32 v2, v14, v17, 6 bitop3:0x36
	s_lshl_b64 s[18:19], s[18:19], 11
	v_bitop3_b32 v6, v15, 7, v13 bitop3:0x48
	v_lshlrev_b32_e32 v188, 4, v2
	v_lshl_add_u64 v[2:3], v[4:5], 0, s[18:19]
	v_lshlrev_b32_e32 v6, 4, v6
	v_or_b32_e32 v2, v2, v6
	v_lshl_add_u64 v[160:161], s[70:71], 0, v[2:3]
	v_lshl_add_u64 v[2:3], v[4:5], 0, s[22:23]
	s_waitcnt vmcnt(0)
	v_or_b32_e32 v2, v2, v6
	v_lshl_add_u64 v[162:163], s[70:71], 0, v[2:3]
	v_mov_b32_e32 v130, 0
	v_mov_b32_e32 v2, 0
	s_mov_b32 s29, 1
	s_mov_b64 s[38:39], 0x3858900
	v_add_u32_e32 v189, 0x10000, v177
	v_add_u32_e32 v190, 0x18000, v177
	v_add_u32_e32 v191, 0x12000, v177
	v_add_u32_e32 v192, 0x1a000, v177
	v_add_u32_e32 v193, 0x14000, v177
	v_add_u32_e32 v194, 0x1c000, v177
	v_add_u32_e32 v195, 0x16000, v177
	v_add_u32_e32 v196, 0x1e000, v177
	v_add_u32_e32 v197, 0x10000, v175
	v_or_b32_e32 v198, 0x10000, v176
	s_mov_b64 s[18:19], 0
	v_mov_b32_e32 v3, v2
	v_mov_b32_e32 v4, v2
	v_mov_b32_e32 v5, v2
	v_mov_b32_e32 v6, v2
	v_mov_b32_e32 v7, v2
	v_mov_b32_e32 v8, v2
	v_mov_b32_e32 v9, v2
	v_mov_b32_e32 v10, v2
	v_mov_b32_e32 v11, v2
	v_mov_b32_e32 v12, v2
	v_mov_b32_e32 v13, v2
	v_mov_b32_e32 v14, v2
	v_mov_b32_e32 v15, v2
	v_mov_b32_e32 v16, v2
	v_mov_b32_e32 v17, v2
	s_waitcnt vmcnt(0)
; template <bool SWAP>
; DI void gemm_mainloop(f32x16 (&acc)[4][2], const u16* __restrict__ A, int lda, int rlo, int rhi,
;                       const u16* __restrict__ B, int ldb, int K, char* lds, const u16* zero_line) {
;     ...
; #pragma unroll
;   for (int mi = 0; mi < 4; ++mi)
; #pragma unroll
;     for (int ni = 0; ni < 2; ++ni)
; #pragma unroll
;       for (int i = 0; i < 16; ++i) acc[mi][ni][i] = 0.f;
;   const int gch = (lc ^ ((lr >> 1) & 7)) * 8;
;   const u16* ap = A + (ptrdiff_t)lr * lda + gch;
;   const u16* bp = B + (ptrdiff_t)lr * ldb + gch;
;   const int nk = K >> 6;
;   typedef __attribute__((address_space(3))) unsigned lds_u32;
;   auto glds = [&](int kt, int st) {
;     char* as_ = lds + st * 65536 + tid * 16;
; #pragma unroll
;     for (int i = 0; i < 4; ++i) {
;       const int rr = lr + 64 * i;
;       const u16* srca = (rr >= rlo && rr < rhi) ? (ap + (ptrdiff_t)(64 * i) * lda + kt * 64) : (zero_line + lc * 8);
;       __builtin_amdgcn_global_load_lds((const unsigned*)srca, (lds_u32*)(as_ + i * 8192), 16, 0, 0);
;       __builtin_amdgcn_global_load_lds((const unsigned*)(bp + (ptrdiff_t)(64 * i) * ldb + kt * 64), (lds_u32*)(as_ + 32768 + i * 8192), 16, 0, 0);
;     }
;   };
;   const int sw = (r >> 1) & 7;
;   const int arow_off = (wm * 128 + r) * 128;
;   const int brow_off = 32768 + (wn * 64 + r) * 128;
;   __syncthreads();
;   glds(0, 0);
;   asm volatile("s_waitcnt vmcnt(0)" ::: "memory");
;   __syncthreads();
;   bf16x8 fa[2][4], fb[2][2];
; #pragma unroll
;   for (int mi = 0; mi < 4; ++mi)
; #pragma unroll
;     for (int e = 0; e < 8; ++e) fa[1][mi][e] = 0;
; #pragma unroll
;   for (int ni = 0; ni < 2; ++ni)
; #pragma unroll
;     for (int e = 0; e < 8; ++e) fb[1][ni][e] = 0;
	v_mov_b32_e32 v18, v2
	v_mov_b32_e32 v19, v2
	v_mov_b32_e32 v20, v2
	v_mov_b32_e32 v21, v2
	v_mov_b32_e32 v22, v2
	v_mov_b32_e32 v23, v2
	v_mov_b32_e32 v24, v2
	v_mov_b32_e32 v25, v2
	v_mov_b32_e32 v26, v2
	v_mov_b32_e32 v27, v2
	v_mov_b32_e32 v28, v2
	v_mov_b32_e32 v29, v2
	v_mov_b32_e32 v30, v2
	v_mov_b32_e32 v31, v2
	v_mov_b32_e32 v32, v2
	v_mov_b32_e32 v33, v2
	v_mov_b32_e32 v34, v2
	v_mov_b32_e32 v35, v2
	v_mov_b32_e32 v36, v2
	v_mov_b32_e32 v37, v2
	v_mov_b32_e32 v38, v2
	v_mov_b32_e32 v39, v2
	v_mov_b32_e32 v40, v2
	v_mov_b32_e32 v41, v2
	v_mov_b32_e32 v42, v2
	v_mov_b32_e32 v43, v2
	v_mov_b32_e32 v44, v2
	v_mov_b32_e32 v45, v2
	v_mov_b32_e32 v46, v2
	v_mov_b32_e32 v47, v2
	v_mov_b32_e32 v48, v2
	v_mov_b32_e32 v49, v2
	v_mov_b32_e32 v50, v2
	v_mov_b32_e32 v51, v2
	v_mov_b32_e32 v52, v2
	v_mov_b32_e32 v53, v2
	v_mov_b32_e32 v54, v2
	v_mov_b32_e32 v55, v2
	v_mov_b32_e32 v56, v2
	v_mov_b32_e32 v57, v2
	v_mov_b32_e32 v58, v2
	v_mov_b32_e32 v59, v2
	v_mov_b32_e32 v60, v2
	v_mov_b32_e32 v61, v2
	v_mov_b32_e32 v62, v2
	v_mov_b32_e32 v63, v2
	v_mov_b32_e32 v64, v2
	v_mov_b32_e32 v65, v2
	v_mov_b32_e32 v66, v2
	v_mov_b32_e32 v67, v2
	v_mov_b32_e32 v68, v2
	v_mov_b32_e32 v69, v2
	v_mov_b32_e32 v70, v2
	v_mov_b32_e32 v71, v2
	v_mov_b32_e32 v72, v2
	v_mov_b32_e32 v73, v2
	v_mov_b32_e32 v74, v2
	v_mov_b32_e32 v75, v2
	v_mov_b32_e32 v76, v2
	v_mov_b32_e32 v77, v2
	v_mov_b32_e32 v78, v2
	v_mov_b32_e32 v79, v2
	v_mov_b32_e32 v80, v2
	v_mov_b32_e32 v81, v2
	v_mov_b32_e32 v82, v2
	v_mov_b32_e32 v83, v2
	v_mov_b32_e32 v84, v2
	v_mov_b32_e32 v85, v2
	v_mov_b32_e32 v86, v2
	v_mov_b32_e32 v87, v2
	v_mov_b32_e32 v88, v2
	v_mov_b32_e32 v89, v2
	v_mov_b32_e32 v90, v2
	v_mov_b32_e32 v91, v2
	v_mov_b32_e32 v92, v2
	v_mov_b32_e32 v93, v2
	v_mov_b32_e32 v94, v2
	v_mov_b32_e32 v95, v2
	v_mov_b32_e32 v96, v2
	v_mov_b32_e32 v97, v2
	v_mov_b32_e32 v98, v2
	v_mov_b32_e32 v99, v2
	v_mov_b32_e32 v100, v2
	v_mov_b32_e32 v101, v2
	v_mov_b32_e32 v102, v2
	v_mov_b32_e32 v103, v2
	v_mov_b32_e32 v104, v2
	v_mov_b32_e32 v105, v2
	v_mov_b32_e32 v106, v2
	v_mov_b32_e32 v107, v2
	v_mov_b32_e32 v108, v2
	v_mov_b32_e32 v109, v2
	v_mov_b32_e32 v110, v2
	v_mov_b32_e32 v111, v2
	v_mov_b32_e32 v112, v2
	v_mov_b32_e32 v113, v2
	v_mov_b32_e32 v114, v2
	v_mov_b32_e32 v115, v2
	v_mov_b32_e32 v116, v2
	v_mov_b32_e32 v117, v2
	v_mov_b32_e32 v118, v2
	v_mov_b32_e32 v119, v2
	v_mov_b32_e32 v120, v2
	v_mov_b32_e32 v121, v2
	v_mov_b32_e32 v122, v2
	v_mov_b32_e32 v123, v2
	v_mov_b32_e32 v124, v2
	v_mov_b32_e32 v125, v2
	v_mov_b32_e32 v126, v2
	v_mov_b32_e32 v127, v2
	v_mov_b32_e32 v128, v2
	v_mov_b32_e32 v129, v2
	v_mov_b32_e32 v131, v130
	v_mov_b32_e32 v132, v130
	v_mov_b32_e32 v133, v130
	v_mov_b32_e32 v134, v130
	v_mov_b32_e32 v135, v130
	v_mov_b32_e32 v136, v130
	v_mov_b32_e32 v137, v130
	v_mov_b32_e32 v138, v130
	v_mov_b32_e32 v139, v130
	v_mov_b32_e32 v140, v130
	v_mov_b32_e32 v141, v130
	v_mov_b32_e32 v142, v130
	v_mov_b32_e32 v143, v130
	v_mov_b32_e32 v144, v130
	v_mov_b32_e32 v145, v130
	v_mov_b32_e32 v146, v130
	v_mov_b32_e32 v147, v130
	v_mov_b32_e32 v148, v130
	v_mov_b32_e32 v149, v130
	v_mov_b32_e32 v150, v130
	v_mov_b32_e32 v151, v130
	v_mov_b32_e32 v152, v130
	v_mov_b32_e32 v153, v130
	s_mov_b64 s[30:31], 0x37f8900
	s_waitcnt vmcnt(0) lgkmcnt(0)
	s_barrier
	s_add_i32 s18, s27, -1
	s_ashr_i32 s19, s18, 31
	s_lshl_b64 s[18:19], s[18:19], 11
	s_add_u32 s18, s90, s18
	s_addc_u32 s19, s91, s19
	v_readlane_b32 s22, v253, 17
	v_readlane_b32 s23, v253, 18
	s_lshl_b32 s21, s28, 19
	s_add_u32 s22, s22, s21
	s_addc_u32 s23, s23, 0
	v_and_b32_e32 v130, 63, v204
	v_lshrrev_b32_e32 v131, 6, v204
	v_lshrrev_b32_e32 v132, 3, v204
	v_lshrrev_b32_e32 v0, 4, v130
	v_lshl_add_u32 v0, v131, 2, v0
	v_xor_b32_e32 v0, v0, v130
	v_and_b32_e32 v0, 7, v0
	v_lshlrev_b32_e32 v133, 4, v0
	v_lshl_add_u32 v236, v132, 11, v133
	v_add_u32_e32 v237, 0x20000, v236
	v_add_u32_e32 v238, 0x40000, v236
	v_add_u32_e32 v239, 0x60000, v236
	v_and_b32_e32 v0, 31, v132
	v_lshrrev_b32_e32 v130, 5, v132
	v_lshl_add_u32 v0, v130, 6, v0
	v_lshl_add_u32 v240, v0, 11, v133
	v_add_u32_e32 v241, 0x10000, v240
	v_add_u32_e32 v242, 0x40000, v240
	v_add_u32_e32 v243, 0x50000, v240
	v_and_b32_e32 v132, 31, v204
	v_lshrrev_b32_e32 v0, 2, v131
	v_lshl_add_u32 v0, v0, 6, v132
	v_lshlrev_b32_e32 v248, 7, v0
	v_and_b32_e32 v0, 3, v131
	v_lshl_add_u32 v0, v0, 5, v132
	v_lshlrev_b32_e32 v249, 7, v0
	v_bfe_u32 v0, v204, 5, 1
	v_bfe_u32 v130, v132, 1, 3
	v_or_b32_e32 v133, 0, v0
	v_xor_b32_e32 v133, v133, v130
	v_lshlrev_b32_e32 v244, 4, v133
	v_or_b32_e32 v133, 2, v0
	v_xor_b32_e32 v133, v133, v130
	v_lshlrev_b32_e32 v245, 4, v133
	v_or_b32_e32 v133, 4, v0
	v_xor_b32_e32 v133, v133, v130
	v_lshlrev_b32_e32 v246, 4, v133
	v_or_b32_e32 v133, 6, v0
	v_xor_b32_e32 v133, v133, v130
	v_lshlrev_b32_e32 v247, 4, v133
	v_add_u32_e32 v202, v249, v244
	v_add_u32_e32 v203, v249, v245
	v_add_u32_e32 v175, v249, v246
	v_add_u32_e32 v185, v249, v247
	v_add_u32_e32 v244, v248, v244
	v_add_u32_e32 v245, v248, v245
	v_add_u32_e32 v246, v248, v246
	v_add_u32_e32 v247, v248, v247
	v_lshlrev_b32_e32 v131, 10, v131
	s_nop 0
	v_readfirstlane_b32 s100, v131
	v_mov_b32_e32 v146, 0
	v_mov_b32_e32 v147, 0
	v_mov_b32_e32 v148, 0
	v_mov_b32_e32 v149, 0
	v_lshlrev_b32_e32 v130, 4, v204
	v_add_u32_e32 v132, 0x10000, v130
	s_not_b64 exec, s[10:11]
	ds_write_b128 v130, v[146:149]
	ds_write_b128 v132, v[146:149]
	s_not_b64 exec, s[12:13]
	ds_write_b128 v130, v[146:149] offset:16384
	ds_write_b128 v132, v[146:149] offset:16384
	s_not_b64 exec, s[14:15]
	ds_write_b128 v130, v[146:149] offset:8192
	ds_write_b128 v132, v[146:149] offset:8192
	s_not_b64 exec, s[16:17]
	ds_write_b128 v130, v[146:149] offset:24576
	ds_write_b128 v132, v[146:149] offset:24576
	s_mov_b64 exec, -1
	s_mov_b32 s29, 0
	s_mov_b32 s21, 0x10000
	s_waitcnt lgkmcnt(0)
	s_cmp_eq_u32 s27, 0
	s_cbranch_scc1 .Lg8_u0_msk
	s_cmp_gt_i32 s20, 0xbf00
	s_cbranch_scc1 .Lg8_u0_msk
	s_add_u32 m0, s100, 0x8000
	s_nop 0
	global_load_lds_dwordx4 v240, s[22:23]
	s_add_u32 m0, s100, 0xa000
	v_add_u32_e32 v240, 0x80, v240
	global_load_lds_dwordx4 v242, s[22:23]
	v_add_u32_e32 v242, 0x80, v242
	s_add_u32 m0, s100, 0x0
	s_nop 0
	global_load_lds_dwordx4 v236, s[18:19]
	s_add_u32 m0, s100, 0x2000
	v_add_u32_e32 v236, 0x80, v236
	global_load_lds_dwordx4 v238, s[18:19]
	v_add_u32_e32 v238, 0x80, v238
	s_add_u32 m0, s100, 0xc000
	s_nop 0
	global_load_lds_dwordx4 v241, s[22:23]
	s_add_u32 m0, s100, 0xe000
	v_add_u32_e32 v241, 0x80, v241
	global_load_lds_dwordx4 v243, s[22:23]
	v_add_u32_e32 v243, 0x80, v243
	s_add_u32 m0, s100, 0x4000
	s_nop 0
	global_load_lds_dwordx4 v237, s[18:19]
	s_add_u32 m0, s100, 0x6000
	v_add_u32_e32 v237, 0x80, v237
	global_load_lds_dwordx4 v239, s[18:19]
	v_add_u32_e32 v239, 0x80, v239
	s_cmp_eq_u32 s101, 1
	s_cbranch_scc0 .Lg8_u0u_p0
	s_barrier
; #define MFMA(a, b, c) __builtin_amdgcn_mfma_f32_32x32x16_bf16((a), (b), (c), 0, 0, 0)
; template <bool SWAP>
; DI void gemm_mainloop(f32x16 (&acc)[4][2], const u16* __restrict__ A, int lda, int rlo, int rhi,
;                       const u16* __restrict__ B, int ldb, int K, char* lds, const u16* zero_line) {
;     ...
;   __syncthreads();
;   glds(0, 0);
;   asm volatile("s_waitcnt vmcnt(0)" ::: "memory");
;   __syncthreads();
;   bf16x8 fa[2][4], fb[2][2];
; #pragma unroll
;   for (int mi = 0; mi < 4; ++mi)
; #pragma unroll
;     for (int e = 0; e < 8; ++e) fa[1][mi][e] = 0;
; #pragma unroll
;   for (int ni = 0; ni < 2; ++ni)
; #pragma unroll
;     for (int e = 0; e < 8; ++e) fb[1][ni][e] = 0;
;   auto ldfrag = [&](const char* st, int ks, int buf) {
;     const int co = ((2 * ks + h) ^ sw) << 4;
; #pragma unroll
;     for (int mi = 0; mi < 4; ++mi) fa[buf][mi] = *(const bf16x8*)(st + arow_off + mi * 4096 + co);
; #pragma unroll
;     for (int ni = 0; ni < 2; ++ni) fb[buf][ni] = *(const bf16x8*)(st + brow_off + ni * 4096 + co);
;   };
;   auto mma = [&](int buf) {
; #pragma unroll
;     for (int mi = 0; mi < 4; ++mi)
; #pragma unroll
;       for (int ni = 0; ni < 2; ++ni)
;         acc[mi][ni] = SWAP ? MFMA(fb[buf][ni], fa[buf][mi], acc[mi][ni]) : MFMA(fa[buf][mi], fb[buf][ni], acc[mi][ni]);
;   };
;   auto pat_rd = [&]() {
; #pragma unroll
;     for (int g = 0; g < 6; ++g) {
;       __builtin_amdgcn_sched_group_barrier(0x100, 1, 0);
;       __builtin_amdgcn_sched_group_barrier(0x008, 1, 0);
;     }
;     __builtin_amdgcn_sched_group_barrier(0x008, 2, 0);
;   };
; #pragma unroll 2
;   for (int kt = 0; kt < nk; ++kt) {
;     const char* st = lds + (kt & 1) * 65536;
;     ldfrag(st, 0, 0);
;     mma(1);
;     pat_rd();
;     if (kt + 1 < nk) glds(kt + 1, (kt + 1) & 1);
;     ldfrag(st, 1, 1);
;     mma(0);
;     pat_rd();
;     ldfrag(st, 2, 0);
;     mma(1);
;     pat_rd();
;     ldfrag(st, 3, 1);
;     mma(0);
;     pat_rd();
;     asm volatile("s_waitcnt vmcnt(0)" ::: "memory");
;     __syncthreads();
.Lg8_u0u_p0:
	s_waitcnt vmcnt(4)
	s_barrier
	s_add_u32 m0, s100, 0x18000
	s_nop 0
	global_load_lds_dwordx4 v240, s[22:23]
	s_add_u32 m0, s100, 0x1a000
	v_add_u32_e32 v240, 0x80, v240
	global_load_lds_dwordx4 v242, s[22:23]
	v_add_u32_e32 v242, 0x80, v242
	s_add_u32 m0, s100, 0x10000
	s_nop 0
	global_load_lds_dwordx4 v236, s[18:19]
	s_add_u32 m0, s100, 0x12000
	v_add_u32_e32 v236, 0x80, v236
	global_load_lds_dwordx4 v238, s[18:19]
	v_add_u32_e32 v238, 0x80, v238
	s_add_u32 m0, s100, 0x1c000
	s_nop 0
	global_load_lds_dwordx4 v241, s[22:23]
	s_add_u32 m0, s100, 0x1e000
	v_add_u32_e32 v241, 0x80, v241
	global_load_lds_dwordx4 v243, s[22:23]
	v_add_u32_e32 v243, 0x80, v243
	s_waitcnt vmcnt(6)
	s_barrier
	ds_read_b128 v[176:179], v202 offset:32768
	ds_read_b128 v[180:183], v203 offset:32768
	ds_read_b128 v[186:189], v175 offset:32768
	ds_read_b128 v[190:193], v185 offset:32768
.Lg8_u0u:
	s_add_u32 m0, s100, 0x14000
	ds_read_b128 v[130:133], v244
	ds_read_b128 v[134:137], v245
	ds_read_b128 v[138:141], v246
	ds_read_b128 v[142:145], v247
	ds_read_b128 v[146:149], v244 offset:4096
	ds_read_b128 v[150:153], v245 offset:4096
	ds_read_b128 v[158:161], v246 offset:4096
	ds_read_b128 v[162:165], v247 offset:4096
	global_load_lds_dwordx4 v237, s[18:19]
	s_add_u32 m0, s100, 0x16000
	v_add_u32_e32 v237, 0x80, v237
	global_load_lds_dwordx4 v239, s[18:19]
	v_add_u32_e32 v239, 0x80, v239
	s_barrier
	s_waitcnt lgkmcnt(0)
	v_mfma_f32_32x32x16_bf16 v[114:129], v[176:179], v[130:133], v[114:129]
	v_mfma_f32_32x32x16_bf16 v[82:97], v[176:179], v[146:149], v[82:97]
	v_mfma_f32_32x32x16_bf16 v[114:129], v[180:183], v[134:137], v[114:129]
	v_mfma_f32_32x32x16_bf16 v[82:97], v[180:183], v[150:153], v[82:97]
	v_mfma_f32_32x32x16_bf16 v[114:129], v[186:189], v[138:141], v[114:129]
	v_mfma_f32_32x32x16_bf16 v[82:97], v[186:189], v[158:161], v[82:97]
	v_mfma_f32_32x32x16_bf16 v[114:129], v[190:193], v[142:145], v[114:129]
	v_mfma_f32_32x32x16_bf16 v[82:97], v[190:193], v[162:165], v[82:97]
	s_barrier
	s_add_u32 m0, s100, 0x8000
	ds_read_b128 v[194:197], v202 offset:49152
	ds_read_b128 v[198:201], v203 offset:49152
	ds_read_b128 v[228:231], v175 offset:49152
	ds_read_b128 v[232:235], v185 offset:49152
	global_load_lds_dwordx4 v240, s[22:23]
	s_add_u32 m0, s100, 0xa000
	v_add_u32_e32 v240, 0x80, v240
	global_load_lds_dwordx4 v242, s[22:23]
	v_add_u32_e32 v242, 0x80, v242
	s_barrier
	s_waitcnt lgkmcnt(0)
	v_mfma_f32_32x32x16_bf16 v[98:113], v[194:197], v[130:133], v[98:113]
	v_mfma_f32_32x32x16_bf16 v[66:81], v[194:197], v[146:149], v[66:81]
	v_mfma_f32_32x32x16_bf16 v[98:113], v[198:201], v[134:137], v[98:113]
	v_mfma_f32_32x32x16_bf16 v[66:81], v[198:201], v[150:153], v[66:81]
	v_mfma_f32_32x32x16_bf16 v[98:113], v[228:231], v[138:141], v[98:113]
	v_mfma_f32_32x32x16_bf16 v[66:81], v[228:231], v[158:161], v[66:81]
	v_mfma_f32_32x32x16_bf16 v[98:113], v[232:235], v[142:145], v[98:113]
	v_mfma_f32_32x32x16_bf16 v[66:81], v[232:235], v[162:165], v[66:81]
	s_barrier
	s_add_u32 m0, s100, 0x0
	ds_read_b128 v[130:133], v244 offset:16384
	ds_read_b128 v[134:137], v245 offset:16384
	ds_read_b128 v[138:141], v246 offset:16384
	ds_read_b128 v[142:145], v247 offset:16384
	ds_read_b128 v[146:149], v244 offset:20480
	ds_read_b128 v[150:153], v245 offset:20480
	ds_read_b128 v[158:161], v246 offset:20480
	ds_read_b128 v[162:165], v247 offset:20480
	global_load_lds_dwordx4 v236, s[18:19]
	s_add_u32 m0, s100, 0x2000
	v_add_u32_e32 v236, 0x80, v236
	global_load_lds_dwordx4 v238, s[18:19]
	v_add_u32_e32 v238, 0x80, v238
	s_waitcnt vmcnt(10)
	s_barrier
	s_waitcnt lgkmcnt(0)
	v_mfma_f32_32x32x16_bf16 v[50:65], v[176:179], v[130:133], v[50:65]
	v_mfma_f32_32x32x16_bf16 v[18:33], v[176:179], v[146:149], v[18:33]
	v_mfma_f32_32x32x16_bf16 v[50:65], v[180:183], v[134:137], v[50:65]
	v_mfma_f32_32x32x16_bf16 v[18:33], v[180:183], v[150:153], v[18:33]
	v_mfma_f32_32x32x16_bf16 v[50:65], v[186:189], v[138:141], v[50:65]
	v_mfma_f32_32x32x16_bf16 v[18:33], v[186:189], v[158:161], v[18:33]
	v_mfma_f32_32x32x16_bf16 v[50:65], v[190:193], v[142:145], v[50:65]
	v_mfma_f32_32x32x16_bf16 v[18:33], v[190:193], v[162:165], v[18:33]
	s_barrier
	s_add_u32 m0, s100, 0xc000
	v_add_u32_e32 v166, s21, v202
	v_add_u32_e32 v167, s21, v203
	ds_read_b128 v[176:179], v166 offset:32768
	ds_read_b128 v[180:183], v167 offset:32768
	v_add_u32_e32 v166, s21, v175
	v_add_u32_e32 v167, s21, v185
	ds_read_b128 v[186:189], v166 offset:32768
	ds_read_b128 v[190:193], v167 offset:32768
	global_load_lds_dwordx4 v241, s[22:23]
	s_add_u32 m0, s100, 0xe000
	v_add_u32_e32 v241, 0x80, v241
	global_load_lds_dwordx4 v243, s[22:23]
	v_add_u32_e32 v243, 0x80, v243
	s_waitcnt vmcnt(6)
	s_barrier
	s_waitcnt lgkmcnt(0)
	v_mfma_f32_32x32x16_bf16 v[34:49], v[194:197], v[130:133], v[34:49]
	v_mfma_f32_32x32x16_bf16 v[2:17], v[194:197], v[146:149], v[2:17]
	v_mfma_f32_32x32x16_bf16 v[34:49], v[198:201], v[134:137], v[34:49]
	v_mfma_f32_32x32x16_bf16 v[2:17], v[198:201], v[150:153], v[2:17]
	v_mfma_f32_32x32x16_bf16 v[34:49], v[228:231], v[138:141], v[34:49]
	v_mfma_f32_32x32x16_bf16 v[2:17], v[228:231], v[158:161], v[2:17]
	v_mfma_f32_32x32x16_bf16 v[34:49], v[232:235], v[142:145], v[34:49]
	v_mfma_f32_32x32x16_bf16 v[2:17], v[232:235], v[162:165], v[2:17]
	s_barrier
	s_add_u32 m0, s100, 0x4000
	v_add_u32_e32 v166, s21, v244
	v_add_u32_e32 v167, s21, v245
	ds_read_b128 v[130:133], v166
	ds_read_b128 v[134:137], v167
	ds_read_b128 v[146:149], v166 offset:4096
	ds_read_b128 v[150:153], v167 offset:4096
	v_add_u32_e32 v166, s21, v246
	v_add_u32_e32 v167, s21, v247
	ds_read_b128 v[138:141], v166
	ds_read_b128 v[142:145], v167
	ds_read_b128 v[158:161], v166 offset:4096
	ds_read_b128 v[162:165], v167 offset:4096
	global_load_lds_dwordx4 v237, s[18:19]
	s_add_u32 m0, s100, 0x6000
	v_add_u32_e32 v237, 0x80, v237
	global_load_lds_dwordx4 v239, s[18:19]
	v_add_u32_e32 v239, 0x80, v239
	s_barrier
; template <bool SWAP>
; DI void gemm_mainloop(f32x16 (&acc)[4][2], const u16* __restrict__ A, int lda, int rlo, int rhi,
;                       const u16* __restrict__ B, int ldb, int K, char* lds, const u16* zero_line) {
;     ...
;   auto glds = [&](int kt, int st) {
;     char* as_ = lds + st * 65536 + tid * 16;
; #pragma unroll
;     for (int i = 0; i < 4; ++i) {
;       const int rr = lr + 64 * i;
;       const u16* srca = (rr >= rlo && rr < rhi) ? (ap + (ptrdiff_t)(64 * i) * lda + kt * 64) : (zero_line + lc * 8);
;       __builtin_amdgcn_global_load_lds((const unsigned*)srca, (lds_u32*)(as_ + i * 8192), 16, 0, 0);
;       __builtin_amdgcn_global_load_lds((const unsigned*)(bp + (ptrdiff_t)(64 * i) * ldb + kt * 64), (lds_u32*)(as_ + 32768 + i * 8192), 16, 0, 0);
;     }
;   };
;     ...
; #pragma unroll 2
;   for (int kt = 0; kt < nk; ++kt) {
;     const char* st = lds + (kt & 1) * 65536;
;     ldfrag(st, 0, 0);
;     mma(1);
;     pat_rd();
;     if (kt + 1 < nk) glds(kt + 1, (kt + 1) & 1);
;     ldfrag(st, 1, 1);
;     mma(0);
;     pat_rd();
;     ldfrag(st, 2, 0);
;     mma(1);
;     pat_rd();
;     ldfrag(st, 3, 1);
;     mma(0);
;     pat_rd();
;     asm volatile("s_waitcnt vmcnt(0)" ::: "memory");
;     __syncthreads();
;   }
;   mma(1);
	s_waitcnt lgkmcnt(0)
	v_mfma_f32_32x32x16_bf16 v[114:129], v[176:179], v[130:133], v[114:129]
	v_mfma_f32_32x32x16_bf16 v[82:97], v[176:179], v[146:149], v[82:97]
	v_mfma_f32_32x32x16_bf16 v[114:129], v[180:183], v[134:137], v[114:129]
	v_mfma_f32_32x32x16_bf16 v[82:97], v[180:183], v[150:153], v[82:97]
	v_mfma_f32_32x32x16_bf16 v[114:129], v[186:189], v[138:141], v[114:129]
	v_mfma_f32_32x32x16_bf16 v[82:97], v[186:189], v[158:161], v[82:97]
	v_mfma_f32_32x32x16_bf16 v[114:129], v[190:193], v[142:145], v[114:129]
	v_mfma_f32_32x32x16_bf16 v[82:97], v[190:193], v[162:165], v[82:97]
	s_barrier
	s_add_u32 m0, s100, 0x18000
	v_add_u32_e32 v166, s21, v202
	v_add_u32_e32 v167, s21, v203
	ds_read_b128 v[194:197], v166 offset:49152
	ds_read_b128 v[198:201], v167 offset:49152
	v_add_u32_e32 v166, s21, v175
	v_add_u32_e32 v167, s21, v185
	ds_read_b128 v[228:231], v166 offset:49152
	ds_read_b128 v[232:235], v167 offset:49152
	global_load_lds_dwordx4 v240, s[22:23]
	s_add_u32 m0, s100, 0x1a000
	v_add_u32_e32 v240, 0x80, v240
	global_load_lds_dwordx4 v242, s[22:23]
	v_add_u32_e32 v242, 0x80, v242
	s_barrier
	s_waitcnt lgkmcnt(0)
	v_mfma_f32_32x32x16_bf16 v[98:113], v[194:197], v[130:133], v[98:113]
	v_mfma_f32_32x32x16_bf16 v[66:81], v[194:197], v[146:149], v[66:81]
	v_mfma_f32_32x32x16_bf16 v[98:113], v[198:201], v[134:137], v[98:113]
	v_mfma_f32_32x32x16_bf16 v[66:81], v[198:201], v[150:153], v[66:81]
	v_mfma_f32_32x32x16_bf16 v[98:113], v[228:231], v[138:141], v[98:113]
	v_mfma_f32_32x32x16_bf16 v[66:81], v[228:231], v[158:161], v[66:81]
	v_mfma_f32_32x32x16_bf16 v[98:113], v[232:235], v[142:145], v[98:113]
	v_mfma_f32_32x32x16_bf16 v[66:81], v[232:235], v[162:165], v[66:81]
	s_barrier
	s_add_u32 m0, s100, 0x10000
	v_add_u32_e32 v166, s21, v244
	v_add_u32_e32 v167, s21, v245
	ds_read_b128 v[130:133], v166 offset:16384
	ds_read_b128 v[134:137], v167 offset:16384
	ds_read_b128 v[146:149], v166 offset:20480
	ds_read_b128 v[150:153], v167 offset:20480
	v_add_u32_e32 v166, s21, v246
	v_add_u32_e32 v167, s21, v247
	ds_read_b128 v[138:141], v166 offset:16384
	ds_read_b128 v[142:145], v167 offset:16384
	ds_read_b128 v[158:161], v166 offset:20480
	ds_read_b128 v[162:165], v167 offset:20480
	global_load_lds_dwordx4 v236, s[18:19]
	s_add_u32 m0, s100, 0x12000
	v_add_u32_e32 v236, 0x80, v236
	global_load_lds_dwordx4 v238, s[18:19]
	v_add_u32_e32 v238, 0x80, v238
	s_waitcnt vmcnt(10)
	s_barrier
	s_waitcnt lgkmcnt(0)
	v_mfma_f32_32x32x16_bf16 v[50:65], v[176:179], v[130:133], v[50:65]
	v_mfma_f32_32x32x16_bf16 v[18:33], v[176:179], v[146:149], v[18:33]
	v_mfma_f32_32x32x16_bf16 v[50:65], v[180:183], v[134:137], v[50:65]
	v_mfma_f32_32x32x16_bf16 v[18:33], v[180:183], v[150:153], v[18:33]
	v_mfma_f32_32x32x16_bf16 v[50:65], v[186:189], v[138:141], v[50:65]
	v_mfma_f32_32x32x16_bf16 v[18:33], v[186:189], v[158:161], v[18:33]
	v_mfma_f32_32x32x16_bf16 v[50:65], v[190:193], v[142:145], v[50:65]
	v_mfma_f32_32x32x16_bf16 v[18:33], v[190:193], v[162:165], v[18:33]
	s_barrier
	s_add_u32 m0, s100, 0x1c000
	ds_read_b128 v[176:179], v202 offset:32768
	ds_read_b128 v[180:183], v203 offset:32768
	ds_read_b128 v[186:189], v175 offset:32768
	ds_read_b128 v[190:193], v185 offset:32768
	global_load_lds_dwordx4 v241, s[22:23]
	s_add_u32 m0, s100, 0x1e000
	v_add_u32_e32 v241, 0x80, v241
	global_load_lds_dwordx4 v243, s[22:23]
	v_add_u32_e32 v243, 0x80, v243
	s_waitcnt vmcnt(6)
	s_barrier
	s_waitcnt lgkmcnt(0)
	v_mfma_f32_32x32x16_bf16 v[34:49], v[194:197], v[130:133], v[34:49]
	v_mfma_f32_32x32x16_bf16 v[2:17], v[194:197], v[146:149], v[2:17]
	v_mfma_f32_32x32x16_bf16 v[34:49], v[198:201], v[134:137], v[34:49]
	v_mfma_f32_32x32x16_bf16 v[2:17], v[198:201], v[150:153], v[2:17]
	v_mfma_f32_32x32x16_bf16 v[34:49], v[228:231], v[138:141], v[34:49]
	v_mfma_f32_32x32x16_bf16 v[2:17], v[228:231], v[158:161], v[2:17]
	v_mfma_f32_32x32x16_bf16 v[34:49], v[232:235], v[142:145], v[34:49]
	v_mfma_f32_32x32x16_bf16 v[2:17], v[232:235], v[162:165], v[2:17]
	s_add_i32 s29, s29, 2
	s_cmp_lt_u32 s29, 14
	s_barrier
	s_cbranch_scc1 .Lg8_u0u
	ds_read_b128 v[130:133], v244
	ds_read_b128 v[134:137], v245
	ds_read_b128 v[138:141], v246
	ds_read_b128 v[142:145], v247
	ds_read_b128 v[146:149], v244 offset:4096
	ds_read_b128 v[150:153], v245 offset:4096
	ds_read_b128 v[158:161], v246 offset:4096
	ds_read_b128 v[162:165], v247 offset:4096
	s_add_u32 m0, s100, 0x14000
	s_nop 0
	global_load_lds_dwordx4 v237, s[18:19]
	s_add_u32 m0, s100, 0x16000
	v_add_u32_e32 v237, 0x80, v237
	global_load_lds_dwordx4 v239, s[18:19]
	v_add_u32_e32 v239, 0x80, v239
	s_barrier
	s_waitcnt lgkmcnt(0)
	v_mfma_f32_32x32x16_bf16 v[114:129], v[176:179], v[130:133], v[114:129]
	v_mfma_f32_32x32x16_bf16 v[82:97], v[176:179], v[146:149], v[82:97]
	v_mfma_f32_32x32x16_bf16 v[114:129], v[180:183], v[134:137], v[114:129]
	v_mfma_f32_32x32x16_bf16 v[82:97], v[180:183], v[150:153], v[82:97]
	v_mfma_f32_32x32x16_bf16 v[114:129], v[186:189], v[138:141], v[114:129]
	v_mfma_f32_32x32x16_bf16 v[82:97], v[186:189], v[158:161], v[82:97]
	v_mfma_f32_32x32x16_bf16 v[114:129], v[190:193], v[142:145], v[114:129]
	v_mfma_f32_32x32x16_bf16 v[82:97], v[190:193], v[162:165], v[82:97]
	s_barrier
	ds_read_b128 v[194:197], v202 offset:49152
	ds_read_b128 v[198:201], v203 offset:49152
	ds_read_b128 v[228:231], v175 offset:49152
	ds_read_b128 v[232:235], v185 offset:49152
	s_barrier
; template <bool SWAP>
; DI void gemm_mainloop(f32x16 (&acc)[4][2], const u16* __restrict__ A, int lda, int rlo, int rhi,
;                       const u16* __restrict__ B, int ldb, int K, char* lds, const u16* zero_line) {
;     ...
; #pragma unroll 2
;   for (int kt = 0; kt < nk; ++kt) {
;     const char* st = lds + (kt & 1) * 65536;
;     ldfrag(st, 0, 0);
;     mma(1);
;     pat_rd();
;     if (kt + 1 < nk) glds(kt + 1, (kt + 1) & 1);
;     ldfrag(st, 1, 1);
;     mma(0);
;     pat_rd();
;     ldfrag(st, 2, 0);
;     mma(1);
;     pat_rd();
;     ldfrag(st, 3, 1);
;     mma(0);
;     pat_rd();
;     asm volatile("s_waitcnt vmcnt(0)" ::: "memory");
;     __syncthreads();
;   }
;   mma(1);
	s_waitcnt lgkmcnt(0)
	v_mfma_f32_32x32x16_bf16 v[98:113], v[194:197], v[130:133], v[98:113]
	v_mfma_f32_32x32x16_bf16 v[66:81], v[194:197], v[146:149], v[66:81]
	v_mfma_f32_32x32x16_bf16 v[98:113], v[198:201], v[134:137], v[98:113]
	v_mfma_f32_32x32x16_bf16 v[66:81], v[198:201], v[150:153], v[66:81]
	v_mfma_f32_32x32x16_bf16 v[98:113], v[228:231], v[138:141], v[98:113]
	v_mfma_f32_32x32x16_bf16 v[66:81], v[228:231], v[158:161], v[66:81]
	v_mfma_f32_32x32x16_bf16 v[98:113], v[232:235], v[142:145], v[98:113]
	v_mfma_f32_32x32x16_bf16 v[66:81], v[232:235], v[162:165], v[66:81]
	s_barrier
	ds_read_b128 v[130:133], v244 offset:16384
	ds_read_b128 v[134:137], v245 offset:16384
	ds_read_b128 v[138:141], v246 offset:16384
	ds_read_b128 v[142:145], v247 offset:16384
	ds_read_b128 v[146:149], v244 offset:20480
	ds_read_b128 v[150:153], v245 offset:20480
	ds_read_b128 v[158:161], v246 offset:20480
	ds_read_b128 v[162:165], v247 offset:20480
	s_waitcnt vmcnt(4)
	s_barrier
	s_waitcnt lgkmcnt(0)
	v_mfma_f32_32x32x16_bf16 v[50:65], v[176:179], v[130:133], v[50:65]
	v_mfma_f32_32x32x16_bf16 v[18:33], v[176:179], v[146:149], v[18:33]
	v_mfma_f32_32x32x16_bf16 v[50:65], v[180:183], v[134:137], v[50:65]
	v_mfma_f32_32x32x16_bf16 v[18:33], v[180:183], v[150:153], v[18:33]
	v_mfma_f32_32x32x16_bf16 v[50:65], v[186:189], v[138:141], v[50:65]
	v_mfma_f32_32x32x16_bf16 v[18:33], v[186:189], v[158:161], v[18:33]
	v_mfma_f32_32x32x16_bf16 v[50:65], v[190:193], v[142:145], v[50:65]
	v_mfma_f32_32x32x16_bf16 v[18:33], v[190:193], v[162:165], v[18:33]
	v_mfma_f32_32x32x16_bf16 v[34:49], v[194:197], v[130:133], v[34:49]
	v_mfma_f32_32x32x16_bf16 v[2:17], v[194:197], v[146:149], v[2:17]
	v_mfma_f32_32x32x16_bf16 v[34:49], v[198:201], v[134:137], v[34:49]
	v_mfma_f32_32x32x16_bf16 v[2:17], v[198:201], v[150:153], v[2:17]
	v_mfma_f32_32x32x16_bf16 v[34:49], v[228:231], v[138:141], v[34:49]
	v_mfma_f32_32x32x16_bf16 v[2:17], v[228:231], v[158:161], v[2:17]
	v_mfma_f32_32x32x16_bf16 v[34:49], v[232:235], v[142:145], v[34:49]
	v_mfma_f32_32x32x16_bf16 v[2:17], v[232:235], v[162:165], v[2:17]
	s_barrier
	v_add_u32_e32 v166, s21, v202
	v_add_u32_e32 v167, s21, v203
	ds_read_b128 v[176:179], v166 offset:32768
	ds_read_b128 v[180:183], v167 offset:32768
	v_add_u32_e32 v166, s21, v175
	v_add_u32_e32 v167, s21, v185
	ds_read_b128 v[186:189], v166 offset:32768
	ds_read_b128 v[190:193], v167 offset:32768
	v_add_u32_e32 v166, s21, v244
	v_add_u32_e32 v167, s21, v245
	ds_read_b128 v[130:133], v166
	ds_read_b128 v[134:137], v167
	ds_read_b128 v[146:149], v166 offset:4096
	ds_read_b128 v[150:153], v167 offset:4096
	v_add_u32_e32 v166, s21, v246
	v_add_u32_e32 v167, s21, v247
	ds_read_b128 v[138:141], v166
	ds_read_b128 v[142:145], v167
	ds_read_b128 v[158:161], v166 offset:4096
	ds_read_b128 v[162:165], v167 offset:4096
	s_waitcnt vmcnt(2)
	s_barrier
	s_waitcnt lgkmcnt(0)
	v_mfma_f32_32x32x16_bf16 v[114:129], v[176:179], v[130:133], v[114:129]
	v_mfma_f32_32x32x16_bf16 v[82:97], v[176:179], v[146:149], v[82:97]
	v_mfma_f32_32x32x16_bf16 v[114:129], v[180:183], v[134:137], v[114:129]
	v_mfma_f32_32x32x16_bf16 v[82:97], v[180:183], v[150:153], v[82:97]
	v_mfma_f32_32x32x16_bf16 v[114:129], v[186:189], v[138:141], v[114:129]
	v_mfma_f32_32x32x16_bf16 v[82:97], v[186:189], v[158:161], v[82:97]
	v_mfma_f32_32x32x16_bf16 v[114:129], v[190:193], v[142:145], v[114:129]
	v_mfma_f32_32x32x16_bf16 v[82:97], v[190:193], v[162:165], v[82:97]
	s_barrier
	v_add_u32_e32 v166, s21, v202
	v_add_u32_e32 v167, s21, v203
	ds_read_b128 v[194:197], v166 offset:49152
	ds_read_b128 v[198:201], v167 offset:49152
	v_add_u32_e32 v166, s21, v175
	v_add_u32_e32 v167, s21, v185
	ds_read_b128 v[228:231], v166 offset:49152
	ds_read_b128 v[232:235], v167 offset:49152
	s_waitcnt vmcnt(0)
	s_barrier
	s_waitcnt lgkmcnt(0)
	v_mfma_f32_32x32x16_bf16 v[98:113], v[194:197], v[130:133], v[98:113]
	v_mfma_f32_32x32x16_bf16 v[66:81], v[194:197], v[146:149], v[66:81]
	v_mfma_f32_32x32x16_bf16 v[98:113], v[198:201], v[134:137], v[98:113]
	v_mfma_f32_32x32x16_bf16 v[66:81], v[198:201], v[150:153], v[66:81]
	v_mfma_f32_32x32x16_bf16 v[98:113], v[228:231], v[138:141], v[98:113]
	v_mfma_f32_32x32x16_bf16 v[66:81], v[228:231], v[158:161], v[66:81]
	v_mfma_f32_32x32x16_bf16 v[98:113], v[232:235], v[142:145], v[98:113]
	v_mfma_f32_32x32x16_bf16 v[66:81], v[232:235], v[162:165], v[66:81]
	s_barrier
	v_add_u32_e32 v166, s21, v244
	v_add_u32_e32 v167, s21, v245
	ds_read_b128 v[130:133], v166 offset:16384
	ds_read_b128 v[134:137], v167 offset:16384
	ds_read_b128 v[146:149], v166 offset:20480
	ds_read_b128 v[150:153], v167 offset:20480
	v_add_u32_e32 v166, s21, v246
	v_add_u32_e32 v167, s21, v247
	ds_read_b128 v[138:141], v166 offset:16384
	ds_read_b128 v[142:145], v167 offset:16384
	ds_read_b128 v[158:161], v166 offset:20480
	ds_read_b128 v[162:165], v167 offset:20480
	s_barrier
	s_waitcnt lgkmcnt(0)
	v_mfma_f32_32x32x16_bf16 v[50:65], v[176:179], v[130:133], v[50:65]
	v_mfma_f32_32x32x16_bf16 v[18:33], v[176:179], v[146:149], v[18:33]
	v_mfma_f32_32x32x16_bf16 v[50:65], v[180:183], v[134:137], v[50:65]
	v_mfma_f32_32x32x16_bf16 v[18:33], v[180:183], v[150:153], v[18:33]
	v_mfma_f32_32x32x16_bf16 v[50:65], v[186:189], v[138:141], v[50:65]
	v_mfma_f32_32x32x16_bf16 v[18:33], v[186:189], v[158:161], v[18:33]
	v_mfma_f32_32x32x16_bf16 v[50:65], v[190:193], v[142:145], v[50:65]
	v_mfma_f32_32x32x16_bf16 v[18:33], v[190:193], v[162:165], v[18:33]
	v_mfma_f32_32x32x16_bf16 v[34:49], v[194:197], v[130:133], v[34:49]
	v_mfma_f32_32x32x16_bf16 v[2:17], v[194:197], v[146:149], v[2:17]
	v_mfma_f32_32x32x16_bf16 v[34:49], v[198:201], v[134:137], v[34:49]
	v_mfma_f32_32x32x16_bf16 v[2:17], v[198:201], v[150:153], v[2:17]
	v_mfma_f32_32x32x16_bf16 v[34:49], v[228:231], v[138:141], v[34:49]
	v_mfma_f32_32x32x16_bf16 v[2:17], v[228:231], v[158:161], v[2:17]
	v_mfma_f32_32x32x16_bf16 v[34:49], v[232:235], v[142:145], v[34:49]
	v_mfma_f32_32x32x16_bf16 v[2:17], v[232:235], v[162:165], v[2:17]
	s_barrier
	s_cmp_eq_u32 s101, 0
	s_cbranch_scc0 .Lg8_u0u_p1
	s_barrier

; #define MFMA(a, b, c) __builtin_amdgcn_mfma_f32_32x32x16_bf16((a), (b), (c), 0, 0, 0)
; template <bool SWAP>
; DI void gemm_mainloop(f32x16 (&acc)[4][2], const u16* __restrict__ A, int lda, int rlo, int rhi,
;                       const u16* __restrict__ B, int ldb, int K, char* lds, const u16* zero_line) {
;     ...
;   __syncthreads();
;   glds(0, 0);
;   asm volatile("s_waitcnt vmcnt(0)" ::: "memory");
;   __syncthreads();
;   bf16x8 fa[2][4], fb[2][2];
; #pragma unroll
;   for (int mi = 0; mi < 4; ++mi)
; #pragma unroll
;     for (int e = 0; e < 8; ++e) fa[1][mi][e] = 0;
; #pragma unroll
;   for (int ni = 0; ni < 2; ++ni)
; #pragma unroll
;     for (int e = 0; e < 8; ++e) fb[1][ni][e] = 0;
;   auto ldfrag = [&](const char* st, int ks, int buf) {
;     const int co = ((2 * ks + h) ^ sw) << 4;
; #pragma unroll
;     for (int mi = 0; mi < 4; ++mi) fa[buf][mi] = *(const bf16x8*)(st + arow_off + mi * 4096 + co);
; #pragma unroll
;     for (int ni = 0; ni < 2; ++ni) fb[buf][ni] = *(const bf16x8*)(st + brow_off + ni * 4096 + co);
;   };
;   auto mma = [&](int buf) {
; #pragma unroll
;     for (int mi = 0; mi < 4; ++mi)
; #pragma unroll
;       for (int ni = 0; ni < 2; ++ni)
;         acc[mi][ni] = SWAP ? MFMA(fb[buf][ni], fa[buf][mi], acc[mi][ni]) : MFMA(fa[buf][mi], fb[buf][ni], acc[mi][ni]);
;   };
;   auto pat_rd = [&]() {
; #pragma unroll
;     for (int g = 0; g < 6; ++g) {
;       __builtin_amdgcn_sched_group_barrier(0x100, 1, 0);
;       __builtin_amdgcn_sched_group_barrier(0x008, 1, 0);
;     }
;     __builtin_amdgcn_sched_group_barrier(0x008, 2, 0);
;   };
; #pragma unroll 2
;   for (int kt = 0; kt < nk; ++kt) {
;     const char* st = lds + (kt & 1) * 65536;
;     ldfrag(st, 0, 0);
;     mma(1);
;     pat_rd();
;     if (kt + 1 < nk) glds(kt + 1, (kt + 1) & 1);
;     ldfrag(st, 1, 1);
;     mma(0);
;     pat_rd();
;     ldfrag(st, 2, 0);
;     mma(1);
;     pat_rd();
;     ldfrag(st, 3, 1);
;     mma(0);
;     pat_rd();
;     asm volatile("s_waitcnt vmcnt(0)" ::: "memory");
;     __syncthreads();
.Lg8_u0_msk:
	s_add_u32 m0, s100, 0x8000
	s_nop 0
	global_load_lds_dwordx4 v240, s[22:23]
	s_add_u32 m0, s100, 0xa000
	v_add_u32_e32 v240, 0x80, v240
	global_load_lds_dwordx4 v242, s[22:23]
	v_add_u32_e32 v242, 0x80, v242
	s_add_u32 m0, s100, 0x0
	s_mov_b64 exec, s[10:11]
	global_load_lds_dwordx4 v236, s[18:19]
	s_mov_b64 exec, -1
	v_add_u32_e32 v236, 0x80, v236
	s_add_u32 m0, s100, 0x2000
	s_mov_b64 exec, s[14:15]
	global_load_lds_dwordx4 v238, s[18:19]
	s_mov_b64 exec, -1
	v_add_u32_e32 v238, 0x80, v238
	s_add_u32 m0, s100, 0xc000
	s_nop 0
	global_load_lds_dwordx4 v241, s[22:23]
	s_add_u32 m0, s100, 0xe000
	v_add_u32_e32 v241, 0x80, v241
	global_load_lds_dwordx4 v243, s[22:23]
	v_add_u32_e32 v243, 0x80, v243
	s_add_u32 m0, s100, 0x4000
	s_mov_b64 exec, s[12:13]
	global_load_lds_dwordx4 v237, s[18:19]
	s_mov_b64 exec, -1
	v_add_u32_e32 v237, 0x80, v237
	s_add_u32 m0, s100, 0x6000
	s_mov_b64 exec, s[16:17]
	global_load_lds_dwordx4 v239, s[18:19]
	s_mov_b64 exec, -1
	v_add_u32_e32 v239, 0x80, v239
	s_cmp_eq_u32 s101, 1
	s_cbranch_scc0 .Lg8_u0m_p0
	s_barrier
.Lg8_u0m_p0:
	s_waitcnt vmcnt(4)
	s_barrier
	s_add_u32 m0, s100, 0x18000
	s_nop 0
	global_load_lds_dwordx4 v240, s[22:23]
	s_add_u32 m0, s100, 0x1a000
	v_add_u32_e32 v240, 0x80, v240
	global_load_lds_dwordx4 v242, s[22:23]
	v_add_u32_e32 v242, 0x80, v242
	s_add_u32 m0, s100, 0x10000
	s_mov_b64 exec, s[10:11]
	global_load_lds_dwordx4 v236, s[18:19]
	s_mov_b64 exec, -1
	v_add_u32_e32 v236, 0x80, v236
	s_add_u32 m0, s100, 0x12000
	s_mov_b64 exec, s[14:15]
	global_load_lds_dwordx4 v238, s[18:19]
	s_mov_b64 exec, -1
	v_add_u32_e32 v238, 0x80, v238
	s_add_u32 m0, s100, 0x1c000
	s_nop 0
	global_load_lds_dwordx4 v241, s[22:23]
	s_add_u32 m0, s100, 0x1e000
	v_add_u32_e32 v241, 0x80, v241
	global_load_lds_dwordx4 v243, s[22:23]
	v_add_u32_e32 v243, 0x80, v243
	s_waitcnt vmcnt(6)
	s_barrier
	ds_read_b128 v[176:179], v202 offset:32768
	ds_read_b128 v[180:183], v203 offset:32768
	ds_read_b128 v[186:189], v175 offset:32768
	ds_read_b128 v[190:193], v185 offset:32768
.Lg8_u0m:
	s_add_u32 m0, s100, 0x14000
	ds_read_b128 v[130:133], v244
	ds_read_b128 v[134:137], v245
	ds_read_b128 v[138:141], v246
	ds_read_b128 v[142:145], v247
	ds_read_b128 v[146:149], v244 offset:4096
	ds_read_b128 v[150:153], v245 offset:4096
	ds_read_b128 v[158:161], v246 offset:4096
	ds_read_b128 v[162:165], v247 offset:4096
	s_mov_b64 exec, s[12:13]
	global_load_lds_dwordx4 v237, s[18:19]
	s_mov_b64 exec, -1
	v_add_u32_e32 v237, 0x80, v237
	s_add_u32 m0, s100, 0x16000
	s_mov_b64 exec, s[16:17]
	global_load_lds_dwordx4 v239, s[18:19]
	s_mov_b64 exec, -1
	v_add_u32_e32 v239, 0x80, v239
	s_barrier
	s_waitcnt lgkmcnt(0)
	v_mfma_f32_32x32x16_bf16 v[114:129], v[176:179], v[130:133], v[114:129]
	v_mfma_f32_32x32x16_bf16 v[82:97], v[176:179], v[146:149], v[82:97]
	v_mfma_f32_32x32x16_bf16 v[114:129], v[180:183], v[134:137], v[114:129]
	v_mfma_f32_32x32x16_bf16 v[82:97], v[180:183], v[150:153], v[82:97]
	v_mfma_f32_32x32x16_bf16 v[114:129], v[186:189], v[138:141], v[114:129]
	v_mfma_f32_32x32x16_bf16 v[82:97], v[186:189], v[158:161], v[82:97]
	v_mfma_f32_32x32x16_bf16 v[114:129], v[190:193], v[142:145], v[114:129]
	v_mfma_f32_32x32x16_bf16 v[82:97], v[190:193], v[162:165], v[82:97]
	s_barrier
	s_add_u32 m0, s100, 0x8000
	ds_read_b128 v[194:197], v202 offset:49152
	ds_read_b128 v[198:201], v203 offset:49152
	ds_read_b128 v[228:231], v175 offset:49152
	ds_read_b128 v[232:235], v185 offset:49152
	global_load_lds_dwordx4 v240, s[22:23]
	s_add_u32 m0, s100, 0xa000
	v_add_u32_e32 v240, 0x80, v240
	global_load_lds_dwordx4 v242, s[22:23]
	v_add_u32_e32 v242, 0x80, v242
	s_barrier
	s_waitcnt lgkmcnt(0)
	v_mfma_f32_32x32x16_bf16 v[98:113], v[194:197], v[130:133], v[98:113]
	v_mfma_f32_32x32x16_bf16 v[66:81], v[194:197], v[146:149], v[66:81]
	v_mfma_f32_32x32x16_bf16 v[98:113], v[198:201], v[134:137], v[98:113]
	v_mfma_f32_32x32x16_bf16 v[66:81], v[198:201], v[150:153], v[66:81]
	v_mfma_f32_32x32x16_bf16 v[98:113], v[228:231], v[138:141], v[98:113]
	v_mfma_f32_32x32x16_bf16 v[66:81], v[228:231], v[158:161], v[66:81]
	v_mfma_f32_32x32x16_bf16 v[98:113], v[232:235], v[142:145], v[98:113]
	v_mfma_f32_32x32x16_bf16 v[66:81], v[232:235], v[162:165], v[66:81]
	s_barrier
	s_add_u32 m0, s100, 0x0
	ds_read_b128 v[130:133], v244 offset:16384
	ds_read_b128 v[134:137], v245 offset:16384
	ds_read_b128 v[138:141], v246 offset:16384
	ds_read_b128 v[142:145], v247 offset:16384
	ds_read_b128 v[146:149], v244 offset:20480
	ds_read_b128 v[150:153], v245 offset:20480
	ds_read_b128 v[158:161], v246 offset:20480
	ds_read_b128 v[162:165], v247 offset:20480
	s_mov_b64 exec, s[10:11]
	global_load_lds_dwordx4 v236, s[18:19]
	s_mov_b64 exec, -1
	v_add_u32_e32 v236, 0x80, v236
	s_add_u32 m0, s100, 0x2000
	s_mov_b64 exec, s[14:15]
	global_load_lds_dwordx4 v238, s[18:19]
	s_mov_b64 exec, -1
	v_add_u32_e32 v238, 0x80, v238
	s_waitcnt vmcnt(10)
	s_barrier
	s_waitcnt lgkmcnt(0)
	v_mfma_f32_32x32x16_bf16 v[50:65], v[176:179], v[130:133], v[50:65]
	v_mfma_f32_32x32x16_bf16 v[18:33], v[176:179], v[146:149], v[18:33]
	v_mfma_f32_32x32x16_bf16 v[50:65], v[180:183], v[134:137], v[50:65]
	v_mfma_f32_32x32x16_bf16 v[18:33], v[180:183], v[150:153], v[18:33]
	v_mfma_f32_32x32x16_bf16 v[50:65], v[186:189], v[138:141], v[50:65]
	v_mfma_f32_32x32x16_bf16 v[18:33], v[186:189], v[158:161], v[18:33]
	v_mfma_f32_32x32x16_bf16 v[50:65], v[190:193], v[142:145], v[50:65]
	v_mfma_f32_32x32x16_bf16 v[18:33], v[190:193], v[162:165], v[18:33]
	s_barrier
; template <bool SWAP>
; DI void gemm_mainloop(f32x16 (&acc)[4][2], const u16* __restrict__ A, int lda, int rlo, int rhi,
;                       const u16* __restrict__ B, int ldb, int K, char* lds, const u16* zero_line) {
;     ...
;   auto glds = [&](int kt, int st) {
;     char* as_ = lds + st * 65536 + tid * 16;
; #pragma unroll
;     for (int i = 0; i < 4; ++i) {
;       const int rr = lr + 64 * i;
;       const u16* srca = (rr >= rlo && rr < rhi) ? (ap + (ptrdiff_t)(64 * i) * lda + kt * 64) : (zero_line + lc * 8);
;       __builtin_amdgcn_global_load_lds((const unsigned*)srca, (lds_u32*)(as_ + i * 8192), 16, 0, 0);
;       __builtin_amdgcn_global_load_lds((const unsigned*)(bp + (ptrdiff_t)(64 * i) * ldb + kt * 64), (lds_u32*)(as_ + 32768 + i * 8192), 16, 0, 0);
;     }
;   };
;     ...
; #pragma unroll 2
;   for (int kt = 0; kt < nk; ++kt) {
;     const char* st = lds + (kt & 1) * 65536;
;     ldfrag(st, 0, 0);
;     mma(1);
;     pat_rd();
;     if (kt + 1 < nk) glds(kt + 1, (kt + 1) & 1);
;     ldfrag(st, 1, 1);
;     mma(0);
;     pat_rd();
;     ldfrag(st, 2, 0);
;     mma(1);
;     pat_rd();
;     ldfrag(st, 3, 1);
;     mma(0);
;     pat_rd();
;     asm volatile("s_waitcnt vmcnt(0)" ::: "memory");
;     __syncthreads();
	s_add_u32 m0, s100, 0xc000
	v_add_u32_e32 v166, s21, v202
	v_add_u32_e32 v167, s21, v203
	ds_read_b128 v[176:179], v166 offset:32768
	ds_read_b128 v[180:183], v167 offset:32768
	v_add_u32_e32 v166, s21, v175
	v_add_u32_e32 v167, s21, v185
	ds_read_b128 v[186:189], v166 offset:32768
	ds_read_b128 v[190:193], v167 offset:32768
	global_load_lds_dwordx4 v241, s[22:23]
	s_add_u32 m0, s100, 0xe000
	v_add_u32_e32 v241, 0x80, v241
	global_load_lds_dwordx4 v243, s[22:23]
	v_add_u32_e32 v243, 0x80, v243
	s_waitcnt vmcnt(6)
	s_barrier
	s_waitcnt lgkmcnt(0)
	v_mfma_f32_32x32x16_bf16 v[34:49], v[194:197], v[130:133], v[34:49]
	v_mfma_f32_32x32x16_bf16 v[2:17], v[194:197], v[146:149], v[2:17]
	v_mfma_f32_32x32x16_bf16 v[34:49], v[198:201], v[134:137], v[34:49]
	v_mfma_f32_32x32x16_bf16 v[2:17], v[198:201], v[150:153], v[2:17]
	v_mfma_f32_32x32x16_bf16 v[34:49], v[228:231], v[138:141], v[34:49]
	v_mfma_f32_32x32x16_bf16 v[2:17], v[228:231], v[158:161], v[2:17]
	v_mfma_f32_32x32x16_bf16 v[34:49], v[232:235], v[142:145], v[34:49]
	v_mfma_f32_32x32x16_bf16 v[2:17], v[232:235], v[162:165], v[2:17]
	s_barrier
	s_add_u32 m0, s100, 0x4000
	v_add_u32_e32 v166, s21, v244
	v_add_u32_e32 v167, s21, v245
	ds_read_b128 v[130:133], v166
	ds_read_b128 v[134:137], v167
	ds_read_b128 v[146:149], v166 offset:4096
	ds_read_b128 v[150:153], v167 offset:4096
	v_add_u32_e32 v166, s21, v246
	v_add_u32_e32 v167, s21, v247
	ds_read_b128 v[138:141], v166
	ds_read_b128 v[142:145], v167
	ds_read_b128 v[158:161], v166 offset:4096
	ds_read_b128 v[162:165], v167 offset:4096
	s_mov_b64 exec, s[12:13]
	global_load_lds_dwordx4 v237, s[18:19]
	s_mov_b64 exec, -1
	v_add_u32_e32 v237, 0x80, v237
	s_add_u32 m0, s100, 0x6000
	s_mov_b64 exec, s[16:17]
	global_load_lds_dwordx4 v239, s[18:19]
	s_mov_b64 exec, -1
	v_add_u32_e32 v239, 0x80, v239
	s_barrier
	s_waitcnt lgkmcnt(0)
	v_mfma_f32_32x32x16_bf16 v[114:129], v[176:179], v[130:133], v[114:129]
	v_mfma_f32_32x32x16_bf16 v[82:97], v[176:179], v[146:149], v[82:97]
	v_mfma_f32_32x32x16_bf16 v[114:129], v[180:183], v[134:137], v[114:129]
	v_mfma_f32_32x32x16_bf16 v[82:97], v[180:183], v[150:153], v[82:97]
	v_mfma_f32_32x32x16_bf16 v[114:129], v[186:189], v[138:141], v[114:129]
	v_mfma_f32_32x32x16_bf16 v[82:97], v[186:189], v[158:161], v[82:97]
	v_mfma_f32_32x32x16_bf16 v[114:129], v[190:193], v[142:145], v[114:129]
	v_mfma_f32_32x32x16_bf16 v[82:97], v[190:193], v[162:165], v[82:97]
	s_barrier
	s_add_u32 m0, s100, 0x18000
	v_add_u32_e32 v166, s21, v202
	v_add_u32_e32 v167, s21, v203
	ds_read_b128 v[194:197], v166 offset:49152
	ds_read_b128 v[198:201], v167 offset:49152
	v_add_u32_e32 v166, s21, v175
	v_add_u32_e32 v167, s21, v185
	ds_read_b128 v[228:231], v166 offset:49152
	ds_read_b128 v[232:235], v167 offset:49152
	global_load_lds_dwordx4 v240, s[22:23]
	s_add_u32 m0, s100, 0x1a000
	v_add_u32_e32 v240, 0x80, v240
	global_load_lds_dwordx4 v242, s[22:23]
	v_add_u32_e32 v242, 0x80, v242
	s_barrier
	s_waitcnt lgkmcnt(0)
	v_mfma_f32_32x32x16_bf16 v[98:113], v[194:197], v[130:133], v[98:113]
	v_mfma_f32_32x32x16_bf16 v[66:81], v[194:197], v[146:149], v[66:81]
	v_mfma_f32_32x32x16_bf16 v[98:113], v[198:201], v[134:137], v[98:113]
	v_mfma_f32_32x32x16_bf16 v[66:81], v[198:201], v[150:153], v[66:81]
	v_mfma_f32_32x32x16_bf16 v[98:113], v[228:231], v[138:141], v[98:113]
	v_mfma_f32_32x32x16_bf16 v[66:81], v[228:231], v[158:161], v[66:81]
	v_mfma_f32_32x32x16_bf16 v[98:113], v[232:235], v[142:145], v[98:113]
	v_mfma_f32_32x32x16_bf16 v[66:81], v[232:235], v[162:165], v[66:81]
	s_barrier
	s_add_u32 m0, s100, 0x10000
	v_add_u32_e32 v166, s21, v244
	v_add_u32_e32 v167, s21, v245
	ds_read_b128 v[130:133], v166 offset:16384
	ds_read_b128 v[134:137], v167 offset:16384
	ds_read_b128 v[146:149], v166 offset:20480
	ds_read_b128 v[150:153], v167 offset:20480
	v_add_u32_e32 v166, s21, v246
	v_add_u32_e32 v167, s21, v247
	ds_read_b128 v[138:141], v166 offset:16384
	ds_read_b128 v[142:145], v167 offset:16384
	ds_read_b128 v[158:161], v166 offset:20480
	ds_read_b128 v[162:165], v167 offset:20480
	s_mov_b64 exec, s[10:11]
	global_load_lds_dwordx4 v236, s[18:19]
	s_mov_b64 exec, -1
	v_add_u32_e32 v236, 0x80, v236
	s_add_u32 m0, s100, 0x12000
	s_mov_b64 exec, s[14:15]
	global_load_lds_dwordx4 v238, s[18:19]
	s_mov_b64 exec, -1
	v_add_u32_e32 v238, 0x80, v238
	s_waitcnt vmcnt(10)
	s_barrier
	s_waitcnt lgkmcnt(0)
	v_mfma_f32_32x32x16_bf16 v[50:65], v[176:179], v[130:133], v[50:65]
	v_mfma_f32_32x32x16_bf16 v[18:33], v[176:179], v[146:149], v[18:33]
	v_mfma_f32_32x32x16_bf16 v[50:65], v[180:183], v[134:137], v[50:65]
	v_mfma_f32_32x32x16_bf16 v[18:33], v[180:183], v[150:153], v[18:33]
	v_mfma_f32_32x32x16_bf16 v[50:65], v[186:189], v[138:141], v[50:65]
	v_mfma_f32_32x32x16_bf16 v[18:33], v[186:189], v[158:161], v[18:33]
	v_mfma_f32_32x32x16_bf16 v[50:65], v[190:193], v[142:145], v[50:65]
	v_mfma_f32_32x32x16_bf16 v[18:33], v[190:193], v[162:165], v[18:33]
	s_barrier
	s_add_u32 m0, s100, 0x1c000
	ds_read_b128 v[176:179], v202 offset:32768
	ds_read_b128 v[180:183], v203 offset:32768
	ds_read_b128 v[186:189], v175 offset:32768
	ds_read_b128 v[190:193], v185 offset:32768
	global_load_lds_dwordx4 v241, s[22:23]
	s_add_u32 m0, s100, 0x1e000
	v_add_u32_e32 v241, 0x80, v241
	global_load_lds_dwordx4 v243, s[22:23]
	v_add_u32_e32 v243, 0x80, v243
	s_waitcnt vmcnt(6)
	s_barrier
; template <bool SWAP>
; DI void gemm_mainloop(f32x16 (&acc)[4][2], const u16* __restrict__ A, int lda, int rlo, int rhi,
;                       const u16* __restrict__ B, int ldb, int K, char* lds, const u16* zero_line) {
;     ...
; #pragma unroll 2
;   for (int kt = 0; kt < nk; ++kt) {
;     const char* st = lds + (kt & 1) * 65536;
;     ldfrag(st, 0, 0);
;     mma(1);
;     pat_rd();
;     if (kt + 1 < nk) glds(kt + 1, (kt + 1) & 1);
;     ldfrag(st, 1, 1);
;     mma(0);
;     pat_rd();
;     ldfrag(st, 2, 0);
;     mma(1);
;     pat_rd();
;     ldfrag(st, 3, 1);
;     mma(0);
;     pat_rd();
;     asm volatile("s_waitcnt vmcnt(0)" ::: "memory");
;     __syncthreads();
;   }
;   mma(1);
	s_waitcnt lgkmcnt(0)
	v_mfma_f32_32x32x16_bf16 v[34:49], v[194:197], v[130:133], v[34:49]
	v_mfma_f32_32x32x16_bf16 v[2:17], v[194:197], v[146:149], v[2:17]
	v_mfma_f32_32x32x16_bf16 v[34:49], v[198:201], v[134:137], v[34:49]
	v_mfma_f32_32x32x16_bf16 v[2:17], v[198:201], v[150:153], v[2:17]
	v_mfma_f32_32x32x16_bf16 v[34:49], v[228:231], v[138:141], v[34:49]
	v_mfma_f32_32x32x16_bf16 v[2:17], v[228:231], v[158:161], v[2:17]
	v_mfma_f32_32x32x16_bf16 v[34:49], v[232:235], v[142:145], v[34:49]
	v_mfma_f32_32x32x16_bf16 v[2:17], v[232:235], v[162:165], v[2:17]
	s_add_i32 s29, s29, 2
	s_cmp_lt_u32 s29, 14
	s_barrier
	s_cbranch_scc1 .Lg8_u0m
	ds_read_b128 v[130:133], v244
	ds_read_b128 v[134:137], v245
	ds_read_b128 v[138:141], v246
	ds_read_b128 v[142:145], v247
	ds_read_b128 v[146:149], v244 offset:4096
	ds_read_b128 v[150:153], v245 offset:4096
	ds_read_b128 v[158:161], v246 offset:4096
	ds_read_b128 v[162:165], v247 offset:4096
	s_add_u32 m0, s100, 0x14000
	s_mov_b64 exec, s[12:13]
	global_load_lds_dwordx4 v237, s[18:19]
	s_mov_b64 exec, -1
	v_add_u32_e32 v237, 0x80, v237
	s_add_u32 m0, s100, 0x16000
	s_mov_b64 exec, s[16:17]
	global_load_lds_dwordx4 v239, s[18:19]
	s_mov_b64 exec, -1
	v_add_u32_e32 v239, 0x80, v239
	s_barrier
	s_waitcnt lgkmcnt(0)
	v_mfma_f32_32x32x16_bf16 v[114:129], v[176:179], v[130:133], v[114:129]
	v_mfma_f32_32x32x16_bf16 v[82:97], v[176:179], v[146:149], v[82:97]
	v_mfma_f32_32x32x16_bf16 v[114:129], v[180:183], v[134:137], v[114:129]
	v_mfma_f32_32x32x16_bf16 v[82:97], v[180:183], v[150:153], v[82:97]
	v_mfma_f32_32x32x16_bf16 v[114:129], v[186:189], v[138:141], v[114:129]
	v_mfma_f32_32x32x16_bf16 v[82:97], v[186:189], v[158:161], v[82:97]
	v_mfma_f32_32x32x16_bf16 v[114:129], v[190:193], v[142:145], v[114:129]
	v_mfma_f32_32x32x16_bf16 v[82:97], v[190:193], v[162:165], v[82:97]
	s_barrier
	ds_read_b128 v[194:197], v202 offset:49152
	ds_read_b128 v[198:201], v203 offset:49152
	ds_read_b128 v[228:231], v175 offset:49152
	ds_read_b128 v[232:235], v185 offset:49152
	s_barrier
	s_waitcnt lgkmcnt(0)
	v_mfma_f32_32x32x16_bf16 v[98:113], v[194:197], v[130:133], v[98:113]
	v_mfma_f32_32x32x16_bf16 v[66:81], v[194:197], v[146:149], v[66:81]
	v_mfma_f32_32x32x16_bf16 v[98:113], v[198:201], v[134:137], v[98:113]
	v_mfma_f32_32x32x16_bf16 v[66:81], v[198:201], v[150:153], v[66:81]
	v_mfma_f32_32x32x16_bf16 v[98:113], v[228:231], v[138:141], v[98:113]
	v_mfma_f32_32x32x16_bf16 v[66:81], v[228:231], v[158:161], v[66:81]
	v_mfma_f32_32x32x16_bf16 v[98:113], v[232:235], v[142:145], v[98:113]
	v_mfma_f32_32x32x16_bf16 v[66:81], v[232:235], v[162:165], v[66:81]
	s_barrier
	ds_read_b128 v[130:133], v244 offset:16384
	ds_read_b128 v[134:137], v245 offset:16384
	ds_read_b128 v[138:141], v246 offset:16384
	ds_read_b128 v[142:145], v247 offset:16384
	ds_read_b128 v[146:149], v244 offset:20480
	ds_read_b128 v[150:153], v245 offset:20480
	ds_read_b128 v[158:161], v246 offset:20480
	ds_read_b128 v[162:165], v247 offset:20480
	s_waitcnt vmcnt(4)
	s_barrier
	s_waitcnt lgkmcnt(0)
	v_mfma_f32_32x32x16_bf16 v[50:65], v[176:179], v[130:133], v[50:65]
	v_mfma_f32_32x32x16_bf16 v[18:33], v[176:179], v[146:149], v[18:33]
	v_mfma_f32_32x32x16_bf16 v[50:65], v[180:183], v[134:137], v[50:65]
	v_mfma_f32_32x32x16_bf16 v[18:33], v[180:183], v[150:153], v[18:33]
	v_mfma_f32_32x32x16_bf16 v[50:65], v[186:189], v[138:141], v[50:65]
	v_mfma_f32_32x32x16_bf16 v[18:33], v[186:189], v[158:161], v[18:33]
	v_mfma_f32_32x32x16_bf16 v[50:65], v[190:193], v[142:145], v[50:65]
	v_mfma_f32_32x32x16_bf16 v[18:33], v[190:193], v[162:165], v[18:33]
	v_mfma_f32_32x32x16_bf16 v[34:49], v[194:197], v[130:133], v[34:49]
	v_mfma_f32_32x32x16_bf16 v[2:17], v[194:197], v[146:149], v[2:17]
	v_mfma_f32_32x32x16_bf16 v[34:49], v[198:201], v[134:137], v[34:49]
	v_mfma_f32_32x32x16_bf16 v[2:17], v[198:201], v[150:153], v[2:17]
	v_mfma_f32_32x32x16_bf16 v[34:49], v[228:231], v[138:141], v[34:49]
	v_mfma_f32_32x32x16_bf16 v[2:17], v[228:231], v[158:161], v[2:17]
	v_mfma_f32_32x32x16_bf16 v[34:49], v[232:235], v[142:145], v[34:49]
	v_mfma_f32_32x32x16_bf16 v[2:17], v[232:235], v[162:165], v[2:17]
	s_barrier
; template <bool SWAP>
; DI void gemm_mainloop(f32x16 (&acc)[4][2], const u16* __restrict__ A, int lda, int rlo, int rhi,
;                       const u16* __restrict__ B, int ldb, int K, char* lds, const u16* zero_line) {
;     ...
; #pragma unroll 2
;   for (int kt = 0; kt < nk; ++kt) {
;     const char* st = lds + (kt & 1) * 65536;
;     ldfrag(st, 0, 0);
;     mma(1);
;     pat_rd();
;     if (kt + 1 < nk) glds(kt + 1, (kt + 1) & 1);
;     ldfrag(st, 1, 1);
;     mma(0);
;     pat_rd();
;     ldfrag(st, 2, 0);
;     mma(1);
;     pat_rd();
;     ldfrag(st, 3, 1);
;     mma(0);
;     pat_rd();
;     asm volatile("s_waitcnt vmcnt(0)" ::: "memory");
;     __syncthreads();
;   }
;   mma(1);
	v_add_u32_e32 v166, s21, v202
	v_add_u32_e32 v167, s21, v203
	ds_read_b128 v[176:179], v166 offset:32768
	ds_read_b128 v[180:183], v167 offset:32768
	v_add_u32_e32 v166, s21, v175
	v_add_u32_e32 v167, s21, v185
	ds_read_b128 v[186:189], v166 offset:32768
	ds_read_b128 v[190:193], v167 offset:32768
	v_add_u32_e32 v166, s21, v244
	v_add_u32_e32 v167, s21, v245
	ds_read_b128 v[130:133], v166
	ds_read_b128 v[134:137], v167
	ds_read_b128 v[146:149], v166 offset:4096
	ds_read_b128 v[150:153], v167 offset:4096
	v_add_u32_e32 v166, s21, v246
	v_add_u32_e32 v167, s21, v247
	ds_read_b128 v[138:141], v166
	ds_read_b128 v[142:145], v167
	ds_read_b128 v[158:161], v166 offset:4096
	ds_read_b128 v[162:165], v167 offset:4096
	s_waitcnt vmcnt(2)
	s_barrier
	s_waitcnt lgkmcnt(0)
	v_mfma_f32_32x32x16_bf16 v[114:129], v[176:179], v[130:133], v[114:129]
	v_mfma_f32_32x32x16_bf16 v[82:97], v[176:179], v[146:149], v[82:97]
	v_mfma_f32_32x32x16_bf16 v[114:129], v[180:183], v[134:137], v[114:129]
	v_mfma_f32_32x32x16_bf16 v[82:97], v[180:183], v[150:153], v[82:97]
	v_mfma_f32_32x32x16_bf16 v[114:129], v[186:189], v[138:141], v[114:129]
	v_mfma_f32_32x32x16_bf16 v[82:97], v[186:189], v[158:161], v[82:97]
	v_mfma_f32_32x32x16_bf16 v[114:129], v[190:193], v[142:145], v[114:129]
	v_mfma_f32_32x32x16_bf16 v[82:97], v[190:193], v[162:165], v[82:97]
	s_barrier
	v_add_u32_e32 v166, s21, v202
	v_add_u32_e32 v167, s21, v203
	ds_read_b128 v[194:197], v166 offset:49152
	ds_read_b128 v[198:201], v167 offset:49152
	v_add_u32_e32 v166, s21, v175
	v_add_u32_e32 v167, s21, v185
	ds_read_b128 v[228:231], v166 offset:49152
	ds_read_b128 v[232:235], v167 offset:49152
	s_waitcnt vmcnt(0)
	s_barrier
	s_waitcnt lgkmcnt(0)
	v_mfma_f32_32x32x16_bf16 v[98:113], v[194:197], v[130:133], v[98:113]
	v_mfma_f32_32x32x16_bf16 v[66:81], v[194:197], v[146:149], v[66:81]
	v_mfma_f32_32x32x16_bf16 v[98:113], v[198:201], v[134:137], v[98:113]
	v_mfma_f32_32x32x16_bf16 v[66:81], v[198:201], v[150:153], v[66:81]
	v_mfma_f32_32x32x16_bf16 v[98:113], v[228:231], v[138:141], v[98:113]
	v_mfma_f32_32x32x16_bf16 v[66:81], v[228:231], v[158:161], v[66:81]
	v_mfma_f32_32x32x16_bf16 v[98:113], v[232:235], v[142:145], v[98:113]
	v_mfma_f32_32x32x16_bf16 v[66:81], v[232:235], v[162:165], v[66:81]
	s_barrier
	v_add_u32_e32 v166, s21, v244
	v_add_u32_e32 v167, s21, v245
	ds_read_b128 v[130:133], v166 offset:16384
	ds_read_b128 v[134:137], v167 offset:16384
	ds_read_b128 v[146:149], v166 offset:20480
	ds_read_b128 v[150:153], v167 offset:20480
	v_add_u32_e32 v166, s21, v246
	v_add_u32_e32 v167, s21, v247
	ds_read_b128 v[138:141], v166 offset:16384
	ds_read_b128 v[142:145], v167 offset:16384
	ds_read_b128 v[158:161], v166 offset:20480
	ds_read_b128 v[162:165], v167 offset:20480
	s_barrier
	s_waitcnt lgkmcnt(0)
	v_mfma_f32_32x32x16_bf16 v[50:65], v[176:179], v[130:133], v[50:65]
	v_mfma_f32_32x32x16_bf16 v[18:33], v[176:179], v[146:149], v[18:33]
	v_mfma_f32_32x32x16_bf16 v[50:65], v[180:183], v[134:137], v[50:65]
	v_mfma_f32_32x32x16_bf16 v[18:33], v[180:183], v[150:153], v[18:33]
	v_mfma_f32_32x32x16_bf16 v[50:65], v[186:189], v[138:141], v[50:65]
	v_mfma_f32_32x32x16_bf16 v[18:33], v[186:189], v[158:161], v[18:33]
	v_mfma_f32_32x32x16_bf16 v[50:65], v[190:193], v[142:145], v[50:65]
	v_mfma_f32_32x32x16_bf16 v[18:33], v[190:193], v[162:165], v[18:33]
	v_mfma_f32_32x32x16_bf16 v[34:49], v[194:197], v[130:133], v[34:49]
	v_mfma_f32_32x32x16_bf16 v[2:17], v[194:197], v[146:149], v[2:17]
	v_mfma_f32_32x32x16_bf16 v[34:49], v[198:201], v[134:137], v[34:49]
	v_mfma_f32_32x32x16_bf16 v[2:17], v[198:201], v[150:153], v[2:17]
	v_mfma_f32_32x32x16_bf16 v[34:49], v[228:231], v[138:141], v[34:49]
	v_mfma_f32_32x32x16_bf16 v[2:17], v[228:231], v[158:161], v[2:17]
	v_mfma_f32_32x32x16_bf16 v[34:49], v[232:235], v[142:145], v[34:49]
	v_mfma_f32_32x32x16_bf16 v[2:17], v[232:235], v[162:165], v[2:17]
	s_barrier
	s_cmp_eq_u32 s101, 0
	s_cbranch_scc0 .Lg8_u0m_p1
	s_barrier

; DI int opaque_tid() { int t = threadIdx.x; asm volatile("" : "+v"(t)); return t; }
; template <bool SWAP>
; DI void gemm_mainloop(f32x16 (&acc)[4][2], const u16* __restrict__ A, int lda, int rlo, int rhi,
;                       const u16* __restrict__ B, int ldb, int K, char* lds, const u16* zero_line) {
;   const int tid = opaque_tid(), lane = tid & 63, w = tid >> 6;
;   const int wm = w >> 2, wn = w & 3;
;   const int h = lane >> 5, r = lane & 31;
;   const int lr = tid >> 3, lc = tid & 7;
; #pragma unroll
;   for (int mi = 0; mi < 4; ++mi)
; #pragma unroll
;     for (int ni = 0; ni < 2; ++ni)
; #pragma unroll
;       for (int i = 0; i < 16; ++i) acc[mi][ni][i] = 0.f;
;   const int gch = (lc ^ ((lr >> 1) & 7)) * 8;
;   const u16* ap = A + (ptrdiff_t)lr * lda + gch;
;   const u16* bp = B + (ptrdiff_t)lr * ldb + gch;
;   const int nk = K >> 6;
;   typedef __attribute__((address_space(3))) unsigned lds_u32;
;   auto glds = [&](int kt, int st) {
;     char* as_ = lds + st * 65536 + tid * 16;
; #pragma unroll
;     for (int i = 0; i < 4; ++i) {
;       const int rr = lr + 64 * i;
;       const u16* srca = (rr >= rlo && rr < rhi) ? (ap + (ptrdiff_t)(64 * i) * lda + kt * 64) : (zero_line + lc * 8);
;       __builtin_amdgcn_global_load_lds((const unsigned*)srca, (lds_u32*)(as_ + i * 8192), 16, 0, 0);
;       __builtin_amdgcn_global_load_lds((const unsigned*)(bp + (ptrdiff_t)(64 * i) * ldb + kt * 64), (lds_u32*)(as_ + 32768 + i * 8192), 16, 0, 0);
;     }
;   };
; template <int EPI>
; DI void phase_gemm(const Params& p, const GemmArgs& ga, char* lds) {
;     ...
;   for (int it = 0; it * (int)gridDim.x < total; ++it) {
;     const int lt = logical_index(it);
;     if (lt >= total) continue;
;     int mt, nt;
;     tile_mn(lt, Mt, ga.Nt, mt, nt);
;     int bb, tokbase, S, pos0, rlo = 0, rhi = 256;
;     if (EPI == EPI_UP) {
;       bb = 0; tokbase = 0; S = NTOK;
;       pos0 = 254 * mt - 1;
;       rlo = (mt == 0) ? 1 : 0;
;       rhi = NTOK - pos0; if (rhi > 256) rhi = 256;
;     } else {
;       seq_of_token(mt * 256, bb, tokbase, S);
;       pos0 = mt * 256 - tokbase;
;     }
;     const u16* A = ga.A + (ptrdiff_t)(tokbase + pos0) * ga.lda;
;     const u16* B = ga.Bt + (size_t)(nt * 256) * ga.K;
.LBB0_167:
	s_add_i32 s30, s10, s25
	s_cmpk_gt_i32 s30, 0x10ab
	s_cbranch_scc1 .LBB0_166
	s_mul_hi_i32 s10, s30, 0x2e8ba2e9
	s_lshr_b32 s11, s10, 31
	s_ashr_i32 s10, s10, 5
	s_add_i32 s31, s10, s11
	s_lshl_b32 s10, s31, 3
	s_sub_i32 s11, 0xc2, s10
	s_min_u32 s11, s11, 8
	v_cvt_f32_ubyte0_e32 v0, s11
	v_rcp_iflag_f32_e32 v0, v0
	s_sub_i32 s15, 0, s11
	s_mul_i32 s12, s31, 0xffffff50
	s_add_i32 s12, s12, s30
	v_mul_f32_e32 v0, 0x4f7ffffe, v0
	v_cvt_u32_f32_e32 v0, v0
	s_abs_i32 s14, s12
	s_ashr_i32 s13, s12, 31
	s_waitcnt vmcnt(5)
	v_mov_b32_e32 v13, v204
	v_readfirstlane_b32 s16, v0
	s_mul_i32 s15, s15, s16
	s_mul_hi_u32 s15, s16, s15
	s_add_i32 s16, s16, s15
	s_mul_hi_u32 s15, s14, s16
	s_mul_i32 s16, s15, s11
	s_sub_i32 s14, s14, s16
	s_add_i32 s16, s15, 1
	s_sub_i32 s17, s14, s11
	s_cmp_ge_u32 s14, s11
	s_cselect_b32 s15, s16, s15
	s_cselect_b32 s14, s17, s14
	s_add_i32 s16, s15, 1
	s_cmp_ge_u32 s14, s11
	s_cselect_b32 s14, s16, s15
	s_xor_b32 s14, s14, s13
	s_sub_i32 s28, s14, s13
	s_mul_i32 s34, s28, s11
	s_add_i32 s14, s12, s10
	s_sub_i32 s27, s14, s34
	s_mulk_i32 s27, 0xfe
	s_lshl_b32 s10, s28, 8
	s_add_i32 s20, s27, -1
	s_ashr_i32 s11, s10, 31
	s_ashr_i32 s21, s20, 31
	s_lshl_b64 s[22:23], s[10:11], 11
	v_readlane_b32 s10, v253, 47
	v_readlane_b32 s11, v253, 48
	s_add_u32 s10, s10, s22
	s_addc_u32 s11, s11, s23
	s_lshl_b64 s[12:13], s[20:21], 11
	s_add_u32 s12, s90, s12
	v_ashrrev_i32_e32 v2, 3, v13
	s_waitcnt vmcnt(4)
	v_lshrrev_b32_e32 v15, 1, v2
	s_addc_u32 s13, s91, s13
	s_sub_i32 s15, 0xc001, s27
	v_xor_b32_e32 v0, v15, v13
	v_ashrrev_i32_e32 v3, 31, v2
	s_min_i32 s18, s15, 0x100
	v_lshlrev_b64 v[4:5], 11, v[2:3]
	v_lshlrev_b32_e32 v0, 4, v0
	s_cmp_eq_u32 s14, s34
	v_and_b32_e32 v10, 31, v13
	v_lshl_add_u64 v[6:7], s[12:13], 0, v[4:5]
	v_and_b32_e32 v0, 0x70, v0
	v_lshl_add_u64 v[8:9], s[10:11], 0, v[4:5]
	v_lshrrev_b32_e32 v16, 1, v13
	s_cselect_b64 s[14:15], -1, 0
	v_lshl_add_u64 v[6:7], v[6:7], 0, v[0:1]
	v_lshl_add_u64 v[8:9], v[8:9], 0, v[0:1]
	v_and_or_b32 v0, v16, s51, v10
	v_cndmask_b32_e64 v12, 0, 1, s[14:15]
	v_lshlrev_b32_e32 v175, 7, v0
	v_lshlrev_b32_e32 v0, 7, v13
	v_lshlrev_b32_e32 v177, 4, v13
	v_and_b32_e32 v176, 0x6f80, v0
	v_cmp_ge_i32_e64 s[10:11], v2, v12
	v_cmp_gt_i32_e64 s[12:13], s18, v2
	v_and_b32_e32 v0, 0x70, v177
	v_add_u32_e32 v178, 0x8000, v177
	v_lshl_add_u64 v[158:159], s[80:81], 0, v[0:1]
	s_and_b64 s[10:11], s[10:11], s[12:13]
	v_readfirstlane_b32 s12, v177
	v_cndmask_b32_e64 v11, v159, v7, s[10:11]
	v_cndmask_b32_e64 v10, v158, v6, s[10:11]
	s_mov_b32 m0, s12
	v_readfirstlane_b32 s12, v178
	v_add_u32_e32 v0, 64, v2
	s_barrier
	s_mov_b32 m0, s12
	v_cmp_ge_i32_e64 s[12:13], v0, v12
	v_cmp_gt_i32_e64 s[14:15], s18, v0
	s_mov_b64 s[16:17], 0x20000
	v_add_u32_e32 v0, 0x2000, v177
	v_lshl_add_u64 v[10:11], v[6:7], 0, s[16:17]
	s_and_b64 s[12:13], s[12:13], s[14:15]
	v_readfirstlane_b32 s14, v0
	v_add_u32_e32 v179, 0xa000, v177
	v_cndmask_b32_e64 v11, v159, v11, s[12:13]
	v_cndmask_b32_e64 v10, v158, v10, s[12:13]
	s_mov_b32 m0, s14
	v_readfirstlane_b32 s14, v179
	v_add_u32_e32 v3, 0x80, v2
	v_lshl_add_u64 v[10:11], v[8:9], 0, s[16:17]
	s_mov_b32 m0, s14
	v_cmp_ge_i32_e64 s[14:15], v3, v12
	v_cmp_gt_i32_e64 s[16:17], s18, v3
	s_mov_b64 s[36:37], 0x40000
	v_add_u32_e32 v180, 0x4000, v177
	v_lshl_add_u64 v[10:11], v[6:7], 0, s[36:37]
	s_and_b64 s[14:15], s[14:15], s[16:17]
	v_readfirstlane_b32 s16, v180
	v_add_u32_e32 v181, 0xc000, v177
	v_cndmask_b32_e64 v11, v159, v11, s[14:15]
	v_cndmask_b32_e64 v10, v158, v10, s[14:15]
	s_mov_b32 m0, s16
	v_readfirstlane_b32 s16, v181
	v_add_u32_e32 v2, 0xc0, v2
	v_lshl_add_u64 v[10:11], v[8:9], 0, s[36:37]
	s_mov_b32 m0, s16
	v_cmp_ge_i32_e64 s[16:17], v2, v12
	v_cmp_gt_i32_e64 s[18:19], s18, v2
	s_mov_b64 s[36:37], 0x60000
	v_add_u32_e32 v182, 0x6000, v177
	v_lshl_add_u64 v[2:3], v[6:7], 0, s[36:37]
	s_and_b64 s[16:17], s[16:17], s[18:19]
	v_readfirstlane_b32 s18, v182
	v_add_u32_e32 v183, 0xe000, v177
	v_cndmask_b32_e64 v3, v159, v3, s[16:17]
	v_cndmask_b32_e64 v2, v158, v2, s[16:17]
	s_mov_b32 m0, s18
	v_readfirstlane_b32 s18, v183
	v_lshl_add_u64 v[2:3], v[8:9], 0, s[36:37]
	s_mov_b32 m0, s18
	s_sub_i32 s18, s30, s34
	s_mulk_i32 s31, 0xa8
	v_bfe_u32 v14, v13, 5, 1
	s_sub_i32 s18, s18, s31
	v_bfe_u32 v17, v13, 1, 3
	v_bitop3_b32 v2, v16, v14, 7 bitop3:0x6c
	s_mulk_i32 s18, 0xfe
	v_lshlrev_b32_e32 v185, 4, v2
	v_bitop3_b32 v2, v14, v17, 2 bitop3:0x36
	s_add_i32 s18, s18, -2
	v_lshlrev_b32_e32 v186, 4, v2
	v_bitop3_b32 v2, v14, v17, 4 bitop3:0x36
	s_ashr_i32 s19, s18, 31
	v_lshlrev_b32_e32 v187, 4, v2
	v_bitop3_b32 v2, v14, v17, 6 bitop3:0x36
	s_lshl_b64 s[18:19], s[18:19], 11
	v_bitop3_b32 v6, v15, 7, v13 bitop3:0x48
	v_lshlrev_b32_e32 v188, 4, v2
	v_lshl_add_u64 v[2:3], v[4:5], 0, s[18:19]
	v_lshlrev_b32_e32 v6, 4, v6
	v_or_b32_e32 v2, v2, v6
	v_lshl_add_u64 v[160:161], s[70:71], 0, v[2:3]
	v_lshl_add_u64 v[2:3], v[4:5], 0, s[22:23]
	s_waitcnt vmcnt(0)
	v_or_b32_e32 v2, v2, v6
	v_lshl_add_u64 v[162:163], s[70:71], 0, v[2:3]
	v_mov_b32_e32 v130, 0
	v_mov_b32_e32 v2, 0
	s_mov_b32 s29, 1
	v_add_u32_e32 v189, 0x10000, v177
	v_add_u32_e32 v190, 0x18000, v177
	v_add_u32_e32 v191, 0x12000, v177
	v_add_u32_e32 v192, 0x1a000, v177
	v_add_u32_e32 v193, 0x14000, v177
	v_add_u32_e32 v194, 0x1c000, v177
	v_add_u32_e32 v195, 0x16000, v177
	v_add_u32_e32 v196, 0x1e000, v177
	v_add_u32_e32 v197, 0x10000, v175
	v_or_b32_e32 v198, 0x10000, v176
	s_mov_b64 s[18:19], 0
	v_mov_b32_e32 v3, v2
	v_mov_b32_e32 v4, v2
	v_mov_b32_e32 v5, v2
	v_mov_b32_e32 v6, v2
	v_mov_b32_e32 v7, v2
	v_mov_b32_e32 v8, v2
	v_mov_b32_e32 v9, v2
	v_mov_b32_e32 v10, v2
	v_mov_b32_e32 v11, v2
	v_mov_b32_e32 v12, v2
	v_mov_b32_e32 v13, v2
	v_mov_b32_e32 v14, v2
	v_mov_b32_e32 v15, v2
	v_mov_b32_e32 v16, v2
	v_mov_b32_e32 v17, v2
	s_waitcnt vmcnt(0)
; template <bool SWAP>
; DI void gemm_mainloop(f32x16 (&acc)[4][2], const u16* __restrict__ A, int lda, int rlo, int rhi,
;                       const u16* __restrict__ B, int ldb, int K, char* lds, const u16* zero_line) {
;     ...
; #pragma unroll
;   for (int mi = 0; mi < 4; ++mi)
; #pragma unroll
;     for (int ni = 0; ni < 2; ++ni)
; #pragma unroll
;       for (int i = 0; i < 16; ++i) acc[mi][ni][i] = 0.f;
;   const int gch = (lc ^ ((lr >> 1) & 7)) * 8;
;   const u16* ap = A + (ptrdiff_t)lr * lda + gch;
;   const u16* bp = B + (ptrdiff_t)lr * ldb + gch;
;   const int nk = K >> 6;
;   typedef __attribute__((address_space(3))) unsigned lds_u32;
;   auto glds = [&](int kt, int st) {
;     char* as_ = lds + st * 65536 + tid * 16;
; #pragma unroll
;     for (int i = 0; i < 4; ++i) {
;       const int rr = lr + 64 * i;
;       const u16* srca = (rr >= rlo && rr < rhi) ? (ap + (ptrdiff_t)(64 * i) * lda + kt * 64) : (zero_line + lc * 8);
;       __builtin_amdgcn_global_load_lds((const unsigned*)srca, (lds_u32*)(as_ + i * 8192), 16, 0, 0);
;       __builtin_amdgcn_global_load_lds((const unsigned*)(bp + (ptrdiff_t)(64 * i) * ldb + kt * 64), (lds_u32*)(as_ + 32768 + i * 8192), 16, 0, 0);
;     }
;   };
;   const int sw = (r >> 1) & 7;
;   const int arow_off = (wm * 128 + r) * 128;
;   const int brow_off = 32768 + (wn * 64 + r) * 128;
;   __syncthreads();
;   glds(0, 0);
;   asm volatile("s_waitcnt vmcnt(0)" ::: "memory");
;   __syncthreads();
;   bf16x8 fa[2][4], fb[2][2];
; #pragma unroll
;   for (int mi = 0; mi < 4; ++mi)
; #pragma unroll
;     for (int e = 0; e < 8; ++e) fa[1][mi][e] = 0;
; #pragma unroll
;   for (int ni = 0; ni < 2; ++ni)
; #pragma unroll
;     for (int e = 0; e < 8; ++e) fb[1][ni][e] = 0;
	v_mov_b32_e32 v18, v2
	v_mov_b32_e32 v19, v2
	v_mov_b32_e32 v20, v2
	v_mov_b32_e32 v21, v2
	v_mov_b32_e32 v22, v2
	v_mov_b32_e32 v23, v2
	v_mov_b32_e32 v24, v2
	v_mov_b32_e32 v25, v2
	v_mov_b32_e32 v26, v2
	v_mov_b32_e32 v27, v2
	v_mov_b32_e32 v28, v2
	v_mov_b32_e32 v29, v2
	v_mov_b32_e32 v30, v2
	v_mov_b32_e32 v31, v2
	v_mov_b32_e32 v32, v2
	v_mov_b32_e32 v33, v2
	v_mov_b32_e32 v34, v2
	v_mov_b32_e32 v35, v2
	v_mov_b32_e32 v36, v2
	v_mov_b32_e32 v37, v2
	v_mov_b32_e32 v38, v2
	v_mov_b32_e32 v39, v2
	v_mov_b32_e32 v40, v2
	v_mov_b32_e32 v41, v2
	v_mov_b32_e32 v42, v2
	v_mov_b32_e32 v43, v2
	v_mov_b32_e32 v44, v2
	v_mov_b32_e32 v45, v2
	v_mov_b32_e32 v46, v2
	v_mov_b32_e32 v47, v2
	v_mov_b32_e32 v48, v2
	v_mov_b32_e32 v49, v2
	v_mov_b32_e32 v50, v2
	v_mov_b32_e32 v51, v2
	v_mov_b32_e32 v52, v2
	v_mov_b32_e32 v53, v2
	v_mov_b32_e32 v54, v2
	v_mov_b32_e32 v55, v2
	v_mov_b32_e32 v56, v2
	v_mov_b32_e32 v57, v2
	v_mov_b32_e32 v58, v2
	v_mov_b32_e32 v59, v2
	v_mov_b32_e32 v60, v2
	v_mov_b32_e32 v61, v2
	v_mov_b32_e32 v62, v2
	v_mov_b32_e32 v63, v2
	v_mov_b32_e32 v64, v2
	v_mov_b32_e32 v65, v2
	v_mov_b32_e32 v66, v2
	v_mov_b32_e32 v67, v2
	v_mov_b32_e32 v68, v2
	v_mov_b32_e32 v69, v2
	v_mov_b32_e32 v70, v2
	v_mov_b32_e32 v71, v2
	v_mov_b32_e32 v72, v2
	v_mov_b32_e32 v73, v2
	v_mov_b32_e32 v74, v2
	v_mov_b32_e32 v75, v2
	v_mov_b32_e32 v76, v2
	v_mov_b32_e32 v77, v2
	v_mov_b32_e32 v78, v2
	v_mov_b32_e32 v79, v2
	v_mov_b32_e32 v80, v2
	v_mov_b32_e32 v81, v2
	v_mov_b32_e32 v82, v2
	v_mov_b32_e32 v83, v2
	v_mov_b32_e32 v84, v2
	v_mov_b32_e32 v85, v2
	v_mov_b32_e32 v86, v2
	v_mov_b32_e32 v87, v2
	v_mov_b32_e32 v88, v2
	v_mov_b32_e32 v89, v2
	v_mov_b32_e32 v90, v2
	v_mov_b32_e32 v91, v2
	v_mov_b32_e32 v92, v2
	v_mov_b32_e32 v93, v2
	v_mov_b32_e32 v94, v2
	v_mov_b32_e32 v95, v2
	v_mov_b32_e32 v96, v2
	v_mov_b32_e32 v97, v2
	v_mov_b32_e32 v98, v2
	v_mov_b32_e32 v99, v2
	v_mov_b32_e32 v100, v2
	v_mov_b32_e32 v101, v2
	v_mov_b32_e32 v102, v2
	v_mov_b32_e32 v103, v2
	v_mov_b32_e32 v104, v2
	v_mov_b32_e32 v105, v2
	v_mov_b32_e32 v106, v2
	v_mov_b32_e32 v107, v2
	v_mov_b32_e32 v108, v2
	v_mov_b32_e32 v109, v2
	v_mov_b32_e32 v110, v2
	v_mov_b32_e32 v111, v2
	v_mov_b32_e32 v112, v2
	v_mov_b32_e32 v113, v2
	v_mov_b32_e32 v114, v2
	v_mov_b32_e32 v115, v2
	v_mov_b32_e32 v116, v2
	v_mov_b32_e32 v117, v2
	v_mov_b32_e32 v118, v2
	v_mov_b32_e32 v119, v2
	v_mov_b32_e32 v120, v2
	v_mov_b32_e32 v121, v2
	v_mov_b32_e32 v122, v2
	v_mov_b32_e32 v123, v2
	v_mov_b32_e32 v124, v2
	v_mov_b32_e32 v125, v2
	v_mov_b32_e32 v126, v2
	v_mov_b32_e32 v127, v2
	v_mov_b32_e32 v128, v2
	v_mov_b32_e32 v129, v2
	v_mov_b32_e32 v131, v130
	v_mov_b32_e32 v132, v130
	v_mov_b32_e32 v133, v130
	v_mov_b32_e32 v134, v130
	v_mov_b32_e32 v135, v130
	v_mov_b32_e32 v136, v130
	v_mov_b32_e32 v137, v130
	v_mov_b32_e32 v138, v130
	v_mov_b32_e32 v139, v130
	v_mov_b32_e32 v140, v130
	v_mov_b32_e32 v141, v130
	v_mov_b32_e32 v142, v130
	v_mov_b32_e32 v143, v130
	v_mov_b32_e32 v144, v130
	v_mov_b32_e32 v145, v130
	v_mov_b32_e32 v146, v130
	v_mov_b32_e32 v147, v130
	v_mov_b32_e32 v148, v130
	v_mov_b32_e32 v149, v130
	v_mov_b32_e32 v150, v130
	v_mov_b32_e32 v151, v130
	v_mov_b32_e32 v152, v130
	v_mov_b32_e32 v153, v130
	s_mov_b64 s[30:31], 0x37f8900
	s_waitcnt lgkmcnt(0)
	s_barrier
	s_add_i32 s18, s27, -1
	s_ashr_i32 s19, s18, 31
	s_lshl_b64 s[18:19], s[18:19], 11
	s_add_u32 s18, s90, s18
	s_addc_u32 s19, s91, s19
	v_readlane_b32 s22, v253, 47
	v_readlane_b32 s23, v253, 48
	s_lshl_b32 s21, s28, 19
	s_add_u32 s22, s22, s21
	s_addc_u32 s23, s23, 0
	v_and_b32_e32 v130, 63, v204
	v_lshrrev_b32_e32 v131, 6, v204
	v_lshrrev_b32_e32 v132, 3, v204
	v_lshrrev_b32_e32 v0, 4, v130
	v_lshl_add_u32 v0, v131, 2, v0
	v_xor_b32_e32 v0, v0, v130
	v_and_b32_e32 v0, 7, v0
	v_lshlrev_b32_e32 v133, 4, v0
	v_lshl_add_u32 v236, v132, 11, v133
	v_add_u32_e32 v237, 0x20000, v236
	v_add_u32_e32 v238, 0x40000, v236
	v_add_u32_e32 v239, 0x60000, v236
	v_and_b32_e32 v0, 31, v132
	v_lshrrev_b32_e32 v130, 5, v132
	v_lshl_add_u32 v0, v130, 6, v0
	v_lshl_add_u32 v240, v0, 11, v133
	v_add_u32_e32 v241, 0x10000, v240
	v_add_u32_e32 v242, 0x40000, v240
	v_add_u32_e32 v243, 0x50000, v240
	v_and_b32_e32 v132, 31, v204
	v_lshrrev_b32_e32 v0, 2, v131
	v_lshl_add_u32 v0, v0, 6, v132
	v_lshlrev_b32_e32 v248, 7, v0
	v_and_b32_e32 v0, 3, v131
	v_lshl_add_u32 v0, v0, 5, v132
	v_lshlrev_b32_e32 v249, 7, v0
	v_bfe_u32 v0, v204, 5, 1
	v_bfe_u32 v130, v132, 1, 3
	v_or_b32_e32 v133, 0, v0
	v_xor_b32_e32 v133, v133, v130
	v_lshlrev_b32_e32 v244, 4, v133
	v_or_b32_e32 v133, 2, v0
	v_xor_b32_e32 v133, v133, v130
	v_lshlrev_b32_e32 v245, 4, v133
	v_or_b32_e32 v133, 4, v0
	v_xor_b32_e32 v133, v133, v130
	v_lshlrev_b32_e32 v246, 4, v133
	v_or_b32_e32 v133, 6, v0
	v_xor_b32_e32 v133, v133, v130
	v_lshlrev_b32_e32 v247, 4, v133
	v_add_u32_e32 v202, v249, v244
	v_add_u32_e32 v203, v249, v245
	v_add_u32_e32 v175, v249, v246
	v_add_u32_e32 v185, v249, v247
	v_add_u32_e32 v244, v248, v244
	v_add_u32_e32 v245, v248, v245
	v_add_u32_e32 v246, v248, v246
	v_add_u32_e32 v247, v248, v247
	v_lshlrev_b32_e32 v131, 10, v131
	s_nop 0
	v_readfirstlane_b32 s100, v131
	v_mov_b32_e32 v146, 0
	v_mov_b32_e32 v147, 0
	v_mov_b32_e32 v148, 0
	v_mov_b32_e32 v149, 0
	v_lshlrev_b32_e32 v130, 4, v204
	v_add_u32_e32 v132, 0x10000, v130
	s_not_b64 exec, s[10:11]
	ds_write_b128 v130, v[146:149]
	ds_write_b128 v132, v[146:149]
	s_not_b64 exec, s[12:13]
	ds_write_b128 v130, v[146:149] offset:16384
	ds_write_b128 v132, v[146:149] offset:16384
	s_not_b64 exec, s[14:15]
	ds_write_b128 v130, v[146:149] offset:8192
	ds_write_b128 v132, v[146:149] offset:8192
	s_not_b64 exec, s[16:17]
	ds_write_b128 v130, v[146:149] offset:24576
	ds_write_b128 v132, v[146:149] offset:24576
	s_mov_b64 exec, -1
	s_mov_b32 s29, 0
	s_mov_b32 s21, 0x10000
	s_waitcnt lgkmcnt(0)
	s_cmp_eq_u32 s27, 0
	s_cbranch_scc1 .Lg8_u1_msk
	s_cmp_gt_i32 s20, 0xbf00
	s_cbranch_scc1 .Lg8_u1_msk
	s_add_u32 m0, s100, 0x8000
	s_nop 0
	global_load_lds_dwordx4 v240, s[22:23]
	s_add_u32 m0, s100, 0xa000
	v_add_u32_e32 v240, 0x80, v240
	global_load_lds_dwordx4 v242, s[22:23]
	v_add_u32_e32 v242, 0x80, v242
	s_add_u32 m0, s100, 0x0
	s_nop 0
	global_load_lds_dwordx4 v236, s[18:19]
	s_add_u32 m0, s100, 0x2000
	v_add_u32_e32 v236, 0x80, v236
	global_load_lds_dwordx4 v238, s[18:19]
	v_add_u32_e32 v238, 0x80, v238
	s_add_u32 m0, s100, 0xc000
	s_nop 0
	global_load_lds_dwordx4 v241, s[22:23]
	s_add_u32 m0, s100, 0xe000
	v_add_u32_e32 v241, 0x80, v241
	global_load_lds_dwordx4 v243, s[22:23]
	v_add_u32_e32 v243, 0x80, v243
	s_add_u32 m0, s100, 0x4000
	s_nop 0
	global_load_lds_dwordx4 v237, s[18:19]
	s_add_u32 m0, s100, 0x6000
	v_add_u32_e32 v237, 0x80, v237
	global_load_lds_dwordx4 v239, s[18:19]
	v_add_u32_e32 v239, 0x80, v239
	s_cmp_eq_u32 s101, 1
	s_cbranch_scc0 .Lg8_u1u_p0
	s_barrier

; DI int opaque_tid() { int t = threadIdx.x; asm volatile("" : "+v"(t)); return t; }
; template <bool SWAP>
; DI void gemm_mainloop(f32x16 (&acc)[4][2], const u16* __restrict__ A, int lda, int rlo, int rhi,
;                       const u16* __restrict__ B, int ldb, int K, char* lds, const u16* zero_line) {
;   const int tid = opaque_tid(), lane = tid & 63, w = tid >> 6;
;   const int wm = w >> 2, wn = w & 3;
;   const int h = lane >> 5, r = lane & 31;
;   const int lr = tid >> 3, lc = tid & 7;
; #pragma unroll
;   for (int mi = 0; mi < 4; ++mi)
; #pragma unroll
;     for (int ni = 0; ni < 2; ++ni)
; #pragma unroll
;       for (int i = 0; i < 16; ++i) acc[mi][ni][i] = 0.f;
;   const int gch = (lc ^ ((lr >> 1) & 7)) * 8;
;   const u16* ap = A + (ptrdiff_t)lr * lda + gch;
;   const u16* bp = B + (ptrdiff_t)lr * ldb + gch;
;   const int nk = K >> 6;
;   typedef __attribute__((address_space(3))) unsigned lds_u32;
;   auto glds = [&](int kt, int st) {
;     char* as_ = lds + st * 65536 + tid * 16;
; #pragma unroll
;     for (int i = 0; i < 4; ++i) {
;       const int rr = lr + 64 * i;
;       const u16* srca = (rr >= rlo && rr < rhi) ? (ap + (ptrdiff_t)(64 * i) * lda + kt * 64) : (zero_line + lc * 8);
;       __builtin_amdgcn_global_load_lds((const unsigned*)srca, (lds_u32*)(as_ + i * 8192), 16, 0, 0);
;       __builtin_amdgcn_global_load_lds((const unsigned*)(bp + (ptrdiff_t)(64 * i) * ldb + kt * 64), (lds_u32*)(as_ + 32768 + i * 8192), 16, 0, 0);
;     }
;   };
;   const int sw = (r >> 1) & 7;
;   const int arow_off = (wm * 128 + r) * 128;
;   const int brow_off = 32768 + (wn * 64 + r) * 128;
;   __syncthreads();
;   glds(0, 0);
;   asm volatile("s_waitcnt vmcnt(0)" ::: "memory");
;   __syncthreads();
; template <int EPI>
; DI void phase_gemm(const Params& p, const GemmArgs& ga, char* lds) {
;     ...
;     tile_mn(lt, Mt, ga.Nt, mt, nt);
;     int bb, tokbase, S, pos0, rlo = 0, rhi = 256;
;     if (EPI == EPI_UP) {
;       bb = 0; tokbase = 0; S = NTOK;
;       pos0 = 254 * mt - 1;
;       rlo = (mt == 0) ? 1 : 0;
;       rhi = NTOK - pos0; if (rhi > 256) rhi = 256;
;     } else {
;       seq_of_token(mt * 256, bb, tokbase, S);
;       pos0 = mt * 256 - tokbase;
;     }
;     const u16* A = ga.A + (ptrdiff_t)(tokbase + pos0) * ga.lda;
;     const u16* B = ga.Bt + (size_t)(nt * 256) * ga.K;
.LBB0_196:
	s_add_i32 s6, s6, s27
	s_cmpk_gt_i32 s6, 0x8ff
	s_cbranch_scc1 .LBB0_195
	s_mul_hi_i32 s7, s6, 0x2aaaaaab
	s_lshr_b32 s8, s7, 31
	s_ashr_i32 s7, s7, 4
	s_add_i32 s8, s7, s8
	s_mul_i32 s7, s8, 0xffffffa0
	s_add_i32 s9, s7, s6
	s_ashr_i32 s7, s9, 31
	s_lshr_b32 s7, s7, 29
	s_lshl_b32 s6, s8, 3
	s_add_i32 s10, s9, s7
	s_add_i32 s6, s9, s6
	s_and_b32 s31, s10, -8
	s_sub_i32 s30, s6, s31
	s_lshl_b32 s12, s30, 8
	s_ashr_i32 s13, s12, 31
	s_lshl_b64 s[6:7], s[12:13], 11
	s_add_u32 s20, s90, s6
	s_addc_u32 s21, s91, s7
	s_lshl_b32 s6, s10, 5
	s_and_b32 s14, s6, 0xffffff00
	s_ashr_i32 s15, s14, 31
	s_lshl_b64 s[18:19], s[14:15], 11
	v_readlane_b32 s6, v253, 43
	v_readlane_b32 s7, v253, 44
	s_add_u32 s22, s6, s18
	s_addc_u32 s23, s7, s19
	s_cmp_gt_i32 s9, 63
	s_cselect_b64 s[16:17], -1, 0
	s_mov_b64 s[6:7], -1
	s_and_b64 vcc, exec, s[16:17]
	s_mul_i32 s13, s8, 0x58
	s_cbranch_vccz .LBB0_203
	v_mov_b32_e32 v12, v204
	s_mov_b64 s[10:11], 0x20000
	v_ashrrev_i32_e32 v2, 3, v12
	v_lshrrev_b32_e32 v14, 1, v2
	v_xor_b32_e32 v0, v14, v12
	v_ashrrev_i32_e32 v3, 31, v2
	v_lshlrev_b64 v[4:5], 11, v[2:3]
	v_lshlrev_b32_e32 v0, 4, v0
	v_and_b32_e32 v10, 31, v12
	v_lshl_add_u64 v[6:7], s[20:21], 0, v[4:5]
	v_and_b32_e32 v0, 0x70, v0
	v_lshl_add_u64 v[8:9], s[22:23], 0, v[4:5]
	v_lshrrev_b32_e32 v15, 1, v12
	v_lshl_add_u64 v[6:7], v[6:7], 0, v[0:1]
	v_lshl_add_u64 v[8:9], v[8:9], 0, v[0:1]
	v_and_or_b32 v0, v15, s51, v10
	v_lshlrev_b32_e32 v169, 7, v0
	v_lshlrev_b32_e32 v0, 7, v12
	v_lshlrev_b32_e32 v171, 4, v12
	v_and_b32_e32 v170, 0x6f80, v0
	v_and_b32_e32 v0, 0x70, v171
	v_add_u32_e32 v172, 0x8000, v171
	v_lshl_add_u64 v[156:157], s[80:81], 0, v[0:1]
	v_cmp_gt_u32_e32 vcc, s50, v2
	v_readfirstlane_b32 s6, v171
	s_mov_b32 m0, s6
	v_cndmask_b32_e32 v11, v157, v7, vcc
	v_cndmask_b32_e32 v10, v156, v6, vcc
	v_readfirstlane_b32 s6, v172
	v_add_u32_e32 v0, 64, v2
	v_add_u32_e32 v173, 0x2000, v171
	s_barrier
	s_mov_b32 m0, s6
	v_lshl_add_u64 v[10:11], v[6:7], 0, s[10:11]
	v_cmp_gt_u32_e64 s[6:7], s50, v0
	v_readfirstlane_b32 s8, v173
	v_add_u32_e32 v174, 0xa000, v171
	v_cndmask_b32_e64 v11, v157, v11, s[6:7]
	v_cndmask_b32_e64 v10, v156, v10, s[6:7]
	s_mov_b32 m0, s8
	v_readfirstlane_b32 s8, v174
	v_lshl_add_u64 v[10:11], v[8:9], 0, s[10:11]
	s_mov_b32 m0, s8
	v_add_u32_e32 v0, 0x80, v2
	s_mov_b64 s[24:25], 0x40000
	v_add_u32_e32 v175, 0x4000, v171
	v_lshl_add_u64 v[10:11], v[6:7], 0, s[24:25]
	v_cmp_gt_u32_e64 s[8:9], s50, v0
	v_readfirstlane_b32 s10, v175
	v_add_u32_e32 v176, 0xc000, v171
	v_cndmask_b32_e64 v11, v157, v11, s[8:9]
	v_cndmask_b32_e64 v10, v156, v10, s[8:9]
	s_mov_b32 m0, s10
	v_readfirstlane_b32 s10, v176
	v_add_u32_e32 v0, 0xc0, v2
	s_mov_b64 s[34:35], 0x60000
	v_add_u32_e32 v177, 0x6000, v171
	v_lshl_add_u64 v[10:11], v[8:9], 0, s[24:25]
	s_mov_b32 m0, s10
	v_lshl_add_u64 v[2:3], v[6:7], 0, s[34:35]
	v_cmp_gt_u32_e64 s[10:11], s50, v0
	v_readfirstlane_b32 s24, v177
	v_add_u32_e32 v178, 0xe000, v171
	v_cndmask_b32_e64 v3, v157, v3, s[10:11]
	v_cndmask_b32_e64 v2, v156, v2, s[10:11]
	s_mov_b32 m0, s24
	v_readfirstlane_b32 s24, v178
	v_lshl_add_u64 v[2:3], v[8:9], 0, s[34:35]
	s_mov_b32 m0, s24
	v_bfe_u32 v13, v12, 5, 1
	v_bfe_u32 v16, v12, 1, 3
	v_bitop3_b32 v0, v15, v13, 7 bitop3:0x6c
	s_sub_i32 s24, s28, s31
	v_lshlrev_b32_e32 v179, 4, v0
	v_bitop3_b32 v0, v13, v16, 2 bitop3:0x36
	s_sub_i32 s24, s24, s13
	v_lshlrev_b32_e32 v180, 4, v0
	v_bitop3_b32 v0, v13, v16, 4 bitop3:0x36
	s_lshl_b32 s24, s24, 8
	v_lshlrev_b32_e32 v181, 4, v0
	v_bitop3_b32 v0, v13, v16, 6 bitop3:0x36
	s_ashr_i32 s25, s24, 31
	v_lshlrev_b32_e32 v182, 4, v0
	s_lshl_b64 s[24:25], s[24:25], 11
	v_bitop3_b32 v0, v14, 7, v12 bitop3:0x48
	v_lshl_add_u64 v[2:3], v[4:5], 0, s[24:25]
	v_lshlrev_b32_e32 v0, 4, v0
	v_or_b32_e32 v2, v2, v0
	v_lshl_add_u64 v[158:159], s[70:71], 0, v[2:3]
	v_lshl_add_u64 v[2:3], v[4:5], 0, s[18:19]
	s_waitcnt vmcnt(0)
	v_lshl_add_u64 v[2:3], v[2:3], 0, v[0:1]
	v_lshl_add_u64 v[160:161], s[70:71], 0, v[2:3]
	v_mov_b32_e32 v130, 0
	v_mov_b32_e32 v2, 0
	s_mov_b32 s15, 1
	v_add_u32_e32 v183, 0x10000, v171
	v_add_u32_e32 v185, 0x18000, v171
	v_add_u32_e32 v186, 0x12000, v171
	v_add_u32_e32 v187, 0x1a000, v171
	v_add_u32_e32 v188, 0x14000, v171
	v_add_u32_e32 v189, 0x1c000, v171
	v_add_u32_e32 v190, 0x16000, v171
	v_add_u32_e32 v191, 0x1e000, v171
	v_add_u32_e32 v192, 0x10000, v169
	v_or_b32_e32 v193, 0x10000, v170
	s_mov_b64 s[24:25], 0
	v_mov_b32_e32 v3, v2
	v_mov_b32_e32 v4, v2
	v_mov_b32_e32 v5, v2
	v_mov_b32_e32 v6, v2
	v_mov_b32_e32 v7, v2
	v_mov_b32_e32 v8, v2
	v_mov_b32_e32 v9, v2
	v_mov_b32_e32 v10, v2
	v_mov_b32_e32 v11, v2
	v_mov_b32_e32 v12, v2
	v_mov_b32_e32 v13, v2
	v_mov_b32_e32 v14, v2
	v_mov_b32_e32 v15, v2
	v_mov_b32_e32 v16, v2
	v_mov_b32_e32 v17, v2
	v_mov_b32_e32 v18, v2
	v_mov_b32_e32 v19, v2
	v_mov_b32_e32 v20, v2
	v_mov_b32_e32 v21, v2
	v_mov_b32_e32 v22, v2
	v_mov_b32_e32 v23, v2
	v_mov_b32_e32 v24, v2
	v_mov_b32_e32 v25, v2
	v_mov_b32_e32 v26, v2
	v_mov_b32_e32 v27, v2
	v_mov_b32_e32 v28, v2
	v_mov_b32_e32 v29, v2
	v_mov_b32_e32 v30, v2
	v_mov_b32_e32 v31, v2
	v_mov_b32_e32 v32, v2
	v_mov_b32_e32 v33, v2
	v_mov_b32_e32 v34, v2
	v_mov_b32_e32 v35, v2
	v_mov_b32_e32 v36, v2
	v_mov_b32_e32 v37, v2
	v_mov_b32_e32 v38, v2
	v_mov_b32_e32 v39, v2
	v_mov_b32_e32 v40, v2
	v_mov_b32_e32 v41, v2
	v_mov_b32_e32 v42, v2
	v_mov_b32_e32 v43, v2
	v_mov_b32_e32 v44, v2
	v_mov_b32_e32 v45, v2
	v_mov_b32_e32 v46, v2
	v_mov_b32_e32 v47, v2
	v_mov_b32_e32 v48, v2
	v_mov_b32_e32 v49, v2
	v_mov_b32_e32 v50, v2
	v_mov_b32_e32 v51, v2
	v_mov_b32_e32 v52, v2
	v_mov_b32_e32 v53, v2
	v_mov_b32_e32 v54, v2
	v_mov_b32_e32 v55, v2
	v_mov_b32_e32 v56, v2
; template <bool SWAP>
; DI void gemm_mainloop(f32x16 (&acc)[4][2], const u16* __restrict__ A, int lda, int rlo, int rhi,
;                       const u16* __restrict__ B, int ldb, int K, char* lds, const u16* zero_line) {
;     ...
; #pragma unroll
;   for (int mi = 0; mi < 4; ++mi)
; #pragma unroll
;     for (int ni = 0; ni < 2; ++ni)
; #pragma unroll
;       for (int i = 0; i < 16; ++i) acc[mi][ni][i] = 0.f;
;   const int gch = (lc ^ ((lr >> 1) & 7)) * 8;
;   const u16* ap = A + (ptrdiff_t)lr * lda + gch;
;   const u16* bp = B + (ptrdiff_t)lr * ldb + gch;
;   const int nk = K >> 6;
;   typedef __attribute__((address_space(3))) unsigned lds_u32;
;   auto glds = [&](int kt, int st) {
;     char* as_ = lds + st * 65536 + tid * 16;
; #pragma unroll
;     for (int i = 0; i < 4; ++i) {
;       const int rr = lr + 64 * i;
;       const u16* srca = (rr >= rlo && rr < rhi) ? (ap + (ptrdiff_t)(64 * i) * lda + kt * 64) : (zero_line + lc * 8);
;       __builtin_amdgcn_global_load_lds((const unsigned*)srca, (lds_u32*)(as_ + i * 8192), 16, 0, 0);
;       __builtin_amdgcn_global_load_lds((const unsigned*)(bp + (ptrdiff_t)(64 * i) * ldb + kt * 64), (lds_u32*)(as_ + 32768 + i * 8192), 16, 0, 0);
;     }
;   };
;   const int sw = (r >> 1) & 7;
;   const int arow_off = (wm * 128 + r) * 128;
;   const int brow_off = 32768 + (wn * 64 + r) * 128;
;   __syncthreads();
;   glds(0, 0);
;   asm volatile("s_waitcnt vmcnt(0)" ::: "memory");
;   __syncthreads();
	v_mov_b32_e32 v57, v2
	v_mov_b32_e32 v58, v2
	v_mov_b32_e32 v59, v2
	v_mov_b32_e32 v60, v2
	v_mov_b32_e32 v61, v2
	v_mov_b32_e32 v62, v2
	v_mov_b32_e32 v63, v2
	v_mov_b32_e32 v64, v2
	v_mov_b32_e32 v65, v2
	v_mov_b32_e32 v66, v2
	v_mov_b32_e32 v67, v2
	v_mov_b32_e32 v68, v2
	v_mov_b32_e32 v69, v2
	v_mov_b32_e32 v70, v2
	v_mov_b32_e32 v71, v2
	v_mov_b32_e32 v72, v2
	v_mov_b32_e32 v73, v2
	v_mov_b32_e32 v74, v2
	v_mov_b32_e32 v75, v2
	v_mov_b32_e32 v76, v2
	v_mov_b32_e32 v77, v2
	v_mov_b32_e32 v78, v2
	v_mov_b32_e32 v79, v2
	v_mov_b32_e32 v80, v2
	v_mov_b32_e32 v81, v2
	v_mov_b32_e32 v82, v2
	v_mov_b32_e32 v83, v2
	v_mov_b32_e32 v84, v2
	v_mov_b32_e32 v85, v2
	v_mov_b32_e32 v86, v2
	v_mov_b32_e32 v87, v2
	v_mov_b32_e32 v88, v2
	v_mov_b32_e32 v89, v2
	v_mov_b32_e32 v90, v2
	v_mov_b32_e32 v91, v2
	v_mov_b32_e32 v92, v2
	v_mov_b32_e32 v93, v2
	v_mov_b32_e32 v94, v2
	v_mov_b32_e32 v95, v2
	v_mov_b32_e32 v96, v2
	v_mov_b32_e32 v97, v2
	v_mov_b32_e32 v98, v2
	v_mov_b32_e32 v99, v2
	v_mov_b32_e32 v100, v2
	v_mov_b32_e32 v101, v2
	v_mov_b32_e32 v102, v2
	v_mov_b32_e32 v103, v2
	v_mov_b32_e32 v104, v2
	v_mov_b32_e32 v105, v2
	v_mov_b32_e32 v106, v2
	v_mov_b32_e32 v107, v2
	v_mov_b32_e32 v108, v2
	v_mov_b32_e32 v109, v2
	v_mov_b32_e32 v110, v2
	v_mov_b32_e32 v111, v2
	v_mov_b32_e32 v112, v2
	v_mov_b32_e32 v113, v2
	v_mov_b32_e32 v114, v2
	v_mov_b32_e32 v115, v2
	v_mov_b32_e32 v116, v2
	v_mov_b32_e32 v117, v2
	v_mov_b32_e32 v118, v2
	v_mov_b32_e32 v119, v2
	v_mov_b32_e32 v120, v2
	v_mov_b32_e32 v121, v2
	v_mov_b32_e32 v122, v2
	v_mov_b32_e32 v123, v2
	v_mov_b32_e32 v124, v2
	v_mov_b32_e32 v125, v2
	v_mov_b32_e32 v126, v2
	v_mov_b32_e32 v127, v2
	v_mov_b32_e32 v128, v2
	v_mov_b32_e32 v129, v2
	v_mov_b32_e32 v131, v130
	v_mov_b32_e32 v132, v130
	v_mov_b32_e32 v133, v130
	v_mov_b32_e32 v134, v130
	v_mov_b32_e32 v135, v130
	v_mov_b32_e32 v136, v130
	v_mov_b32_e32 v137, v130
	v_mov_b32_e32 v138, v130
	v_mov_b32_e32 v139, v130
	v_mov_b32_e32 v140, v130
	v_mov_b32_e32 v141, v130
	v_mov_b32_e32 v146, v130
	v_mov_b32_e32 v147, v130
	v_mov_b32_e32 v148, v130
	v_mov_b32_e32 v149, v130
	v_mov_b32_e32 v142, v130
	v_mov_b32_e32 v143, v130
	v_mov_b32_e32 v144, v130
	v_mov_b32_e32 v145, v130
	v_mov_b32_e32 v150, v130
	v_mov_b32_e32 v151, v130
	v_mov_b32_e32 v152, v130
	v_mov_b32_e32 v153, v130
	s_waitcnt vmcnt(0) lgkmcnt(0)
	s_barrier
	s_ashr_i32 s7, s12, 31
	s_mov_b32 s6, s12
	s_lshl_b64 s[6:7], s[6:7], 11
	s_add_u32 s6, s90, s6
	s_addc_u32 s7, s91, s7
	s_ashr_i32 s9, s14, 31
	s_mov_b32 s8, s14
	s_lshl_b64 s[8:9], s[8:9], 11
	v_readlane_b32 s10, v253, 43
	v_readlane_b32 s11, v253, 44
	s_add_u32 s8, s10, s8
	s_addc_u32 s9, s11, s9
	v_and_b32_e32 v130, 63, v204
	v_lshrrev_b32_e32 v131, 6, v204
	v_lshrrev_b32_e32 v132, 3, v204
	v_lshrrev_b32_e32 v0, 4, v130
	v_lshl_add_u32 v0, v131, 2, v0
	v_xor_b32_e32 v0, v0, v130
	v_and_b32_e32 v0, 7, v0
	v_lshlrev_b32_e32 v133, 4, v0
	v_lshl_add_u32 v232, v132, 11, v133
	v_add_u32_e32 v233, 0x20000, v232
	v_add_u32_e32 v234, 0x40000, v232
	v_add_u32_e32 v235, 0x60000, v232
	v_and_b32_e32 v0, 31, v132
	v_lshrrev_b32_e32 v130, 5, v132
	v_lshl_add_u32 v0, v130, 6, v0
	v_lshl_add_u32 v236, v0, 11, v133
	v_add_u32_e32 v237, 0x10000, v236
	v_add_u32_e32 v238, 0x40000, v236
	v_add_u32_e32 v239, 0x50000, v236
	v_and_b32_e32 v132, 31, v204
	v_lshrrev_b32_e32 v0, 2, v131
	v_lshl_add_u32 v0, v0, 6, v132
	v_lshlrev_b32_e32 v244, 7, v0
	v_and_b32_e32 v0, 3, v131
	v_lshl_add_u32 v0, v0, 5, v132
	v_lshlrev_b32_e32 v245, 7, v0
	v_bfe_u32 v0, v204, 5, 1
	v_bfe_u32 v130, v132, 1, 3
	v_or_b32_e32 v133, 0, v0
	v_xor_b32_e32 v133, v133, v130
	v_lshlrev_b32_e32 v240, 4, v133
	v_or_b32_e32 v133, 2, v0
	v_xor_b32_e32 v133, v133, v130
	v_lshlrev_b32_e32 v241, 4, v133
	v_or_b32_e32 v133, 4, v0
	v_xor_b32_e32 v133, v133, v130
	v_lshlrev_b32_e32 v242, 4, v133
	v_or_b32_e32 v133, 6, v0
	v_xor_b32_e32 v133, v133, v130
	v_lshlrev_b32_e32 v243, 4, v133
	v_add_u32_e32 v164, v245, v240
	v_add_u32_e32 v165, v245, v241
	v_add_u32_e32 v202, v245, v242
	v_add_u32_e32 v203, v245, v243
	v_add_u32_e32 v240, v244, v240
	v_add_u32_e32 v241, v244, v241
	v_add_u32_e32 v242, v244, v242
	v_add_u32_e32 v243, v244, v243
	v_lshlrev_b32_e32 v131, 10, v131
	s_nop 0
	v_readfirstlane_b32 s100, v131
	v_mov_b32_e32 v146, 0
	v_mov_b32_e32 v147, 0
	v_mov_b32_e32 v148, 0
	v_mov_b32_e32 v149, 0
	v_lshlrev_b32_e32 v130, 4, v204
	v_add_u32_e32 v132, 0x10000, v130
	s_mov_b64 exec, -1
	s_mov_b32 s11, 0
	s_mov_b32 s10, 0x10000
	s_waitcnt lgkmcnt(0)
	s_add_u32 m0, s100, 0x8000
	s_nop 0
	global_load_lds_dwordx4 v236, s[8:9]
	s_add_u32 m0, s100, 0xa000
	v_add_u32_e32 v236, 0x80, v236
	global_load_lds_dwordx4 v238, s[8:9]
	v_add_u32_e32 v238, 0x80, v238
	s_add_u32 m0, s100, 0x0
	s_nop 0
	global_load_lds_dwordx4 v232, s[6:7]
	s_add_u32 m0, s100, 0x2000
	v_add_u32_e32 v232, 0x80, v232
	global_load_lds_dwordx4 v234, s[6:7]
	v_add_u32_e32 v234, 0x80, v234
	s_add_u32 m0, s100, 0xc000
	s_nop 0
	global_load_lds_dwordx4 v237, s[8:9]
	s_add_u32 m0, s100, 0xe000
	v_add_u32_e32 v237, 0x80, v237
	global_load_lds_dwordx4 v239, s[8:9]
	v_add_u32_e32 v239, 0x80, v239
	s_add_u32 m0, s100, 0x4000
	s_nop 0
	global_load_lds_dwordx4 v233, s[6:7]
	s_add_u32 m0, s100, 0x6000
	v_add_u32_e32 v233, 0x80, v233
	global_load_lds_dwordx4 v235, s[6:7]
	v_add_u32_e32 v235, 0x80, v235
	s_cmp_eq_u32 s101, 1
	s_cbranch_scc0 .Lg8_qa_p0
	s_barrier
; #define MFMA(a, b, c) __builtin_amdgcn_mfma_f32_32x32x16_bf16((a), (b), (c), 0, 0, 0)
; template <bool SWAP>
; DI void gemm_mainloop(f32x16 (&acc)[4][2], const u16* __restrict__ A, int lda, int rlo, int rhi,
;                       const u16* __restrict__ B, int ldb, int K, char* lds, const u16* zero_line) {
;     ...
;   auto ldfrag = [&](const char* st, int ks, int buf) {
;     const int co = ((2 * ks + h) ^ sw) << 4;
; #pragma unroll
;     for (int mi = 0; mi < 4; ++mi) fa[buf][mi] = *(const bf16x8*)(st + arow_off + mi * 4096 + co);
; #pragma unroll
;     for (int ni = 0; ni < 2; ++ni) fb[buf][ni] = *(const bf16x8*)(st + brow_off + ni * 4096 + co);
;   };
;   auto mma = [&](int buf) {
; #pragma unroll
;     for (int mi = 0; mi < 4; ++mi)
; #pragma unroll
;       for (int ni = 0; ni < 2; ++ni)
;         acc[mi][ni] = SWAP ? MFMA(fb[buf][ni], fa[buf][mi], acc[mi][ni]) : MFMA(fa[buf][mi], fb[buf][ni], acc[mi][ni]);
;   };
;   auto pat_rd = [&]() {
; #pragma unroll
;     for (int g = 0; g < 6; ++g) {
;       __builtin_amdgcn_sched_group_barrier(0x100, 1, 0);
;       __builtin_amdgcn_sched_group_barrier(0x008, 1, 0);
;     }
;     __builtin_amdgcn_sched_group_barrier(0x008, 2, 0);
;   };
; #pragma unroll 2
;   for (int kt = 0; kt < nk; ++kt) {
;     const char* st = lds + (kt & 1) * 65536;
;     ldfrag(st, 0, 0);
;     mma(1);
;     pat_rd();
;     if (kt + 1 < nk) glds(kt + 1, (kt + 1) & 1);
;     ldfrag(st, 1, 1);
;     mma(0);
;     pat_rd();
;     ldfrag(st, 2, 0);
;     mma(1);
;     pat_rd();
;     ldfrag(st, 3, 1);
;     mma(0);
;     pat_rd();
;     asm volatile("s_waitcnt vmcnt(0)" ::: "memory");
;     __syncthreads();
;   }
.Lg8_qa_p0:
	s_waitcnt vmcnt(4)
	s_barrier
	s_add_u32 m0, s100, 0x18000
	s_nop 0
	global_load_lds_dwordx4 v236, s[8:9]
	s_add_u32 m0, s100, 0x1a000
	v_add_u32_e32 v236, 0x80, v236
	global_load_lds_dwordx4 v238, s[8:9]
	v_add_u32_e32 v238, 0x80, v238
	s_add_u32 m0, s100, 0x10000
	s_nop 0
	global_load_lds_dwordx4 v232, s[6:7]
	s_add_u32 m0, s100, 0x12000
	v_add_u32_e32 v232, 0x80, v232
	global_load_lds_dwordx4 v234, s[6:7]
	v_add_u32_e32 v234, 0x80, v234
	s_add_u32 m0, s100, 0x1c000
	s_nop 0
	global_load_lds_dwordx4 v237, s[8:9]
	s_add_u32 m0, s100, 0x1e000
	v_add_u32_e32 v237, 0x80, v237
	global_load_lds_dwordx4 v239, s[8:9]
	v_add_u32_e32 v239, 0x80, v239
	s_waitcnt vmcnt(6)
	s_barrier
	ds_read_b128 v[170:173], v164 offset:32768
	ds_read_b128 v[174:177], v165 offset:32768
	ds_read_b128 v[178:181], v202 offset:32768
	ds_read_b128 v[186:189], v203 offset:32768
.Lg8_qa:
	s_add_u32 m0, s100, 0x14000
	ds_read_b128 v[130:133], v240
	ds_read_b128 v[134:137], v241
	ds_read_b128 v[138:141], v242
	ds_read_b128 v[142:145], v243
	ds_read_b128 v[146:149], v240 offset:4096
	ds_read_b128 v[150:153], v241 offset:4096
	ds_read_b128 v[156:159], v242 offset:4096
	ds_read_b128 v[160:163], v243 offset:4096
	global_load_lds_dwordx4 v233, s[6:7]
	s_add_u32 m0, s100, 0x16000
	v_add_u32_e32 v233, 0x80, v233
	global_load_lds_dwordx4 v235, s[6:7]
	v_add_u32_e32 v235, 0x80, v235
	s_barrier
	s_waitcnt lgkmcnt(0)
	v_mfma_f32_32x32x16_bf16 v[114:129], v[130:133], v[170:173], v[114:129]
	v_mfma_f32_32x32x16_bf16 v[82:97], v[146:149], v[170:173], v[82:97]
	v_mfma_f32_32x32x16_bf16 v[114:129], v[134:137], v[174:177], v[114:129]
	v_mfma_f32_32x32x16_bf16 v[82:97], v[150:153], v[174:177], v[82:97]
	v_mfma_f32_32x32x16_bf16 v[114:129], v[138:141], v[178:181], v[114:129]
	v_mfma_f32_32x32x16_bf16 v[82:97], v[156:159], v[178:181], v[82:97]
	v_mfma_f32_32x32x16_bf16 v[114:129], v[142:145], v[186:189], v[114:129]
	v_mfma_f32_32x32x16_bf16 v[82:97], v[160:163], v[186:189], v[82:97]
	s_barrier
	s_add_u32 m0, s100, 0x8000
	ds_read_b128 v[190:193], v164 offset:49152
	ds_read_b128 v[194:197], v165 offset:49152
	ds_read_b128 v[198:201], v202 offset:49152
	ds_read_b128 v[228:231], v203 offset:49152
	global_load_lds_dwordx4 v236, s[8:9]
	s_add_u32 m0, s100, 0xa000
	v_add_u32_e32 v236, 0x80, v236
	global_load_lds_dwordx4 v238, s[8:9]
	v_add_u32_e32 v238, 0x80, v238
	s_barrier
	s_waitcnt lgkmcnt(0)
	v_mfma_f32_32x32x16_bf16 v[98:113], v[130:133], v[190:193], v[98:113]
	v_mfma_f32_32x32x16_bf16 v[66:81], v[146:149], v[190:193], v[66:81]
	v_mfma_f32_32x32x16_bf16 v[98:113], v[134:137], v[194:197], v[98:113]
	v_mfma_f32_32x32x16_bf16 v[66:81], v[150:153], v[194:197], v[66:81]
	v_mfma_f32_32x32x16_bf16 v[98:113], v[138:141], v[198:201], v[98:113]
	v_mfma_f32_32x32x16_bf16 v[66:81], v[156:159], v[198:201], v[66:81]
	v_mfma_f32_32x32x16_bf16 v[98:113], v[142:145], v[228:231], v[98:113]
	v_mfma_f32_32x32x16_bf16 v[66:81], v[160:163], v[228:231], v[66:81]
	s_barrier
	s_add_u32 m0, s100, 0x0
	ds_read_b128 v[130:133], v240 offset:16384
	ds_read_b128 v[134:137], v241 offset:16384
	ds_read_b128 v[138:141], v242 offset:16384
	ds_read_b128 v[142:145], v243 offset:16384
	ds_read_b128 v[146:149], v240 offset:20480
	ds_read_b128 v[150:153], v241 offset:20480
	ds_read_b128 v[156:159], v242 offset:20480
	ds_read_b128 v[160:163], v243 offset:20480
	global_load_lds_dwordx4 v232, s[6:7]
	s_add_u32 m0, s100, 0x2000
	v_add_u32_e32 v232, 0x80, v232
	global_load_lds_dwordx4 v234, s[6:7]
	v_add_u32_e32 v234, 0x80, v234
	s_waitcnt vmcnt(10)
	s_barrier
	s_waitcnt lgkmcnt(0)
	v_mfma_f32_32x32x16_bf16 v[50:65], v[130:133], v[170:173], v[50:65]
	v_mfma_f32_32x32x16_bf16 v[18:33], v[146:149], v[170:173], v[18:33]
	v_mfma_f32_32x32x16_bf16 v[50:65], v[134:137], v[174:177], v[50:65]
	v_mfma_f32_32x32x16_bf16 v[18:33], v[150:153], v[174:177], v[18:33]
	v_mfma_f32_32x32x16_bf16 v[50:65], v[138:141], v[178:181], v[50:65]
	v_mfma_f32_32x32x16_bf16 v[18:33], v[156:159], v[178:181], v[18:33]
	v_mfma_f32_32x32x16_bf16 v[50:65], v[142:145], v[186:189], v[50:65]
	v_mfma_f32_32x32x16_bf16 v[18:33], v[160:163], v[186:189], v[18:33]
	s_barrier
	s_add_u32 m0, s100, 0xc000
	v_add_u32_e32 v246, s10, v164
	v_add_u32_e32 v247, s10, v165
	v_add_u32_e32 v248, s10, v202
	v_add_u32_e32 v249, s10, v203
	ds_read_b128 v[170:173], v246 offset:32768
	ds_read_b128 v[174:177], v247 offset:32768
	ds_read_b128 v[178:181], v248 offset:32768
	ds_read_b128 v[186:189], v249 offset:32768
	global_load_lds_dwordx4 v237, s[8:9]
	s_add_u32 m0, s100, 0xe000
	v_add_u32_e32 v237, 0x80, v237
	global_load_lds_dwordx4 v239, s[8:9]
	v_add_u32_e32 v239, 0x80, v239
	s_waitcnt vmcnt(6)
	s_barrier
	s_waitcnt lgkmcnt(0)
	v_mfma_f32_32x32x16_bf16 v[34:49], v[130:133], v[190:193], v[34:49]
	v_mfma_f32_32x32x16_bf16 v[2:17], v[146:149], v[190:193], v[2:17]
	v_mfma_f32_32x32x16_bf16 v[34:49], v[134:137], v[194:197], v[34:49]
	v_mfma_f32_32x32x16_bf16 v[2:17], v[150:153], v[194:197], v[2:17]
	v_mfma_f32_32x32x16_bf16 v[34:49], v[138:141], v[198:201], v[34:49]
	v_mfma_f32_32x32x16_bf16 v[2:17], v[156:159], v[198:201], v[2:17]
	v_mfma_f32_32x32x16_bf16 v[34:49], v[142:145], v[228:231], v[34:49]
	v_mfma_f32_32x32x16_bf16 v[2:17], v[160:163], v[228:231], v[2:17]
	s_barrier
	s_add_u32 m0, s100, 0x4000
	v_add_u32_e32 v246, s10, v240
	v_add_u32_e32 v247, s10, v241
	v_add_u32_e32 v248, s10, v242
	v_add_u32_e32 v249, s10, v243
	ds_read_b128 v[130:133], v246
	ds_read_b128 v[134:137], v247
	ds_read_b128 v[138:141], v248
	ds_read_b128 v[142:145], v249
	ds_read_b128 v[146:149], v246 offset:4096
	ds_read_b128 v[150:153], v247 offset:4096
	ds_read_b128 v[156:159], v248 offset:4096
	ds_read_b128 v[160:163], v249 offset:4096
	global_load_lds_dwordx4 v233, s[6:7]
	s_add_u32 m0, s100, 0x6000
	v_add_u32_e32 v233, 0x80, v233
	global_load_lds_dwordx4 v235, s[6:7]
	v_add_u32_e32 v235, 0x80, v235
	s_barrier
; #define MFMA(a, b, c) __builtin_amdgcn_mfma_f32_32x32x16_bf16((a), (b), (c), 0, 0, 0)
; template <bool SWAP>
; DI void gemm_mainloop(f32x16 (&acc)[4][2], const u16* __restrict__ A, int lda, int rlo, int rhi,
;                       const u16* __restrict__ B, int ldb, int K, char* lds, const u16* zero_line) {
;     ...
;   auto ldfrag = [&](const char* st, int ks, int buf) {
;     const int co = ((2 * ks + h) ^ sw) << 4;
; #pragma unroll
;     for (int mi = 0; mi < 4; ++mi) fa[buf][mi] = *(const bf16x8*)(st + arow_off + mi * 4096 + co);
; #pragma unroll
;     for (int ni = 0; ni < 2; ++ni) fb[buf][ni] = *(const bf16x8*)(st + brow_off + ni * 4096 + co);
;   };
;   auto mma = [&](int buf) {
; #pragma unroll
;     for (int mi = 0; mi < 4; ++mi)
; #pragma unroll
;       for (int ni = 0; ni < 2; ++ni)
;         acc[mi][ni] = SWAP ? MFMA(fb[buf][ni], fa[buf][mi], acc[mi][ni]) : MFMA(fa[buf][mi], fb[buf][ni], acc[mi][ni]);
;   };
;   auto pat_rd = [&]() {
; #pragma unroll
;     for (int g = 0; g < 6; ++g) {
;       __builtin_amdgcn_sched_group_barrier(0x100, 1, 0);
;       __builtin_amdgcn_sched_group_barrier(0x008, 1, 0);
;     }
;     __builtin_amdgcn_sched_group_barrier(0x008, 2, 0);
;   };
; #pragma unroll 2
;   for (int kt = 0; kt < nk; ++kt) {
;     const char* st = lds + (kt & 1) * 65536;
;     ldfrag(st, 0, 0);
;     mma(1);
;     pat_rd();
;     if (kt + 1 < nk) glds(kt + 1, (kt + 1) & 1);
;     ldfrag(st, 1, 1);
;     mma(0);
;     pat_rd();
;     ldfrag(st, 2, 0);
;     mma(1);
;     pat_rd();
;     ldfrag(st, 3, 1);
;     mma(0);
;     pat_rd();
;     asm volatile("s_waitcnt vmcnt(0)" ::: "memory");
;     __syncthreads();
;   }
;   mma(1);
	s_waitcnt lgkmcnt(0)
	v_mfma_f32_32x32x16_bf16 v[114:129], v[130:133], v[170:173], v[114:129]
	v_mfma_f32_32x32x16_bf16 v[82:97], v[146:149], v[170:173], v[82:97]
	v_mfma_f32_32x32x16_bf16 v[114:129], v[134:137], v[174:177], v[114:129]
	v_mfma_f32_32x32x16_bf16 v[82:97], v[150:153], v[174:177], v[82:97]
	v_mfma_f32_32x32x16_bf16 v[114:129], v[138:141], v[178:181], v[114:129]
	v_mfma_f32_32x32x16_bf16 v[82:97], v[156:159], v[178:181], v[82:97]
	v_mfma_f32_32x32x16_bf16 v[114:129], v[142:145], v[186:189], v[114:129]
	v_mfma_f32_32x32x16_bf16 v[82:97], v[160:163], v[186:189], v[82:97]
	s_barrier
	s_add_u32 m0, s100, 0x18000
	v_add_u32_e32 v246, s10, v164
	v_add_u32_e32 v247, s10, v165
	v_add_u32_e32 v248, s10, v202
	v_add_u32_e32 v249, s10, v203
	ds_read_b128 v[190:193], v246 offset:49152
	ds_read_b128 v[194:197], v247 offset:49152
	ds_read_b128 v[198:201], v248 offset:49152
	ds_read_b128 v[228:231], v249 offset:49152
	global_load_lds_dwordx4 v236, s[8:9]
	s_add_u32 m0, s100, 0x1a000
	v_add_u32_e32 v236, 0x80, v236
	global_load_lds_dwordx4 v238, s[8:9]
	v_add_u32_e32 v238, 0x80, v238
	s_barrier
	s_waitcnt lgkmcnt(0)
	v_mfma_f32_32x32x16_bf16 v[98:113], v[130:133], v[190:193], v[98:113]
	v_mfma_f32_32x32x16_bf16 v[66:81], v[146:149], v[190:193], v[66:81]
	v_mfma_f32_32x32x16_bf16 v[98:113], v[134:137], v[194:197], v[98:113]
	v_mfma_f32_32x32x16_bf16 v[66:81], v[150:153], v[194:197], v[66:81]
	v_mfma_f32_32x32x16_bf16 v[98:113], v[138:141], v[198:201], v[98:113]
	v_mfma_f32_32x32x16_bf16 v[66:81], v[156:159], v[198:201], v[66:81]
	v_mfma_f32_32x32x16_bf16 v[98:113], v[142:145], v[228:231], v[98:113]
	v_mfma_f32_32x32x16_bf16 v[66:81], v[160:163], v[228:231], v[66:81]
	s_barrier
	s_add_u32 m0, s100, 0x10000
	v_add_u32_e32 v246, s10, v240
	v_add_u32_e32 v247, s10, v241
	v_add_u32_e32 v248, s10, v242
	v_add_u32_e32 v249, s10, v243
	ds_read_b128 v[130:133], v246 offset:16384
	ds_read_b128 v[134:137], v247 offset:16384
	ds_read_b128 v[138:141], v248 offset:16384
	ds_read_b128 v[142:145], v249 offset:16384
	ds_read_b128 v[146:149], v246 offset:20480
	ds_read_b128 v[150:153], v247 offset:20480
	ds_read_b128 v[156:159], v248 offset:20480
	ds_read_b128 v[160:163], v249 offset:20480
	global_load_lds_dwordx4 v232, s[6:7]
	s_add_u32 m0, s100, 0x12000
	v_add_u32_e32 v232, 0x80, v232
	global_load_lds_dwordx4 v234, s[6:7]
	v_add_u32_e32 v234, 0x80, v234
	s_waitcnt vmcnt(10)
	s_barrier
	s_waitcnt lgkmcnt(0)
	v_mfma_f32_32x32x16_bf16 v[50:65], v[130:133], v[170:173], v[50:65]
	v_mfma_f32_32x32x16_bf16 v[18:33], v[146:149], v[170:173], v[18:33]
	v_mfma_f32_32x32x16_bf16 v[50:65], v[134:137], v[174:177], v[50:65]
	v_mfma_f32_32x32x16_bf16 v[18:33], v[150:153], v[174:177], v[18:33]
	v_mfma_f32_32x32x16_bf16 v[50:65], v[138:141], v[178:181], v[50:65]
	v_mfma_f32_32x32x16_bf16 v[18:33], v[156:159], v[178:181], v[18:33]
	v_mfma_f32_32x32x16_bf16 v[50:65], v[142:145], v[186:189], v[50:65]
	v_mfma_f32_32x32x16_bf16 v[18:33], v[160:163], v[186:189], v[18:33]
	s_barrier
	s_add_u32 m0, s100, 0x1c000
	ds_read_b128 v[170:173], v164 offset:32768
	ds_read_b128 v[174:177], v165 offset:32768
	ds_read_b128 v[178:181], v202 offset:32768
	ds_read_b128 v[186:189], v203 offset:32768
	global_load_lds_dwordx4 v237, s[8:9]
	s_add_u32 m0, s100, 0x1e000
	v_add_u32_e32 v237, 0x80, v237
	global_load_lds_dwordx4 v239, s[8:9]
	v_add_u32_e32 v239, 0x80, v239
	s_waitcnt vmcnt(6)
	s_barrier
	s_waitcnt lgkmcnt(0)
	v_mfma_f32_32x32x16_bf16 v[34:49], v[130:133], v[190:193], v[34:49]
	v_mfma_f32_32x32x16_bf16 v[2:17], v[146:149], v[190:193], v[2:17]
	v_mfma_f32_32x32x16_bf16 v[34:49], v[134:137], v[194:197], v[34:49]
	v_mfma_f32_32x32x16_bf16 v[2:17], v[150:153], v[194:197], v[2:17]
	v_mfma_f32_32x32x16_bf16 v[34:49], v[138:141], v[198:201], v[34:49]
	v_mfma_f32_32x32x16_bf16 v[2:17], v[156:159], v[198:201], v[2:17]
	v_mfma_f32_32x32x16_bf16 v[34:49], v[142:145], v[228:231], v[34:49]
	v_mfma_f32_32x32x16_bf16 v[2:17], v[160:163], v[228:231], v[2:17]
	s_add_i32 s11, s11, 2
	s_cmp_lt_u32 s11, 14
	s_barrier
	s_cbranch_scc1 .Lg8_qa
	ds_read_b128 v[130:133], v240
	ds_read_b128 v[134:137], v241
	ds_read_b128 v[138:141], v242
	ds_read_b128 v[142:145], v243
	ds_read_b128 v[146:149], v240 offset:4096
	ds_read_b128 v[150:153], v241 offset:4096
	ds_read_b128 v[156:159], v242 offset:4096
	ds_read_b128 v[160:163], v243 offset:4096
	s_add_u32 m0, s100, 0x14000
	s_nop 0
	global_load_lds_dwordx4 v233, s[6:7]
	s_add_u32 m0, s100, 0x16000
	v_add_u32_e32 v233, 0x80, v233
	global_load_lds_dwordx4 v235, s[6:7]
	v_add_u32_e32 v235, 0x80, v235
	s_barrier
	s_waitcnt lgkmcnt(0)
	v_mfma_f32_32x32x16_bf16 v[114:129], v[130:133], v[170:173], v[114:129]
	v_mfma_f32_32x32x16_bf16 v[82:97], v[146:149], v[170:173], v[82:97]
	v_mfma_f32_32x32x16_bf16 v[114:129], v[134:137], v[174:177], v[114:129]
	v_mfma_f32_32x32x16_bf16 v[82:97], v[150:153], v[174:177], v[82:97]
	v_mfma_f32_32x32x16_bf16 v[114:129], v[138:141], v[178:181], v[114:129]
	v_mfma_f32_32x32x16_bf16 v[82:97], v[156:159], v[178:181], v[82:97]
	v_mfma_f32_32x32x16_bf16 v[114:129], v[142:145], v[186:189], v[114:129]
	v_mfma_f32_32x32x16_bf16 v[82:97], v[160:163], v[186:189], v[82:97]
	s_barrier
	ds_read_b128 v[190:193], v164 offset:49152
	ds_read_b128 v[194:197], v165 offset:49152
	ds_read_b128 v[198:201], v202 offset:49152
	ds_read_b128 v[228:231], v203 offset:49152
	s_barrier
; template <bool SWAP>
; DI void gemm_mainloop(f32x16 (&acc)[4][2], const u16* __restrict__ A, int lda, int rlo, int rhi,
;                       const u16* __restrict__ B, int ldb, int K, char* lds, const u16* zero_line) {
;     ...
; #pragma unroll 2
;   for (int kt = 0; kt < nk; ++kt) {
;     const char* st = lds + (kt & 1) * 65536;
;     ldfrag(st, 0, 0);
;     mma(1);
;     pat_rd();
;     if (kt + 1 < nk) glds(kt + 1, (kt + 1) & 1);
;     ldfrag(st, 1, 1);
;     mma(0);
;     pat_rd();
;     ldfrag(st, 2, 0);
;     mma(1);
;     pat_rd();
;     ldfrag(st, 3, 1);
;     mma(0);
;     pat_rd();
;     asm volatile("s_waitcnt vmcnt(0)" ::: "memory");
;     __syncthreads();
;   }
;   mma(1);
	s_waitcnt lgkmcnt(0)
	v_mfma_f32_32x32x16_bf16 v[98:113], v[130:133], v[190:193], v[98:113]
	v_mfma_f32_32x32x16_bf16 v[66:81], v[146:149], v[190:193], v[66:81]
	v_mfma_f32_32x32x16_bf16 v[98:113], v[134:137], v[194:197], v[98:113]
	v_mfma_f32_32x32x16_bf16 v[66:81], v[150:153], v[194:197], v[66:81]
	v_mfma_f32_32x32x16_bf16 v[98:113], v[138:141], v[198:201], v[98:113]
	v_mfma_f32_32x32x16_bf16 v[66:81], v[156:159], v[198:201], v[66:81]
	v_mfma_f32_32x32x16_bf16 v[98:113], v[142:145], v[228:231], v[98:113]
	v_mfma_f32_32x32x16_bf16 v[66:81], v[160:163], v[228:231], v[66:81]
	s_barrier
	ds_read_b128 v[130:133], v240 offset:16384
	ds_read_b128 v[134:137], v241 offset:16384
	ds_read_b128 v[138:141], v242 offset:16384
	ds_read_b128 v[142:145], v243 offset:16384
	ds_read_b128 v[146:149], v240 offset:20480
	ds_read_b128 v[150:153], v241 offset:20480
	ds_read_b128 v[156:159], v242 offset:20480
	ds_read_b128 v[160:163], v243 offset:20480
	s_waitcnt vmcnt(4)
	s_barrier
	s_waitcnt lgkmcnt(0)
	v_mfma_f32_32x32x16_bf16 v[50:65], v[130:133], v[170:173], v[50:65]
	v_mfma_f32_32x32x16_bf16 v[18:33], v[146:149], v[170:173], v[18:33]
	v_mfma_f32_32x32x16_bf16 v[50:65], v[134:137], v[174:177], v[50:65]
	v_mfma_f32_32x32x16_bf16 v[18:33], v[150:153], v[174:177], v[18:33]
	v_mfma_f32_32x32x16_bf16 v[50:65], v[138:141], v[178:181], v[50:65]
	v_mfma_f32_32x32x16_bf16 v[18:33], v[156:159], v[178:181], v[18:33]
	v_mfma_f32_32x32x16_bf16 v[50:65], v[142:145], v[186:189], v[50:65]
	v_mfma_f32_32x32x16_bf16 v[18:33], v[160:163], v[186:189], v[18:33]
	v_mfma_f32_32x32x16_bf16 v[34:49], v[130:133], v[190:193], v[34:49]
	v_mfma_f32_32x32x16_bf16 v[2:17], v[146:149], v[190:193], v[2:17]
	v_mfma_f32_32x32x16_bf16 v[34:49], v[134:137], v[194:197], v[34:49]
	v_mfma_f32_32x32x16_bf16 v[2:17], v[150:153], v[194:197], v[2:17]
	v_mfma_f32_32x32x16_bf16 v[34:49], v[138:141], v[198:201], v[34:49]
	v_mfma_f32_32x32x16_bf16 v[2:17], v[156:159], v[198:201], v[2:17]
	v_mfma_f32_32x32x16_bf16 v[34:49], v[142:145], v[228:231], v[34:49]
	v_mfma_f32_32x32x16_bf16 v[2:17], v[160:163], v[228:231], v[2:17]
	s_barrier
	v_add_u32_e32 v246, s10, v164
	v_add_u32_e32 v247, s10, v165
	v_add_u32_e32 v248, s10, v202
	v_add_u32_e32 v249, s10, v203
	ds_read_b128 v[170:173], v246 offset:32768
	ds_read_b128 v[174:177], v247 offset:32768
	ds_read_b128 v[178:181], v248 offset:32768
	ds_read_b128 v[186:189], v249 offset:32768
	v_add_u32_e32 v246, s10, v240
	v_add_u32_e32 v247, s10, v241
	v_add_u32_e32 v248, s10, v242
	v_add_u32_e32 v249, s10, v243
	ds_read_b128 v[130:133], v246
	ds_read_b128 v[134:137], v247
	ds_read_b128 v[138:141], v248
	ds_read_b128 v[142:145], v249
	ds_read_b128 v[146:149], v246 offset:4096
	ds_read_b128 v[150:153], v247 offset:4096
	ds_read_b128 v[156:159], v248 offset:4096
	ds_read_b128 v[160:163], v249 offset:4096
	s_waitcnt vmcnt(2)
	s_barrier
	s_waitcnt lgkmcnt(0)
	v_mfma_f32_32x32x16_bf16 v[114:129], v[130:133], v[170:173], v[114:129]
	v_mfma_f32_32x32x16_bf16 v[82:97], v[146:149], v[170:173], v[82:97]
	v_mfma_f32_32x32x16_bf16 v[114:129], v[134:137], v[174:177], v[114:129]
	v_mfma_f32_32x32x16_bf16 v[82:97], v[150:153], v[174:177], v[82:97]
	v_mfma_f32_32x32x16_bf16 v[114:129], v[138:141], v[178:181], v[114:129]
	v_mfma_f32_32x32x16_bf16 v[82:97], v[156:159], v[178:181], v[82:97]
	v_mfma_f32_32x32x16_bf16 v[114:129], v[142:145], v[186:189], v[114:129]
	v_mfma_f32_32x32x16_bf16 v[82:97], v[160:163], v[186:189], v[82:97]
	s_barrier
	v_add_u32_e32 v246, s10, v164
	v_add_u32_e32 v247, s10, v165
	v_add_u32_e32 v248, s10, v202
	v_add_u32_e32 v249, s10, v203
	ds_read_b128 v[190:193], v246 offset:49152
	ds_read_b128 v[194:197], v247 offset:49152
	ds_read_b128 v[198:201], v248 offset:49152
	ds_read_b128 v[228:231], v249 offset:49152
	s_waitcnt vmcnt(0)
	s_barrier
	s_waitcnt lgkmcnt(0)
	v_mfma_f32_32x32x16_bf16 v[98:113], v[130:133], v[190:193], v[98:113]
	v_mfma_f32_32x32x16_bf16 v[66:81], v[146:149], v[190:193], v[66:81]
	v_mfma_f32_32x32x16_bf16 v[98:113], v[134:137], v[194:197], v[98:113]
	v_mfma_f32_32x32x16_bf16 v[66:81], v[150:153], v[194:197], v[66:81]
	v_mfma_f32_32x32x16_bf16 v[98:113], v[138:141], v[198:201], v[98:113]
	v_mfma_f32_32x32x16_bf16 v[66:81], v[156:159], v[198:201], v[66:81]
	v_mfma_f32_32x32x16_bf16 v[98:113], v[142:145], v[228:231], v[98:113]
	v_mfma_f32_32x32x16_bf16 v[66:81], v[160:163], v[228:231], v[66:81]
	s_barrier
	v_add_u32_e32 v246, s10, v240
	v_add_u32_e32 v247, s10, v241
	v_add_u32_e32 v248, s10, v242
	v_add_u32_e32 v249, s10, v243
	ds_read_b128 v[130:133], v246 offset:16384
	ds_read_b128 v[134:137], v247 offset:16384
	ds_read_b128 v[138:141], v248 offset:16384
	ds_read_b128 v[142:145], v249 offset:16384
	ds_read_b128 v[146:149], v246 offset:20480
	ds_read_b128 v[150:153], v247 offset:20480
	ds_read_b128 v[156:159], v248 offset:20480
	ds_read_b128 v[160:163], v249 offset:20480
	s_barrier
	s_waitcnt lgkmcnt(0)
	v_mfma_f32_32x32x16_bf16 v[50:65], v[130:133], v[170:173], v[50:65]
	v_mfma_f32_32x32x16_bf16 v[18:33], v[146:149], v[170:173], v[18:33]
	v_mfma_f32_32x32x16_bf16 v[50:65], v[134:137], v[174:177], v[50:65]
	v_mfma_f32_32x32x16_bf16 v[18:33], v[150:153], v[174:177], v[18:33]
	v_mfma_f32_32x32x16_bf16 v[50:65], v[138:141], v[178:181], v[50:65]
	v_mfma_f32_32x32x16_bf16 v[18:33], v[156:159], v[178:181], v[18:33]
	v_mfma_f32_32x32x16_bf16 v[50:65], v[142:145], v[186:189], v[50:65]
	v_mfma_f32_32x32x16_bf16 v[18:33], v[160:163], v[186:189], v[18:33]
	v_mfma_f32_32x32x16_bf16 v[34:49], v[130:133], v[190:193], v[34:49]
	v_mfma_f32_32x32x16_bf16 v[2:17], v[146:149], v[190:193], v[2:17]
	v_mfma_f32_32x32x16_bf16 v[34:49], v[134:137], v[194:197], v[34:49]
	v_mfma_f32_32x32x16_bf16 v[2:17], v[150:153], v[194:197], v[2:17]
	v_mfma_f32_32x32x16_bf16 v[34:49], v[138:141], v[198:201], v[34:49]
	v_mfma_f32_32x32x16_bf16 v[2:17], v[156:159], v[198:201], v[2:17]
	v_mfma_f32_32x32x16_bf16 v[34:49], v[142:145], v[228:231], v[34:49]
	v_mfma_f32_32x32x16_bf16 v[2:17], v[160:163], v[228:231], v[2:17]
	s_barrier
	s_cmp_eq_u32 s101, 0
	s_cbranch_scc0 .Lg8_qa_p1
	s_barrier

; DI int opaque_tid() { int t = threadIdx.x; asm volatile("" : "+v"(t)); return t; }
; template <bool SWAP>
; DI void gemm_mainloop(f32x16 (&acc)[4][2], const u16* __restrict__ A, int lda, int rlo, int rhi,
;                       const u16* __restrict__ B, int ldb, int K, char* lds, const u16* zero_line) {
;   const int tid = opaque_tid(), lane = tid & 63, w = tid >> 6;
;   const int wm = w >> 2, wn = w & 3;
;   const int h = lane >> 5, r = lane & 31;
;   const int lr = tid >> 3, lc = tid & 7;
; #pragma unroll
;   for (int mi = 0; mi < 4; ++mi)
; #pragma unroll
;     for (int ni = 0; ni < 2; ++ni)
; #pragma unroll
;       for (int i = 0; i < 16; ++i) acc[mi][ni][i] = 0.f;
;   const int gch = (lc ^ ((lr >> 1) & 7)) * 8;
;   const u16* ap = A + (ptrdiff_t)lr * lda + gch;
;   const u16* bp = B + (ptrdiff_t)lr * ldb + gch;
;   const int nk = K >> 6;
;   typedef __attribute__((address_space(3))) unsigned lds_u32;
;   auto glds = [&](int kt, int st) {
;     char* as_ = lds + st * 65536 + tid * 16;
; #pragma unroll
;     for (int i = 0; i < 4; ++i) {
;       const int rr = lr + 64 * i;
;       const u16* srca = (rr >= rlo && rr < rhi) ? (ap + (ptrdiff_t)(64 * i) * lda + kt * 64) : (zero_line + lc * 8);
;       __builtin_amdgcn_global_load_lds((const unsigned*)srca, (lds_u32*)(as_ + i * 8192), 16, 0, 0);
;       __builtin_amdgcn_global_load_lds((const unsigned*)(bp + (ptrdiff_t)(64 * i) * ldb + kt * 64), (lds_u32*)(as_ + 32768 + i * 8192), 16, 0, 0);
;     }
;   };
;   const int sw = (r >> 1) & 7;
;   const int arow_off = (wm * 128 + r) * 128;
;   const int brow_off = 32768 + (wn * 64 + r) * 128;
;   __syncthreads();
;   glds(0, 0);
;   asm volatile("s_waitcnt vmcnt(0)" ::: "memory");
;   __syncthreads();
; template <int EPI>
; DI void phase_gemm(const Params& p, const GemmArgs& ga, char* lds) {
;     ...
;     bool swap;
;     if (EPI == EPI_M) swap = true;
;     else if (EPI == EPI_UP) swap = true;
;     else if (EPI == EPI_QKV1) swap = (nt < 8);
;     else swap = !(nt == 4 || nt == 5);
;     if (swap) gemm_mainloop<true>(acc, A, ga.lda, rlo, rhi, B, ga.K, ga.K, lds, (const u16*)(p.ws + OFF_ZERO));
;     else gemm_mainloop<false>(acc, A, ga.lda, rlo, rhi, B, ga.K, ga.K, lds, (const u16*)(p.ws + OFF_ZERO));
.LBB0_203:
	s_and_b64 vcc, exec, s[6:7]
	s_cbranch_vccz .LBB0_209
	s_nop 9
	v_mov_b32_e32 v12, v204
	s_mov_b64 s[10:11], 0x20000
	v_ashrrev_i32_e32 v2, 3, v12
	v_lshrrev_b32_e32 v14, 1, v2
	v_xor_b32_e32 v0, v14, v12
	v_ashrrev_i32_e32 v3, 31, v2
	v_lshlrev_b64 v[4:5], 11, v[2:3]
	v_lshlrev_b32_e32 v0, 4, v0
	v_and_b32_e32 v10, 31, v12
	v_lshl_add_u64 v[6:7], s[20:21], 0, v[4:5]
	v_and_b32_e32 v0, 0x70, v0
	v_lshl_add_u64 v[8:9], s[22:23], 0, v[4:5]
	v_lshrrev_b32_e32 v15, 1, v12
	v_lshl_add_u64 v[6:7], v[6:7], 0, v[0:1]
	v_lshl_add_u64 v[8:9], v[8:9], 0, v[0:1]
	v_and_or_b32 v0, v15, s51, v10
	v_lshlrev_b32_e32 v169, 7, v0
	v_lshlrev_b32_e32 v0, 7, v12
	v_lshlrev_b32_e32 v171, 4, v12
	v_and_b32_e32 v170, 0x6f80, v0
	v_and_b32_e32 v0, 0x70, v171
	v_add_u32_e32 v172, 0x8000, v171
	v_lshl_add_u64 v[156:157], s[80:81], 0, v[0:1]
	v_cmp_gt_u32_e32 vcc, s50, v2
	v_readfirstlane_b32 s6, v171
	s_mov_b32 m0, s6
	v_cndmask_b32_e32 v11, v157, v7, vcc
	v_cndmask_b32_e32 v10, v156, v6, vcc
	v_readfirstlane_b32 s6, v172
	v_add_u32_e32 v0, 64, v2
	v_add_u32_e32 v173, 0x2000, v171
	s_barrier
	s_mov_b32 m0, s6
	v_lshl_add_u64 v[10:11], v[6:7], 0, s[10:11]
	v_cmp_gt_u32_e64 s[6:7], s50, v0
	v_readfirstlane_b32 s8, v173
	v_add_u32_e32 v174, 0xa000, v171
	v_cndmask_b32_e64 v11, v157, v11, s[6:7]
	v_cndmask_b32_e64 v10, v156, v10, s[6:7]
	s_mov_b32 m0, s8
	v_readfirstlane_b32 s8, v174
	v_lshl_add_u64 v[10:11], v[8:9], 0, s[10:11]
	s_mov_b32 m0, s8
	v_add_u32_e32 v0, 0x80, v2
	s_mov_b64 s[20:21], 0x40000
	v_add_u32_e32 v175, 0x4000, v171
	v_lshl_add_u64 v[10:11], v[6:7], 0, s[20:21]
	v_cmp_gt_u32_e64 s[8:9], s50, v0
	v_readfirstlane_b32 s10, v175
	v_add_u32_e32 v176, 0xc000, v171
	v_cndmask_b32_e64 v11, v157, v11, s[8:9]
	v_cndmask_b32_e64 v10, v156, v10, s[8:9]
	s_mov_b32 m0, s10
	v_readfirstlane_b32 s10, v176
	v_add_u32_e32 v0, 0xc0, v2
	s_mov_b64 s[22:23], 0x60000
	v_add_u32_e32 v177, 0x6000, v171
	v_lshl_add_u64 v[10:11], v[8:9], 0, s[20:21]
	s_mov_b32 m0, s10
	v_lshl_add_u64 v[2:3], v[6:7], 0, s[22:23]
	v_cmp_gt_u32_e64 s[10:11], s50, v0
	v_readfirstlane_b32 s20, v177
	v_add_u32_e32 v178, 0xe000, v171
	v_cndmask_b32_e64 v3, v157, v3, s[10:11]
	v_cndmask_b32_e64 v2, v156, v2, s[10:11]
	s_mov_b32 m0, s20
	v_readfirstlane_b32 s20, v178
	v_lshl_add_u64 v[2:3], v[8:9], 0, s[22:23]
	s_mov_b32 m0, s20
	v_bfe_u32 v13, v12, 5, 1
	v_bfe_u32 v16, v12, 1, 3
	v_bitop3_b32 v0, v15, v13, 7 bitop3:0x6c
	s_sub_i32 s20, s28, s31
	v_lshlrev_b32_e32 v179, 4, v0
	v_bitop3_b32 v0, v13, v16, 2 bitop3:0x36
	s_sub_i32 s13, s20, s13
	v_lshlrev_b32_e32 v180, 4, v0
	v_bitop3_b32 v0, v13, v16, 4 bitop3:0x36
	s_lshl_b32 s20, s13, 8
	v_lshlrev_b32_e32 v181, 4, v0
	v_bitop3_b32 v0, v13, v16, 6 bitop3:0x36
	s_ashr_i32 s21, s20, 31
	v_lshlrev_b32_e32 v182, 4, v0
	s_lshl_b64 s[20:21], s[20:21], 11
	v_bitop3_b32 v0, v14, 7, v12 bitop3:0x48
	v_lshl_add_u64 v[2:3], v[4:5], 0, s[20:21]
	v_lshlrev_b32_e32 v0, 4, v0
	v_or_b32_e32 v2, v2, v0
	v_lshl_add_u64 v[158:159], s[70:71], 0, v[2:3]
	v_lshl_add_u64 v[2:3], v[4:5], 0, s[18:19]
	s_waitcnt vmcnt(0)
	v_lshl_add_u64 v[2:3], v[2:3], 0, v[0:1]
	v_lshl_add_u64 v[160:161], s[70:71], 0, v[2:3]
	v_mov_b32_e32 v130, 0
	v_mov_b32_e32 v2, 0
	s_mov_b32 s15, 1
	v_add_u32_e32 v183, 0x10000, v171
	v_add_u32_e32 v185, 0x18000, v171
	v_add_u32_e32 v186, 0x12000, v171
	v_add_u32_e32 v187, 0x1a000, v171
	v_add_u32_e32 v188, 0x14000, v171
	v_add_u32_e32 v189, 0x1c000, v171
	v_add_u32_e32 v190, 0x16000, v171
	v_add_u32_e32 v191, 0x1e000, v171
	v_add_u32_e32 v192, 0x10000, v169
	v_or_b32_e32 v193, 0x10000, v170
	s_mov_b64 s[18:19], 0
	v_mov_b32_e32 v3, v2
	v_mov_b32_e32 v4, v2
	v_mov_b32_e32 v5, v2
	v_mov_b32_e32 v6, v2
	v_mov_b32_e32 v7, v2
	v_mov_b32_e32 v8, v2
	v_mov_b32_e32 v9, v2
	v_mov_b32_e32 v10, v2
	v_mov_b32_e32 v11, v2
	v_mov_b32_e32 v12, v2
	v_mov_b32_e32 v13, v2
	v_mov_b32_e32 v14, v2
	v_mov_b32_e32 v15, v2
	v_mov_b32_e32 v16, v2
	v_mov_b32_e32 v17, v2
	v_mov_b32_e32 v18, v2
	v_mov_b32_e32 v19, v2
	v_mov_b32_e32 v20, v2
	v_mov_b32_e32 v21, v2
	v_mov_b32_e32 v22, v2
	v_mov_b32_e32 v23, v2
	v_mov_b32_e32 v24, v2
	v_mov_b32_e32 v25, v2
	v_mov_b32_e32 v26, v2
	v_mov_b32_e32 v27, v2
	v_mov_b32_e32 v28, v2
	v_mov_b32_e32 v29, v2
	v_mov_b32_e32 v30, v2
	v_mov_b32_e32 v31, v2
	v_mov_b32_e32 v32, v2
	v_mov_b32_e32 v33, v2
	v_mov_b32_e32 v34, v2
	v_mov_b32_e32 v35, v2
	v_mov_b32_e32 v36, v2
	v_mov_b32_e32 v37, v2
	v_mov_b32_e32 v38, v2
	v_mov_b32_e32 v39, v2
	v_mov_b32_e32 v40, v2
	v_mov_b32_e32 v41, v2
	v_mov_b32_e32 v42, v2
	v_mov_b32_e32 v43, v2
	v_mov_b32_e32 v44, v2
	v_mov_b32_e32 v45, v2
	v_mov_b32_e32 v46, v2
	v_mov_b32_e32 v47, v2
	v_mov_b32_e32 v48, v2
	v_mov_b32_e32 v49, v2
	v_mov_b32_e32 v50, v2
	v_mov_b32_e32 v51, v2
	v_mov_b32_e32 v52, v2
	v_mov_b32_e32 v53, v2
	v_mov_b32_e32 v54, v2
	v_mov_b32_e32 v55, v2
	v_mov_b32_e32 v56, v2
	v_mov_b32_e32 v57, v2
	v_mov_b32_e32 v58, v2
	v_mov_b32_e32 v59, v2
	v_mov_b32_e32 v60, v2
	v_mov_b32_e32 v61, v2
	v_mov_b32_e32 v62, v2
	v_mov_b32_e32 v63, v2
	v_mov_b32_e32 v64, v2
	v_mov_b32_e32 v65, v2
	v_mov_b32_e32 v66, v2
	v_mov_b32_e32 v67, v2
	v_mov_b32_e32 v68, v2
; template <bool SWAP>
; DI void gemm_mainloop(f32x16 (&acc)[4][2], const u16* __restrict__ A, int lda, int rlo, int rhi,
;                       const u16* __restrict__ B, int ldb, int K, char* lds, const u16* zero_line) {
;     ...
; #pragma unroll
;   for (int mi = 0; mi < 4; ++mi)
; #pragma unroll
;     for (int ni = 0; ni < 2; ++ni)
; #pragma unroll
;       for (int i = 0; i < 16; ++i) acc[mi][ni][i] = 0.f;
;   const int gch = (lc ^ ((lr >> 1) & 7)) * 8;
;   const u16* ap = A + (ptrdiff_t)lr * lda + gch;
;   const u16* bp = B + (ptrdiff_t)lr * ldb + gch;
;   const int nk = K >> 6;
;   typedef __attribute__((address_space(3))) unsigned lds_u32;
;   auto glds = [&](int kt, int st) {
;     char* as_ = lds + st * 65536 + tid * 16;
; #pragma unroll
;     for (int i = 0; i < 4; ++i) {
;       const int rr = lr + 64 * i;
;       const u16* srca = (rr >= rlo && rr < rhi) ? (ap + (ptrdiff_t)(64 * i) * lda + kt * 64) : (zero_line + lc * 8);
;       __builtin_amdgcn_global_load_lds((const unsigned*)srca, (lds_u32*)(as_ + i * 8192), 16, 0, 0);
;       __builtin_amdgcn_global_load_lds((const unsigned*)(bp + (ptrdiff_t)(64 * i) * ldb + kt * 64), (lds_u32*)(as_ + 32768 + i * 8192), 16, 0, 0);
;     }
;   };
;   const int sw = (r >> 1) & 7;
;   const int arow_off = (wm * 128 + r) * 128;
;   const int brow_off = 32768 + (wn * 64 + r) * 128;
;   __syncthreads();
;   glds(0, 0);
;   asm volatile("s_waitcnt vmcnt(0)" ::: "memory");
;   __syncthreads();
	v_mov_b32_e32 v69, v2
	v_mov_b32_e32 v70, v2
	v_mov_b32_e32 v71, v2
	v_mov_b32_e32 v72, v2
	v_mov_b32_e32 v73, v2
	v_mov_b32_e32 v74, v2
	v_mov_b32_e32 v75, v2
	v_mov_b32_e32 v76, v2
	v_mov_b32_e32 v77, v2
	v_mov_b32_e32 v78, v2
	v_mov_b32_e32 v79, v2
	v_mov_b32_e32 v80, v2
	v_mov_b32_e32 v81, v2
	v_mov_b32_e32 v82, v2
	v_mov_b32_e32 v83, v2
	v_mov_b32_e32 v84, v2
	v_mov_b32_e32 v85, v2
	v_mov_b32_e32 v86, v2
	v_mov_b32_e32 v87, v2
	v_mov_b32_e32 v88, v2
	v_mov_b32_e32 v89, v2
	v_mov_b32_e32 v90, v2
	v_mov_b32_e32 v91, v2
	v_mov_b32_e32 v92, v2
	v_mov_b32_e32 v93, v2
	v_mov_b32_e32 v94, v2
	v_mov_b32_e32 v95, v2
	v_mov_b32_e32 v96, v2
	v_mov_b32_e32 v97, v2
	v_mov_b32_e32 v98, v2
	v_mov_b32_e32 v99, v2
	v_mov_b32_e32 v100, v2
	v_mov_b32_e32 v101, v2
	v_mov_b32_e32 v102, v2
	v_mov_b32_e32 v103, v2
	v_mov_b32_e32 v104, v2
	v_mov_b32_e32 v105, v2
	v_mov_b32_e32 v106, v2
	v_mov_b32_e32 v107, v2
	v_mov_b32_e32 v108, v2
	v_mov_b32_e32 v109, v2
	v_mov_b32_e32 v110, v2
	v_mov_b32_e32 v111, v2
	v_mov_b32_e32 v112, v2
	v_mov_b32_e32 v113, v2
	v_mov_b32_e32 v114, v2
	v_mov_b32_e32 v115, v2
	v_mov_b32_e32 v116, v2
	v_mov_b32_e32 v117, v2
	v_mov_b32_e32 v118, v2
	v_mov_b32_e32 v119, v2
	v_mov_b32_e32 v120, v2
	v_mov_b32_e32 v121, v2
	v_mov_b32_e32 v122, v2
	v_mov_b32_e32 v123, v2
	v_mov_b32_e32 v124, v2
	v_mov_b32_e32 v125, v2
	v_mov_b32_e32 v126, v2
	v_mov_b32_e32 v127, v2
	v_mov_b32_e32 v128, v2
	v_mov_b32_e32 v129, v2
	v_mov_b32_e32 v131, v130
	v_mov_b32_e32 v132, v130
	v_mov_b32_e32 v133, v130
	v_mov_b32_e32 v134, v130
	v_mov_b32_e32 v135, v130
	v_mov_b32_e32 v136, v130
	v_mov_b32_e32 v137, v130
	v_mov_b32_e32 v138, v130
	v_mov_b32_e32 v139, v130
	v_mov_b32_e32 v140, v130
	v_mov_b32_e32 v141, v130
	v_mov_b32_e32 v146, v130
	v_mov_b32_e32 v147, v130
	v_mov_b32_e32 v148, v130
	v_mov_b32_e32 v149, v130
	v_mov_b32_e32 v142, v130
	v_mov_b32_e32 v143, v130
	v_mov_b32_e32 v144, v130
	v_mov_b32_e32 v145, v130
	v_mov_b32_e32 v150, v130
	v_mov_b32_e32 v151, v130
	v_mov_b32_e32 v152, v130
	v_mov_b32_e32 v153, v130
	s_waitcnt vmcnt(0) lgkmcnt(0)
	s_barrier
	s_ashr_i32 s7, s12, 31
	s_mov_b32 s6, s12
	s_lshl_b64 s[6:7], s[6:7], 11
	s_add_u32 s6, s90, s6
	s_addc_u32 s7, s91, s7
	s_ashr_i32 s9, s14, 31
	s_mov_b32 s8, s14
	s_lshl_b64 s[8:9], s[8:9], 11
	v_readlane_b32 s10, v253, 43
	v_readlane_b32 s11, v253, 44
	s_add_u32 s8, s10, s8
	s_addc_u32 s9, s11, s9
	v_and_b32_e32 v130, 63, v204
	v_lshrrev_b32_e32 v131, 6, v204
	v_lshrrev_b32_e32 v132, 3, v204
	v_lshrrev_b32_e32 v0, 4, v130
	v_lshl_add_u32 v0, v131, 2, v0
	v_xor_b32_e32 v0, v0, v130
	v_and_b32_e32 v0, 7, v0
	v_lshlrev_b32_e32 v133, 4, v0
	v_lshl_add_u32 v232, v132, 11, v133
	v_add_u32_e32 v233, 0x20000, v232
	v_add_u32_e32 v234, 0x40000, v232
	v_add_u32_e32 v235, 0x60000, v232
	v_and_b32_e32 v0, 31, v132
	v_lshrrev_b32_e32 v130, 5, v132
	v_lshl_add_u32 v0, v130, 6, v0
	v_lshl_add_u32 v236, v0, 11, v133
	v_add_u32_e32 v237, 0x10000, v236
	v_add_u32_e32 v238, 0x40000, v236
	v_add_u32_e32 v239, 0x50000, v236
	v_and_b32_e32 v132, 31, v204
	v_lshrrev_b32_e32 v0, 2, v131
	v_lshl_add_u32 v0, v0, 6, v132
	v_lshlrev_b32_e32 v244, 7, v0
	v_and_b32_e32 v0, 3, v131
	v_lshl_add_u32 v0, v0, 5, v132
	v_lshlrev_b32_e32 v245, 7, v0
	v_bfe_u32 v0, v204, 5, 1
	v_bfe_u32 v130, v132, 1, 3
	v_or_b32_e32 v133, 0, v0
	v_xor_b32_e32 v133, v133, v130
	v_lshlrev_b32_e32 v240, 4, v133
	v_or_b32_e32 v133, 2, v0
	v_xor_b32_e32 v133, v133, v130
	v_lshlrev_b32_e32 v241, 4, v133
	v_or_b32_e32 v133, 4, v0
	v_xor_b32_e32 v133, v133, v130
	v_lshlrev_b32_e32 v242, 4, v133
	v_or_b32_e32 v133, 6, v0
	v_xor_b32_e32 v133, v133, v130
	v_lshlrev_b32_e32 v243, 4, v133
	v_add_u32_e32 v164, v245, v240
	v_add_u32_e32 v165, v245, v241
	v_add_u32_e32 v202, v245, v242
	v_add_u32_e32 v203, v245, v243
	v_add_u32_e32 v240, v244, v240
	v_add_u32_e32 v241, v244, v241
	v_add_u32_e32 v242, v244, v242
	v_add_u32_e32 v243, v244, v243
	v_lshlrev_b32_e32 v131, 10, v131
	s_nop 0
	v_readfirstlane_b32 s100, v131
	v_mov_b32_e32 v146, 0
	v_mov_b32_e32 v147, 0
	v_mov_b32_e32 v148, 0
	v_mov_b32_e32 v149, 0
	v_lshlrev_b32_e32 v130, 4, v204
	v_add_u32_e32 v132, 0x10000, v130
	s_mov_b64 exec, -1
	s_mov_b32 s11, 0
	s_mov_b32 s10, 0x10000
	s_waitcnt lgkmcnt(0)
	s_add_u32 m0, s100, 0x8000
	s_nop 0
	global_load_lds_dwordx4 v236, s[8:9]
	s_add_u32 m0, s100, 0xa000
	v_add_u32_e32 v236, 0x80, v236
	global_load_lds_dwordx4 v238, s[8:9]
	v_add_u32_e32 v238, 0x80, v238
	s_add_u32 m0, s100, 0x0
	s_nop 0
	global_load_lds_dwordx4 v232, s[6:7]
	s_add_u32 m0, s100, 0x2000
	v_add_u32_e32 v232, 0x80, v232
	global_load_lds_dwordx4 v234, s[6:7]
	v_add_u32_e32 v234, 0x80, v234
	s_add_u32 m0, s100, 0xc000
	s_nop 0
	global_load_lds_dwordx4 v237, s[8:9]
	s_add_u32 m0, s100, 0xe000
	v_add_u32_e32 v237, 0x80, v237
	global_load_lds_dwordx4 v239, s[8:9]
	v_add_u32_e32 v239, 0x80, v239
	s_add_u32 m0, s100, 0x4000
	s_nop 0
	global_load_lds_dwordx4 v233, s[6:7]
	s_add_u32 m0, s100, 0x6000
	v_add_u32_e32 v233, 0x80, v233
	global_load_lds_dwordx4 v235, s[6:7]
	v_add_u32_e32 v235, 0x80, v235
	s_cmp_eq_u32 s101, 1
	s_cbranch_scc0 .Lg8_qb_p0
	s_barrier

; #define MFMA(a, b, c) __builtin_amdgcn_mfma_f32_32x32x16_bf16((a), (b), (c), 0, 0, 0)
; template <bool SWAP>
; DI void gemm_mainloop(f32x16 (&acc)[4][2], const u16* __restrict__ A, int lda, int rlo, int rhi,
;                       const u16* __restrict__ B, int ldb, int K, char* lds, const u16* zero_line) {
;     ...
;   auto ldfrag = [&](const char* st, int ks, int buf) {
;     const int co = ((2 * ks + h) ^ sw) << 4;
; #pragma unroll
;     for (int mi = 0; mi < 4; ++mi) fa[buf][mi] = *(const bf16x8*)(st + arow_off + mi * 4096 + co);
; #pragma unroll
;     for (int ni = 0; ni < 2; ++ni) fb[buf][ni] = *(const bf16x8*)(st + brow_off + ni * 4096 + co);
;   };
;   auto mma = [&](int buf) {
; #pragma unroll
;     for (int mi = 0; mi < 4; ++mi)
; #pragma unroll
;       for (int ni = 0; ni < 2; ++ni)
;         acc[mi][ni] = SWAP ? MFMA(fb[buf][ni], fa[buf][mi], acc[mi][ni]) : MFMA(fa[buf][mi], fb[buf][ni], acc[mi][ni]);
;   };
;   auto pat_rd = [&]() {
; #pragma unroll
;     for (int g = 0; g < 6; ++g) {
;       __builtin_amdgcn_sched_group_barrier(0x100, 1, 0);
;       __builtin_amdgcn_sched_group_barrier(0x008, 1, 0);
;     }
;     __builtin_amdgcn_sched_group_barrier(0x008, 2, 0);
;   };
; #pragma unroll 2
;   for (int kt = 0; kt < nk; ++kt) {
;     const char* st = lds + (kt & 1) * 65536;
;     ldfrag(st, 0, 0);
;     mma(1);
;     pat_rd();
;     if (kt + 1 < nk) glds(kt + 1, (kt + 1) & 1);
;     ldfrag(st, 1, 1);
;     mma(0);
;     pat_rd();
;     ldfrag(st, 2, 0);
;     mma(1);
;     pat_rd();
;     ldfrag(st, 3, 1);
;     mma(0);
;     pat_rd();
;     asm volatile("s_waitcnt vmcnt(0)" ::: "memory");
;     __syncthreads();
;   }
.Lg8_qb:
	s_add_u32 m0, s100, 0x14000
	ds_read_b128 v[130:133], v240
	ds_read_b128 v[134:137], v241
	ds_read_b128 v[138:141], v242
	ds_read_b128 v[142:145], v243
	ds_read_b128 v[146:149], v240 offset:4096
	ds_read_b128 v[150:153], v241 offset:4096
	ds_read_b128 v[156:159], v242 offset:4096
	ds_read_b128 v[160:163], v243 offset:4096
	global_load_lds_dwordx4 v233, s[6:7]
	s_add_u32 m0, s100, 0x16000
	v_add_u32_e32 v233, 0x80, v233
	global_load_lds_dwordx4 v235, s[6:7]
	v_add_u32_e32 v235, 0x80, v235
	s_barrier
	s_waitcnt lgkmcnt(0)
	v_mfma_f32_32x32x16_bf16 v[114:129], v[170:173], v[130:133], v[114:129]
	v_mfma_f32_32x32x16_bf16 v[82:97], v[170:173], v[146:149], v[82:97]
	v_mfma_f32_32x32x16_bf16 v[114:129], v[174:177], v[134:137], v[114:129]
	v_mfma_f32_32x32x16_bf16 v[82:97], v[174:177], v[150:153], v[82:97]
	v_mfma_f32_32x32x16_bf16 v[114:129], v[178:181], v[138:141], v[114:129]
	v_mfma_f32_32x32x16_bf16 v[82:97], v[178:181], v[156:159], v[82:97]
	v_mfma_f32_32x32x16_bf16 v[114:129], v[186:189], v[142:145], v[114:129]
	v_mfma_f32_32x32x16_bf16 v[82:97], v[186:189], v[160:163], v[82:97]
	s_barrier
	s_add_u32 m0, s100, 0x8000
	ds_read_b128 v[190:193], v164 offset:49152
	ds_read_b128 v[194:197], v165 offset:49152
	ds_read_b128 v[198:201], v202 offset:49152
	ds_read_b128 v[228:231], v203 offset:49152
	global_load_lds_dwordx4 v236, s[8:9]
	s_add_u32 m0, s100, 0xa000
	v_add_u32_e32 v236, 0x80, v236
	global_load_lds_dwordx4 v238, s[8:9]
	v_add_u32_e32 v238, 0x80, v238
	s_barrier
	s_waitcnt lgkmcnt(0)
	v_mfma_f32_32x32x16_bf16 v[98:113], v[190:193], v[130:133], v[98:113]
	v_mfma_f32_32x32x16_bf16 v[66:81], v[190:193], v[146:149], v[66:81]
	v_mfma_f32_32x32x16_bf16 v[98:113], v[194:197], v[134:137], v[98:113]
	v_mfma_f32_32x32x16_bf16 v[66:81], v[194:197], v[150:153], v[66:81]
	v_mfma_f32_32x32x16_bf16 v[98:113], v[198:201], v[138:141], v[98:113]
	v_mfma_f32_32x32x16_bf16 v[66:81], v[198:201], v[156:159], v[66:81]
	v_mfma_f32_32x32x16_bf16 v[98:113], v[228:231], v[142:145], v[98:113]
	v_mfma_f32_32x32x16_bf16 v[66:81], v[228:231], v[160:163], v[66:81]
	s_barrier
	s_add_u32 m0, s100, 0x0
	ds_read_b128 v[130:133], v240 offset:16384
	ds_read_b128 v[134:137], v241 offset:16384
	ds_read_b128 v[138:141], v242 offset:16384
	ds_read_b128 v[142:145], v243 offset:16384
	ds_read_b128 v[146:149], v240 offset:20480
	ds_read_b128 v[150:153], v241 offset:20480
	ds_read_b128 v[156:159], v242 offset:20480
	ds_read_b128 v[160:163], v243 offset:20480
	global_load_lds_dwordx4 v232, s[6:7]
	s_add_u32 m0, s100, 0x2000
	v_add_u32_e32 v232, 0x80, v232
	global_load_lds_dwordx4 v234, s[6:7]
	v_add_u32_e32 v234, 0x80, v234
	s_waitcnt vmcnt(10)
	s_barrier
	s_waitcnt lgkmcnt(0)
	v_mfma_f32_32x32x16_bf16 v[50:65], v[170:173], v[130:133], v[50:65]
	v_mfma_f32_32x32x16_bf16 v[18:33], v[170:173], v[146:149], v[18:33]
	v_mfma_f32_32x32x16_bf16 v[50:65], v[174:177], v[134:137], v[50:65]
	v_mfma_f32_32x32x16_bf16 v[18:33], v[174:177], v[150:153], v[18:33]
	v_mfma_f32_32x32x16_bf16 v[50:65], v[178:181], v[138:141], v[50:65]
	v_mfma_f32_32x32x16_bf16 v[18:33], v[178:181], v[156:159], v[18:33]
	v_mfma_f32_32x32x16_bf16 v[50:65], v[186:189], v[142:145], v[50:65]
	v_mfma_f32_32x32x16_bf16 v[18:33], v[186:189], v[160:163], v[18:33]
	s_barrier
	s_add_u32 m0, s100, 0xc000
	v_add_u32_e32 v246, s10, v164
	v_add_u32_e32 v247, s10, v165
	v_add_u32_e32 v248, s10, v202
	v_add_u32_e32 v249, s10, v203
	ds_read_b128 v[170:173], v246 offset:32768
	ds_read_b128 v[174:177], v247 offset:32768
	ds_read_b128 v[178:181], v248 offset:32768
	ds_read_b128 v[186:189], v249 offset:32768
	global_load_lds_dwordx4 v237, s[8:9]
	s_add_u32 m0, s100, 0xe000
	v_add_u32_e32 v237, 0x80, v237
	global_load_lds_dwordx4 v239, s[8:9]
	v_add_u32_e32 v239, 0x80, v239
	s_waitcnt vmcnt(6)
	s_barrier
	s_waitcnt lgkmcnt(0)
	v_mfma_f32_32x32x16_bf16 v[34:49], v[190:193], v[130:133], v[34:49]
	v_mfma_f32_32x32x16_bf16 v[2:17], v[190:193], v[146:149], v[2:17]
	v_mfma_f32_32x32x16_bf16 v[34:49], v[194:197], v[134:137], v[34:49]
	v_mfma_f32_32x32x16_bf16 v[2:17], v[194:197], v[150:153], v[2:17]
	v_mfma_f32_32x32x16_bf16 v[34:49], v[198:201], v[138:141], v[34:49]
	v_mfma_f32_32x32x16_bf16 v[2:17], v[198:201], v[156:159], v[2:17]
	v_mfma_f32_32x32x16_bf16 v[34:49], v[228:231], v[142:145], v[34:49]
	v_mfma_f32_32x32x16_bf16 v[2:17], v[228:231], v[160:163], v[2:17]
	s_barrier
	s_add_u32 m0, s100, 0x4000
	v_add_u32_e32 v246, s10, v240
	v_add_u32_e32 v247, s10, v241
	v_add_u32_e32 v248, s10, v242
	v_add_u32_e32 v249, s10, v243
	ds_read_b128 v[130:133], v246
	ds_read_b128 v[134:137], v247
	ds_read_b128 v[138:141], v248
	ds_read_b128 v[142:145], v249
	ds_read_b128 v[146:149], v246 offset:4096
	ds_read_b128 v[150:153], v247 offset:4096
	ds_read_b128 v[156:159], v248 offset:4096
	ds_read_b128 v[160:163], v249 offset:4096
	global_load_lds_dwordx4 v233, s[6:7]
	s_add_u32 m0, s100, 0x6000
	v_add_u32_e32 v233, 0x80, v233
	global_load_lds_dwordx4 v235, s[6:7]
	v_add_u32_e32 v235, 0x80, v235
	s_barrier
	s_waitcnt lgkmcnt(0)
	v_mfma_f32_32x32x16_bf16 v[114:129], v[170:173], v[130:133], v[114:129]
	v_mfma_f32_32x32x16_bf16 v[82:97], v[170:173], v[146:149], v[82:97]
	v_mfma_f32_32x32x16_bf16 v[114:129], v[174:177], v[134:137], v[114:129]
	v_mfma_f32_32x32x16_bf16 v[82:97], v[174:177], v[150:153], v[82:97]
	v_mfma_f32_32x32x16_bf16 v[114:129], v[178:181], v[138:141], v[114:129]
	v_mfma_f32_32x32x16_bf16 v[82:97], v[178:181], v[156:159], v[82:97]
	v_mfma_f32_32x32x16_bf16 v[114:129], v[186:189], v[142:145], v[114:129]
	v_mfma_f32_32x32x16_bf16 v[82:97], v[186:189], v[160:163], v[82:97]
	s_barrier
; #define MFMA(a, b, c) __builtin_amdgcn_mfma_f32_32x32x16_bf16((a), (b), (c), 0, 0, 0)
; template <bool SWAP>
; DI void gemm_mainloop(f32x16 (&acc)[4][2], const u16* __restrict__ A, int lda, int rlo, int rhi,
;                       const u16* __restrict__ B, int ldb, int K, char* lds, const u16* zero_line) {
;     ...
;   auto ldfrag = [&](const char* st, int ks, int buf) {
;     const int co = ((2 * ks + h) ^ sw) << 4;
; #pragma unroll
;     for (int mi = 0; mi < 4; ++mi) fa[buf][mi] = *(const bf16x8*)(st + arow_off + mi * 4096 + co);
; #pragma unroll
;     for (int ni = 0; ni < 2; ++ni) fb[buf][ni] = *(const bf16x8*)(st + brow_off + ni * 4096 + co);
;   };
;   auto mma = [&](int buf) {
; #pragma unroll
;     for (int mi = 0; mi < 4; ++mi)
; #pragma unroll
;       for (int ni = 0; ni < 2; ++ni)
;         acc[mi][ni] = SWAP ? MFMA(fb[buf][ni], fa[buf][mi], acc[mi][ni]) : MFMA(fa[buf][mi], fb[buf][ni], acc[mi][ni]);
;   };
;   auto pat_rd = [&]() {
; #pragma unroll
;     for (int g = 0; g < 6; ++g) {
;       __builtin_amdgcn_sched_group_barrier(0x100, 1, 0);
;       __builtin_amdgcn_sched_group_barrier(0x008, 1, 0);
;     }
;     __builtin_amdgcn_sched_group_barrier(0x008, 2, 0);
;   };
; #pragma unroll 2
;   for (int kt = 0; kt < nk; ++kt) {
;     const char* st = lds + (kt & 1) * 65536;
;     ldfrag(st, 0, 0);
;     mma(1);
;     pat_rd();
;     if (kt + 1 < nk) glds(kt + 1, (kt + 1) & 1);
;     ldfrag(st, 1, 1);
;     mma(0);
;     pat_rd();
;     ldfrag(st, 2, 0);
;     mma(1);
;     pat_rd();
;     ldfrag(st, 3, 1);
;     mma(0);
;     pat_rd();
;     asm volatile("s_waitcnt vmcnt(0)" ::: "memory");
;     __syncthreads();
;   }
;   mma(1);
	s_add_u32 m0, s100, 0x18000
	v_add_u32_e32 v246, s10, v164
	v_add_u32_e32 v247, s10, v165
	v_add_u32_e32 v248, s10, v202
	v_add_u32_e32 v249, s10, v203
	ds_read_b128 v[190:193], v246 offset:49152
	ds_read_b128 v[194:197], v247 offset:49152
	ds_read_b128 v[198:201], v248 offset:49152
	ds_read_b128 v[228:231], v249 offset:49152
	global_load_lds_dwordx4 v236, s[8:9]
	s_add_u32 m0, s100, 0x1a000
	v_add_u32_e32 v236, 0x80, v236
	global_load_lds_dwordx4 v238, s[8:9]
	v_add_u32_e32 v238, 0x80, v238
	s_barrier
	s_waitcnt lgkmcnt(0)
	v_mfma_f32_32x32x16_bf16 v[98:113], v[190:193], v[130:133], v[98:113]
	v_mfma_f32_32x32x16_bf16 v[66:81], v[190:193], v[146:149], v[66:81]
	v_mfma_f32_32x32x16_bf16 v[98:113], v[194:197], v[134:137], v[98:113]
	v_mfma_f32_32x32x16_bf16 v[66:81], v[194:197], v[150:153], v[66:81]
	v_mfma_f32_32x32x16_bf16 v[98:113], v[198:201], v[138:141], v[98:113]
	v_mfma_f32_32x32x16_bf16 v[66:81], v[198:201], v[156:159], v[66:81]
	v_mfma_f32_32x32x16_bf16 v[98:113], v[228:231], v[142:145], v[98:113]
	v_mfma_f32_32x32x16_bf16 v[66:81], v[228:231], v[160:163], v[66:81]
	s_barrier
	s_add_u32 m0, s100, 0x10000
	v_add_u32_e32 v246, s10, v240
	v_add_u32_e32 v247, s10, v241
	v_add_u32_e32 v248, s10, v242
	v_add_u32_e32 v249, s10, v243
	ds_read_b128 v[130:133], v246 offset:16384
	ds_read_b128 v[134:137], v247 offset:16384
	ds_read_b128 v[138:141], v248 offset:16384
	ds_read_b128 v[142:145], v249 offset:16384
	ds_read_b128 v[146:149], v246 offset:20480
	ds_read_b128 v[150:153], v247 offset:20480
	ds_read_b128 v[156:159], v248 offset:20480
	ds_read_b128 v[160:163], v249 offset:20480
	global_load_lds_dwordx4 v232, s[6:7]
	s_add_u32 m0, s100, 0x12000
	v_add_u32_e32 v232, 0x80, v232
	global_load_lds_dwordx4 v234, s[6:7]
	v_add_u32_e32 v234, 0x80, v234
	s_waitcnt vmcnt(10)
	s_barrier
	s_waitcnt lgkmcnt(0)
	v_mfma_f32_32x32x16_bf16 v[50:65], v[170:173], v[130:133], v[50:65]
	v_mfma_f32_32x32x16_bf16 v[18:33], v[170:173], v[146:149], v[18:33]
	v_mfma_f32_32x32x16_bf16 v[50:65], v[174:177], v[134:137], v[50:65]
	v_mfma_f32_32x32x16_bf16 v[18:33], v[174:177], v[150:153], v[18:33]
	v_mfma_f32_32x32x16_bf16 v[50:65], v[178:181], v[138:141], v[50:65]
	v_mfma_f32_32x32x16_bf16 v[18:33], v[178:181], v[156:159], v[18:33]
	v_mfma_f32_32x32x16_bf16 v[50:65], v[186:189], v[142:145], v[50:65]
	v_mfma_f32_32x32x16_bf16 v[18:33], v[186:189], v[160:163], v[18:33]
	s_barrier
	s_add_u32 m0, s100, 0x1c000
	ds_read_b128 v[170:173], v164 offset:32768
	ds_read_b128 v[174:177], v165 offset:32768
	ds_read_b128 v[178:181], v202 offset:32768
	ds_read_b128 v[186:189], v203 offset:32768
	global_load_lds_dwordx4 v237, s[8:9]
	s_add_u32 m0, s100, 0x1e000
	v_add_u32_e32 v237, 0x80, v237
	global_load_lds_dwordx4 v239, s[8:9]
	v_add_u32_e32 v239, 0x80, v239
	s_waitcnt vmcnt(6)
	s_barrier
	s_waitcnt lgkmcnt(0)
	v_mfma_f32_32x32x16_bf16 v[34:49], v[190:193], v[130:133], v[34:49]
	v_mfma_f32_32x32x16_bf16 v[2:17], v[190:193], v[146:149], v[2:17]
	v_mfma_f32_32x32x16_bf16 v[34:49], v[194:197], v[134:137], v[34:49]
	v_mfma_f32_32x32x16_bf16 v[2:17], v[194:197], v[150:153], v[2:17]
	v_mfma_f32_32x32x16_bf16 v[34:49], v[198:201], v[138:141], v[34:49]
	v_mfma_f32_32x32x16_bf16 v[2:17], v[198:201], v[156:159], v[2:17]
	v_mfma_f32_32x32x16_bf16 v[34:49], v[228:231], v[142:145], v[34:49]
	v_mfma_f32_32x32x16_bf16 v[2:17], v[228:231], v[160:163], v[2:17]
	s_add_i32 s11, s11, 2
	s_cmp_lt_u32 s11, 14
	s_barrier
	s_cbranch_scc1 .Lg8_qb
	ds_read_b128 v[130:133], v240
	ds_read_b128 v[134:137], v241
	ds_read_b128 v[138:141], v242
	ds_read_b128 v[142:145], v243
	ds_read_b128 v[146:149], v240 offset:4096
	ds_read_b128 v[150:153], v241 offset:4096
	ds_read_b128 v[156:159], v242 offset:4096
	ds_read_b128 v[160:163], v243 offset:4096
	s_add_u32 m0, s100, 0x14000
	s_nop 0
	global_load_lds_dwordx4 v233, s[6:7]
	s_add_u32 m0, s100, 0x16000
	v_add_u32_e32 v233, 0x80, v233
	global_load_lds_dwordx4 v235, s[6:7]
	v_add_u32_e32 v235, 0x80, v235
	s_barrier
	s_waitcnt lgkmcnt(0)
	v_mfma_f32_32x32x16_bf16 v[114:129], v[170:173], v[130:133], v[114:129]
	v_mfma_f32_32x32x16_bf16 v[82:97], v[170:173], v[146:149], v[82:97]
	v_mfma_f32_32x32x16_bf16 v[114:129], v[174:177], v[134:137], v[114:129]
	v_mfma_f32_32x32x16_bf16 v[82:97], v[174:177], v[150:153], v[82:97]
	v_mfma_f32_32x32x16_bf16 v[114:129], v[178:181], v[138:141], v[114:129]
	v_mfma_f32_32x32x16_bf16 v[82:97], v[178:181], v[156:159], v[82:97]
	v_mfma_f32_32x32x16_bf16 v[114:129], v[186:189], v[142:145], v[114:129]
	v_mfma_f32_32x32x16_bf16 v[82:97], v[186:189], v[160:163], v[82:97]
	s_barrier
	ds_read_b128 v[190:193], v164 offset:49152
	ds_read_b128 v[194:197], v165 offset:49152
	ds_read_b128 v[198:201], v202 offset:49152
	ds_read_b128 v[228:231], v203 offset:49152
	s_barrier
	s_waitcnt lgkmcnt(0)
	v_mfma_f32_32x32x16_bf16 v[98:113], v[190:193], v[130:133], v[98:113]
	v_mfma_f32_32x32x16_bf16 v[66:81], v[190:193], v[146:149], v[66:81]
	v_mfma_f32_32x32x16_bf16 v[98:113], v[194:197], v[134:137], v[98:113]
	v_mfma_f32_32x32x16_bf16 v[66:81], v[194:197], v[150:153], v[66:81]
	v_mfma_f32_32x32x16_bf16 v[98:113], v[198:201], v[138:141], v[98:113]
	v_mfma_f32_32x32x16_bf16 v[66:81], v[198:201], v[156:159], v[66:81]
	v_mfma_f32_32x32x16_bf16 v[98:113], v[228:231], v[142:145], v[98:113]
	v_mfma_f32_32x32x16_bf16 v[66:81], v[228:231], v[160:163], v[66:81]
	s_barrier
; template <bool SWAP>
; DI void gemm_mainloop(f32x16 (&acc)[4][2], const u16* __restrict__ A, int lda, int rlo, int rhi,
;                       const u16* __restrict__ B, int ldb, int K, char* lds, const u16* zero_line) {
;     ...
; #pragma unroll 2
;   for (int kt = 0; kt < nk; ++kt) {
;     const char* st = lds + (kt & 1) * 65536;
;     ldfrag(st, 0, 0);
;     mma(1);
;     pat_rd();
;     if (kt + 1 < nk) glds(kt + 1, (kt + 1) & 1);
;     ldfrag(st, 1, 1);
;     mma(0);
;     pat_rd();
;     ldfrag(st, 2, 0);
;     mma(1);
;     pat_rd();
;     ldfrag(st, 3, 1);
;     mma(0);
;     pat_rd();
;     asm volatile("s_waitcnt vmcnt(0)" ::: "memory");
;     __syncthreads();
;   }
;   mma(1);
	ds_read_b128 v[130:133], v240 offset:16384
	ds_read_b128 v[134:137], v241 offset:16384
	ds_read_b128 v[138:141], v242 offset:16384
	ds_read_b128 v[142:145], v243 offset:16384
	ds_read_b128 v[146:149], v240 offset:20480
	ds_read_b128 v[150:153], v241 offset:20480
	ds_read_b128 v[156:159], v242 offset:20480
	ds_read_b128 v[160:163], v243 offset:20480
	s_waitcnt vmcnt(4)
	s_barrier
	s_waitcnt lgkmcnt(0)
	v_mfma_f32_32x32x16_bf16 v[50:65], v[170:173], v[130:133], v[50:65]
	v_mfma_f32_32x32x16_bf16 v[18:33], v[170:173], v[146:149], v[18:33]
	v_mfma_f32_32x32x16_bf16 v[50:65], v[174:177], v[134:137], v[50:65]
	v_mfma_f32_32x32x16_bf16 v[18:33], v[174:177], v[150:153], v[18:33]
	v_mfma_f32_32x32x16_bf16 v[50:65], v[178:181], v[138:141], v[50:65]
	v_mfma_f32_32x32x16_bf16 v[18:33], v[178:181], v[156:159], v[18:33]
	v_mfma_f32_32x32x16_bf16 v[50:65], v[186:189], v[142:145], v[50:65]
	v_mfma_f32_32x32x16_bf16 v[18:33], v[186:189], v[160:163], v[18:33]
	v_mfma_f32_32x32x16_bf16 v[34:49], v[190:193], v[130:133], v[34:49]
	v_mfma_f32_32x32x16_bf16 v[2:17], v[190:193], v[146:149], v[2:17]
	v_mfma_f32_32x32x16_bf16 v[34:49], v[194:197], v[134:137], v[34:49]
	v_mfma_f32_32x32x16_bf16 v[2:17], v[194:197], v[150:153], v[2:17]
	v_mfma_f32_32x32x16_bf16 v[34:49], v[198:201], v[138:141], v[34:49]
	v_mfma_f32_32x32x16_bf16 v[2:17], v[198:201], v[156:159], v[2:17]
	v_mfma_f32_32x32x16_bf16 v[34:49], v[228:231], v[142:145], v[34:49]
	v_mfma_f32_32x32x16_bf16 v[2:17], v[228:231], v[160:163], v[2:17]
	s_barrier
	v_add_u32_e32 v246, s10, v164
	v_add_u32_e32 v247, s10, v165
	v_add_u32_e32 v248, s10, v202
	v_add_u32_e32 v249, s10, v203
	ds_read_b128 v[170:173], v246 offset:32768
	ds_read_b128 v[174:177], v247 offset:32768
	ds_read_b128 v[178:181], v248 offset:32768
	ds_read_b128 v[186:189], v249 offset:32768
	v_add_u32_e32 v246, s10, v240
	v_add_u32_e32 v247, s10, v241
	v_add_u32_e32 v248, s10, v242
	v_add_u32_e32 v249, s10, v243
	ds_read_b128 v[130:133], v246
	ds_read_b128 v[134:137], v247
	ds_read_b128 v[138:141], v248
	ds_read_b128 v[142:145], v249
	ds_read_b128 v[146:149], v246 offset:4096
	ds_read_b128 v[150:153], v247 offset:4096
	ds_read_b128 v[156:159], v248 offset:4096
	ds_read_b128 v[160:163], v249 offset:4096
	s_waitcnt vmcnt(2)
	s_barrier
	s_waitcnt lgkmcnt(0)
	v_mfma_f32_32x32x16_bf16 v[114:129], v[170:173], v[130:133], v[114:129]
	v_mfma_f32_32x32x16_bf16 v[82:97], v[170:173], v[146:149], v[82:97]
	v_mfma_f32_32x32x16_bf16 v[114:129], v[174:177], v[134:137], v[114:129]
	v_mfma_f32_32x32x16_bf16 v[82:97], v[174:177], v[150:153], v[82:97]
	v_mfma_f32_32x32x16_bf16 v[114:129], v[178:181], v[138:141], v[114:129]
	v_mfma_f32_32x32x16_bf16 v[82:97], v[178:181], v[156:159], v[82:97]
	v_mfma_f32_32x32x16_bf16 v[114:129], v[186:189], v[142:145], v[114:129]
	v_mfma_f32_32x32x16_bf16 v[82:97], v[186:189], v[160:163], v[82:97]
	s_barrier
	v_add_u32_e32 v246, s10, v164
	v_add_u32_e32 v247, s10, v165
	v_add_u32_e32 v248, s10, v202
	v_add_u32_e32 v249, s10, v203
	ds_read_b128 v[190:193], v246 offset:49152
	ds_read_b128 v[194:197], v247 offset:49152
	ds_read_b128 v[198:201], v248 offset:49152
	ds_read_b128 v[228:231], v249 offset:49152
	s_waitcnt vmcnt(0)
	s_barrier
	s_waitcnt lgkmcnt(0)
	v_mfma_f32_32x32x16_bf16 v[98:113], v[190:193], v[130:133], v[98:113]
	v_mfma_f32_32x32x16_bf16 v[66:81], v[190:193], v[146:149], v[66:81]
	v_mfma_f32_32x32x16_bf16 v[98:113], v[194:197], v[134:137], v[98:113]
	v_mfma_f32_32x32x16_bf16 v[66:81], v[194:197], v[150:153], v[66:81]
	v_mfma_f32_32x32x16_bf16 v[98:113], v[198:201], v[138:141], v[98:113]
	v_mfma_f32_32x32x16_bf16 v[66:81], v[198:201], v[156:159], v[66:81]
	v_mfma_f32_32x32x16_bf16 v[98:113], v[228:231], v[142:145], v[98:113]
	v_mfma_f32_32x32x16_bf16 v[66:81], v[228:231], v[160:163], v[66:81]
	s_barrier
	v_add_u32_e32 v246, s10, v240
	v_add_u32_e32 v247, s10, v241
	v_add_u32_e32 v248, s10, v242
	v_add_u32_e32 v249, s10, v243
	ds_read_b128 v[130:133], v246 offset:16384
	ds_read_b128 v[134:137], v247 offset:16384
	ds_read_b128 v[138:141], v248 offset:16384
	ds_read_b128 v[142:145], v249 offset:16384
	ds_read_b128 v[146:149], v246 offset:20480
	ds_read_b128 v[150:153], v247 offset:20480
	ds_read_b128 v[156:159], v248 offset:20480
	ds_read_b128 v[160:163], v249 offset:20480
	s_barrier
	s_waitcnt lgkmcnt(0)
	v_mfma_f32_32x32x16_bf16 v[50:65], v[170:173], v[130:133], v[50:65]
	v_mfma_f32_32x32x16_bf16 v[18:33], v[170:173], v[146:149], v[18:33]
	v_mfma_f32_32x32x16_bf16 v[50:65], v[174:177], v[134:137], v[50:65]
	v_mfma_f32_32x32x16_bf16 v[18:33], v[174:177], v[150:153], v[18:33]
	v_mfma_f32_32x32x16_bf16 v[50:65], v[178:181], v[138:141], v[50:65]
	v_mfma_f32_32x32x16_bf16 v[18:33], v[178:181], v[156:159], v[18:33]
	v_mfma_f32_32x32x16_bf16 v[50:65], v[186:189], v[142:145], v[50:65]
	v_mfma_f32_32x32x16_bf16 v[18:33], v[186:189], v[160:163], v[18:33]
	v_mfma_f32_32x32x16_bf16 v[34:49], v[190:193], v[130:133], v[34:49]
	v_mfma_f32_32x32x16_bf16 v[2:17], v[190:193], v[146:149], v[2:17]
	v_mfma_f32_32x32x16_bf16 v[34:49], v[194:197], v[134:137], v[34:49]
	v_mfma_f32_32x32x16_bf16 v[2:17], v[194:197], v[150:153], v[2:17]
	v_mfma_f32_32x32x16_bf16 v[34:49], v[198:201], v[138:141], v[34:49]
	v_mfma_f32_32x32x16_bf16 v[2:17], v[198:201], v[156:159], v[2:17]
	v_mfma_f32_32x32x16_bf16 v[34:49], v[228:231], v[142:145], v[34:49]
	v_mfma_f32_32x32x16_bf16 v[2:17], v[228:231], v[160:163], v[2:17]
	s_barrier
	s_cmp_eq_u32 s101, 0
	s_cbranch_scc0 .Lg8_qb_p1
	s_barrier

; template <bool SWAP>
; DI void gemm_mainloop(f32x16 (&acc)[4][2], const u16* __restrict__ A, int lda, int rlo, int rhi,
;                       const u16* __restrict__ B, int ldb, int K, char* lds, const u16* zero_line) {
;     ...
;   const int gch = (lc ^ ((lr >> 1) & 7)) * 8;
;   const u16* ap = A + (ptrdiff_t)lr * lda + gch;
;   const u16* bp = B + (ptrdiff_t)lr * ldb + gch;
;   const int nk = K >> 6;
;   typedef __attribute__((address_space(3))) unsigned lds_u32;
;   auto glds = [&](int kt, int st) {
;     char* as_ = lds + st * 65536 + tid * 16;
; #pragma unroll
;     for (int i = 0; i < 4; ++i) {
;       const int rr = lr + 64 * i;
;       const u16* srca = (rr >= rlo && rr < rhi) ? (ap + (ptrdiff_t)(64 * i) * lda + kt * 64) : (zero_line + lc * 8);
;       __builtin_amdgcn_global_load_lds((const unsigned*)srca, (lds_u32*)(as_ + i * 8192), 16, 0, 0);
;       __builtin_amdgcn_global_load_lds((const unsigned*)(bp + (ptrdiff_t)(64 * i) * ldb + kt * 64), (lds_u32*)(as_ + 32768 + i * 8192), 16, 0, 0);
;     }
;   };
; template <int EPI>
; DI void phase_gemm(const Params& p, const GemmArgs& ga, char* lds) {
;     ...
;   for (int it = 0; it * (int)gridDim.x < total; ++it) {
;     const int lt = logical_index(it);
;     if (lt >= total) continue;
;     int mt, nt;
;     tile_mn(lt, Mt, ga.Nt, mt, nt);
;     int bb, tokbase, S, pos0, rlo = 0, rhi = 256;
;     if (EPI == EPI_UP) {
;       bb = 0; tokbase = 0; S = NTOK;
;       pos0 = 254 * mt - 1;
;       rlo = (mt == 0) ? 1 : 0;
;       rhi = NTOK - pos0; if (rhi > 256) rhi = 256;
;     } else {
;       seq_of_token(mt * 256, bb, tokbase, S);
;       pos0 = mt * 256 - tokbase;
;     }
;     const u16* A = ga.A + (ptrdiff_t)(tokbase + pos0) * ga.lda;
;     const u16* B = ga.Bt + (size_t)(nt * 256) * ga.K;
.LBB0_244:
	s_add_i32 s6, s6, s27
	s_cmpk_gt_i32 s6, 0x2ff
	s_cbranch_scc1 .LBB0_243
	s_ashr_i32 s7, s6, 31
	s_lshr_b32 s7, s7, 27
	s_add_i32 s7, s6, s7
	s_ashr_i32 s35, s7, 5
	s_andn2_b32 s7, s7, 31
	s_sub_i32 s6, s6, s7
	s_ashr_i32 s7, s6, 31
	s_lshr_b32 s7, s7, 29
	s_add_i32 s7, s6, s7
	s_ashr_i32 s7, s7, 3
	s_lshl_b32 s8, s35, 11
	s_lshl_b32 s6, s6, 8
	s_lshl_b32 s24, s7, 8
	s_add_i32 s6, s6, s8
	s_lshl_b32 s36, s7, 11
	s_ashr_i32 s25, s24, 31
	s_sub_i32 s34, s6, s36
	s_mul_i32 s6, s25, s98
	s_mul_hi_u32 s7, s24, s98
	s_add_i32 s7, s7, s6
	s_mul_i32 s6, s24, s98
	s_lshl_b64 s[6:7], s[6:7], 1
	s_add_u32 s6, s16, s6
	v_mov_b32_e32 v10, v204
	s_addc_u32 s7, s17, s7
	s_ashr_i32 s8, s34, 31
	s_mul_i32 s8, s8, s98
	v_ashrrev_i32_e32 v2, 3, v10
	s_mul_hi_u32 s9, s34, s98
	v_mad_u64_u32 v[4:5], s[10:11], v2, s98, 0
	s_add_i32 s9, s9, s8
	s_mul_i32 s8, s34, s98
	v_ashrrev_i32_e32 v3, 31, v2
	v_mov_b32_e32 v0, v5
	s_lshl_b64 s[8:9], s[8:9], 1
	v_lshrrev_b32_e32 v12, 1, v2
	v_mad_u64_u32 v[6:7], s[10:11], v3, s98, v[0:1]
	s_add_u32 s8, s12, s8
	v_xor_b32_e32 v9, v12, v10
	v_mov_b32_e32 v5, v6
	s_addc_u32 s9, s13, s9
	v_lshlrev_b64 v[4:5], 1, v[4:5]
	v_lshlrev_b32_e32 v0, 4, v9
	v_and_b32_e32 v8, 31, v10
	v_lshl_add_u64 v[6:7], s[8:9], 0, v[4:5]
	v_and_b32_e32 v0, 0x70, v0
	v_lshl_add_u64 v[4:5], s[6:7], 0, v[4:5]
	v_lshrrev_b32_e32 v13, 1, v10
	v_lshl_add_u64 v[6:7], v[6:7], 0, v[0:1]
	v_lshl_add_u64 v[4:5], v[4:5], 0, v[0:1]
	v_and_or_b32 v0, v13, s51, v8
	v_lshlrev_b32_e32 v203, 7, v0
	v_lshlrev_b32_e32 v0, 7, v10
	v_lshlrev_b32_e32 v226, 4, v10
	v_and_b32_e32 v202, 0x6f80, v0
	v_and_b32_e32 v0, 0x70, v226
	v_add_u32_e32 v15, 0x8000, v226
	v_lshl_add_u64 v[180:181], s[80:81], 0, v[0:1]
	v_cmp_gt_u32_e32 vcc, s50, v2
	v_readfirstlane_b32 s6, v226
	s_mov_b32 m0, s6
	v_cndmask_b32_e32 v9, v181, v7, vcc
	v_cndmask_b32_e32 v8, v180, v6, vcc
	v_readfirstlane_b32 s6, v15
	v_add_u32_e32 v0, 64, v2
	s_barrier
	s_mov_b32 m0, s6
	v_cmp_gt_u32_e64 s[6:7], s50, v0
	v_add_u32_e32 v0, 0x2000, v226
	v_lshl_add_u64 v[6:7], v[6:7], 0, s[18:19]
	v_readfirstlane_b32 s8, v0
	v_add_u32_e32 v0, 0xa000, v226
	v_cndmask_b32_e64 v9, v181, v7, s[6:7]
	v_cndmask_b32_e64 v8, v180, v6, s[6:7]
	s_mov_b32 m0, s8
	v_readfirstlane_b32 s8, v0
	v_add_u32_e32 v0, 0x80, v2
	s_mov_b32 m0, s8
	v_cmp_gt_u32_e64 s[8:9], s50, v0
	v_add_u32_e32 v0, 0x4000, v226
	v_lshl_add_u64 v[4:5], v[4:5], 0, s[18:19]
	v_lshl_add_u64 v[6:7], v[6:7], 0, s[18:19]
	v_readfirstlane_b32 s10, v0
	v_add_u32_e32 v0, 0xc000, v226
	v_cndmask_b32_e64 v9, v181, v7, s[8:9]
	v_cndmask_b32_e64 v8, v180, v6, s[8:9]
	s_mov_b32 m0, s10
	v_readfirstlane_b32 s10, v0
	v_add_u32_e32 v0, 0xc0, v2
	s_mov_b32 m0, s10
	v_cmp_gt_u32_e64 s[10:11], s50, v0
	v_add_u32_e32 v0, 0x6000, v226
	v_lshl_add_u64 v[4:5], v[4:5], 0, s[18:19]
	v_lshl_add_u64 v[6:7], v[6:7], 0, s[18:19]
	v_readfirstlane_b32 s37, v0
	v_add_u32_e32 v0, 0xe000, v226
	v_cndmask_b32_e64 v7, v181, v7, s[10:11]
	v_cndmask_b32_e64 v6, v180, v6, s[10:11]
	s_mov_b32 m0, s37
	v_readfirstlane_b32 s37, v0
	v_lshl_add_u64 v[4:5], v[4:5], 0, s[18:19]
	s_mov_b32 m0, s37
	s_sub_i32 s36, s29, s36
	s_mulk_i32 s35, 0x1800
	s_sub_i32 s36, s36, s35
	s_ashr_i32 s37, s36, 31
	v_lshlrev_b64 v[2:3], 1, v[2:3]
	s_lshl_b64 s[36:37], s[36:37], 1
	v_lshl_add_u64 v[4:5], v[2:3], 0, s[36:37]
	v_mov_b64_e32 v[6:7], s[20:21]
	v_mad_u64_u32 v[182:183], s[38:39], s98, v4, v[6:7]
	v_mov_b32_e32 v4, v183
	v_mad_u64_u32 v[4:5], s[38:39], s98, v5, v[4:5]
	s_lshl_b64 s[38:39], s[24:25], 1
	v_bfe_u32 v11, v10, 5, 1
	v_mov_b32_e32 v183, v4
	v_lshl_add_u64 v[4:5], v[2:3], 0, s[38:39]
	v_mov_b64_e32 v[8:9], s[22:23]
	v_bfe_u32 v14, v10, 1, 3
	v_bitop3_b32 v0, v13, v11, 7 bitop3:0x6c
	v_mad_u64_u32 v[186:187], s[40:41], s98, v4, v[8:9]
	v_lshlrev_b32_e32 v228, 4, v0
	v_bitop3_b32 v0, v11, v14, 2 bitop3:0x36
	v_mov_b32_e32 v4, v187
	v_lshlrev_b32_e32 v227, 4, v0
	v_bitop3_b32 v0, v11, v14, 4 bitop3:0x36
	v_mad_u64_u32 v[4:5], s[40:41], s98, v5, v[4:5]
	v_lshlrev_b32_e32 v201, 4, v0
	v_bitop3_b32 v0, v11, v14, 6 bitop3:0x36
	v_mov_b32_e32 v187, v4
	v_lshl_add_u64 v[4:5], v[2:3], 0, s[4:5]
	v_lshlrev_b32_e32 v179, 4, v0
	v_bitop3_b32 v0, v12, 7, v10 bitop3:0x48
	v_lshl_add_u64 v[10:11], v[4:5], 0, s[36:37]
	v_lshl_add_u64 v[4:5], v[4:5], 0, s[38:39]
	v_mad_u64_u32 v[188:189], s[40:41], s98, v10, v[6:7]
	v_mad_u64_u32 v[190:191], s[40:41], s98, v4, v[8:9]
	v_mov_b32_e32 v10, v189
	v_mov_b32_e32 v4, v191
	v_mad_u64_u32 v[10:11], s[40:41], s98, v11, v[10:11]
	v_mad_u64_u32 v[4:5], s[40:41], s98, v5, v[4:5]
	s_mov_b64 s[40:41], 0x100
	v_mov_b32_e32 v191, v4
	v_lshl_add_u64 v[4:5], v[2:3], 0, s[40:41]
	v_mov_b32_e32 v189, v10
	v_lshl_add_u64 v[10:11], v[4:5], 0, s[36:37]
	v_lshl_add_u64 v[4:5], v[4:5], 0, s[38:39]
	v_mad_u64_u32 v[192:193], s[40:41], s98, v10, v[6:7]
	v_mad_u64_u32 v[194:195], s[40:41], s98, v4, v[8:9]
	v_mov_b32_e32 v10, v193
	v_mov_b32_e32 v4, v195
	v_mad_u64_u32 v[10:11], s[40:41], s98, v11, v[10:11]
	v_mad_u64_u32 v[4:5], s[40:41], s98, v5, v[4:5]
	s_mov_b64 s[40:41], 0x180
	s_nop 0
	v_lshl_add_u64 v[2:3], v[2:3], 0, s[40:41]
	v_mov_b32_e32 v195, v4
	v_lshl_add_u64 v[4:5], v[2:3], 0, s[36:37]
	v_lshl_add_u64 v[2:3], v[2:3], 0, s[38:39]
	v_mad_u64_u32 v[198:199], s[36:37], s98, v2, v[8:9]
	v_mad_u64_u32 v[196:197], s[36:37], s98, v4, v[6:7]
	v_mov_b32_e32 v2, v199
	s_waitcnt vmcnt(0)
; template <bool SWAP>
; DI void gemm_mainloop(f32x16 (&acc)[4][2], const u16* __restrict__ A, int lda, int rlo, int rhi,
;                       const u16* __restrict__ B, int ldb, int K, char* lds, const u16* zero_line) {
;     ...
; #pragma unroll
;   for (int mi = 0; mi < 4; ++mi)
; #pragma unroll
;     for (int ni = 0; ni < 2; ++ni)
; #pragma unroll
;       for (int i = 0; i < 16; ++i) acc[mi][ni][i] = 0.f;
;   const int gch = (lc ^ ((lr >> 1) & 7)) * 8;
;   const u16* ap = A + (ptrdiff_t)lr * lda + gch;
;   const u16* bp = B + (ptrdiff_t)lr * ldb + gch;
;   const int nk = K >> 6;
;   typedef __attribute__((address_space(3))) unsigned lds_u32;
;   auto glds = [&](int kt, int st) {
;     char* as_ = lds + st * 65536 + tid * 16;
; #pragma unroll
;     for (int i = 0; i < 4; ++i) {
;       const int rr = lr + 64 * i;
;       const u16* srca = (rr >= rlo && rr < rhi) ? (ap + (ptrdiff_t)(64 * i) * lda + kt * 64) : (zero_line + lc * 8);
;       __builtin_amdgcn_global_load_lds((const unsigned*)srca, (lds_u32*)(as_ + i * 8192), 16, 0, 0);
;       __builtin_amdgcn_global_load_lds((const unsigned*)(bp + (ptrdiff_t)(64 * i) * ldb + kt * 64), (lds_u32*)(as_ + 32768 + i * 8192), 16, 0, 0);
;     }
;   };
;   const int sw = (r >> 1) & 7;
;   const int arow_off = (wm * 128 + r) * 128;
;   const int brow_off = 32768 + (wn * 64 + r) * 128;
;   __syncthreads();
;   glds(0, 0);
;   asm volatile("s_waitcnt vmcnt(0)" ::: "memory");
;   __syncthreads();
	v_mov_b32_e32 v4, v197
	v_mad_u64_u32 v[2:3], s[36:37], s98, v3, v[2:3]
	v_mad_u64_u32 v[4:5], s[36:37], s98, v5, v[4:5]
	v_mov_b32_e32 v199, v2
	v_mov_b32_e32 v130, 0
	v_mov_b32_e32 v2, 0
	v_lshlrev_b32_e32 v0, 4, v0
	v_mov_b32_e32 v193, v10
	v_mov_b32_e32 v197, v4
	s_mov_b32 s25, 0x10000
	v_mov_b32_e32 v3, v2
	v_mov_b32_e32 v4, v2
	v_mov_b32_e32 v5, v2
	v_mov_b32_e32 v6, v2
	v_mov_b32_e32 v7, v2
	v_mov_b32_e32 v8, v2
	v_mov_b32_e32 v9, v2
	v_mov_b32_e32 v10, v2
	v_mov_b32_e32 v11, v2
	v_mov_b32_e32 v12, v2
	v_mov_b32_e32 v13, v2
	v_mov_b32_e32 v14, v2
	v_mov_b32_e32 v15, v2
	v_mov_b32_e32 v16, v2
	v_mov_b32_e32 v17, v2
	v_mov_b32_e32 v18, v2
	v_mov_b32_e32 v19, v2
	v_mov_b32_e32 v20, v2
	v_mov_b32_e32 v21, v2
	v_mov_b32_e32 v22, v2
	v_mov_b32_e32 v23, v2
	v_mov_b32_e32 v24, v2
	v_mov_b32_e32 v25, v2
	v_mov_b32_e32 v26, v2
	v_mov_b32_e32 v27, v2
	v_mov_b32_e32 v28, v2
	v_mov_b32_e32 v29, v2
	v_mov_b32_e32 v30, v2
	v_mov_b32_e32 v31, v2
	v_mov_b32_e32 v32, v2
	v_mov_b32_e32 v33, v2
	v_mov_b32_e32 v34, v2
	v_mov_b32_e32 v35, v2
	v_mov_b32_e32 v36, v2
	v_mov_b32_e32 v37, v2
	v_mov_b32_e32 v38, v2
	v_mov_b32_e32 v39, v2
	v_mov_b32_e32 v40, v2
	v_mov_b32_e32 v41, v2
	v_mov_b32_e32 v42, v2
	v_mov_b32_e32 v43, v2
	v_mov_b32_e32 v44, v2
	v_mov_b32_e32 v45, v2
	v_mov_b32_e32 v46, v2
	v_mov_b32_e32 v47, v2
	v_mov_b32_e32 v48, v2
	v_mov_b32_e32 v49, v2
	v_mov_b32_e32 v50, v2
	v_mov_b32_e32 v51, v2
	v_mov_b32_e32 v52, v2
	v_mov_b32_e32 v53, v2
	v_mov_b32_e32 v54, v2
	v_mov_b32_e32 v55, v2
	v_mov_b32_e32 v56, v2
	v_mov_b32_e32 v57, v2
	v_mov_b32_e32 v58, v2
	v_mov_b32_e32 v59, v2
	v_mov_b32_e32 v60, v2
	v_mov_b32_e32 v61, v2
	v_mov_b32_e32 v62, v2
	v_mov_b32_e32 v63, v2
	v_mov_b32_e32 v64, v2
	v_mov_b32_e32 v65, v2
	v_mov_b32_e32 v66, v2
	v_mov_b32_e32 v67, v2
	v_mov_b32_e32 v68, v2
	v_mov_b32_e32 v69, v2
	v_mov_b32_e32 v70, v2
	v_mov_b32_e32 v71, v2
	v_mov_b32_e32 v72, v2
	v_mov_b32_e32 v73, v2
	v_mov_b32_e32 v74, v2
	v_mov_b32_e32 v75, v2
	v_mov_b32_e32 v76, v2
	v_mov_b32_e32 v77, v2
	v_mov_b32_e32 v78, v2
	v_mov_b32_e32 v79, v2
	v_mov_b32_e32 v80, v2
	v_mov_b32_e32 v81, v2
	v_mov_b32_e32 v82, v2
	v_mov_b32_e32 v83, v2
	v_mov_b32_e32 v84, v2
	v_mov_b32_e32 v85, v2
	v_mov_b32_e32 v86, v2
	v_mov_b32_e32 v87, v2
	v_mov_b32_e32 v88, v2
	v_mov_b32_e32 v89, v2
	v_mov_b32_e32 v90, v2
	v_mov_b32_e32 v91, v2
	v_mov_b32_e32 v92, v2
	v_mov_b32_e32 v93, v2
	v_mov_b32_e32 v94, v2
	v_mov_b32_e32 v95, v2
	v_mov_b32_e32 v96, v2
	v_mov_b32_e32 v97, v2
	v_mov_b32_e32 v98, v2
	v_mov_b32_e32 v99, v2
	v_mov_b32_e32 v100, v2
	v_mov_b32_e32 v101, v2
	v_mov_b32_e32 v102, v2
	v_mov_b32_e32 v103, v2
	v_mov_b32_e32 v104, v2
	v_mov_b32_e32 v105, v2
	v_mov_b32_e32 v106, v2
	v_mov_b32_e32 v107, v2
	v_mov_b32_e32 v108, v2
	v_mov_b32_e32 v109, v2
	v_mov_b32_e32 v110, v2
	v_mov_b32_e32 v111, v2
	v_mov_b32_e32 v112, v2
	v_mov_b32_e32 v113, v2
	v_mov_b32_e32 v114, v2
	v_mov_b32_e32 v115, v2
	v_mov_b32_e32 v116, v2
	v_mov_b32_e32 v117, v2
	v_mov_b32_e32 v118, v2
	v_mov_b32_e32 v119, v2
	v_mov_b32_e32 v120, v2
	v_mov_b32_e32 v121, v2
	v_mov_b32_e32 v122, v2
	v_mov_b32_e32 v123, v2
	v_mov_b32_e32 v124, v2
	v_mov_b32_e32 v125, v2
	v_mov_b32_e32 v126, v2
	v_mov_b32_e32 v127, v2
	v_mov_b32_e32 v128, v2
	v_mov_b32_e32 v129, v2
	v_mov_b32_e32 v131, v130
	v_mov_b32_e32 v132, v130
	v_mov_b32_e32 v133, v130
	v_mov_b32_e32 v134, v130
	v_mov_b32_e32 v135, v130
	v_mov_b32_e32 v136, v130
	v_mov_b32_e32 v137, v130
	v_mov_b32_e32 v142, v130
	v_mov_b32_e32 v143, v130
	v_mov_b32_e32 v144, v130
	v_mov_b32_e32 v145, v130
	v_mov_b32_e32 v150, v130
	v_mov_b32_e32 v151, v130
	v_mov_b32_e32 v152, v130
	v_mov_b32_e32 v153, v130
	v_mov_b32_e32 v138, v130
	v_mov_b32_e32 v139, v130
	v_mov_b32_e32 v140, v130
	v_mov_b32_e32 v141, v130
	v_mov_b32_e32 v146, v130
	v_mov_b32_e32 v147, v130
	v_mov_b32_e32 v148, v130
	v_mov_b32_e32 v149, v130
	s_waitcnt vmcnt(0) lgkmcnt(0)
	s_barrier
	s_mul_i32 s6, s34, s98
	s_mul_hi_u32 s7, s34, s98
	s_lshl_b64 s[6:7], s[6:7], 1
	s_add_u32 s6, s12, s6
	s_addc_u32 s7, s13, s7
	s_mul_i32 s8, s24, s98
	s_mul_hi_u32 s9, s24, s98
	s_lshl_b64 s[8:9], s[8:9], 1
	s_add_u32 s8, s16, s8
	s_addc_u32 s9, s17, s9
	v_and_b32_e32 v130, 63, v204
	v_lshrrev_b32_e32 v131, 6, v204
	v_lshrrev_b32_e32 v132, 3, v204
	v_lshrrev_b32_e32 v0, 4, v130
	v_lshl_add_u32 v0, v131, 2, v0
	v_xor_b32_e32 v0, v0, v130
	v_and_b32_e32 v0, 7, v0
	v_lshlrev_b32_e32 v133, 4, v0
	v_mul_lo_u32 v0, v132, s98
	v_lshl_add_u32 v232, v0, 1, v133
	s_lshl_b32 s28, s98, 7
	v_add_u32_e32 v233, s28, v232
	v_add_u32_e32 v234, s28, v233
	v_add_u32_e32 v235, s28, v234
	v_and_b32_e32 v0, 31, v132
	v_lshrrev_b32_e32 v130, 5, v132
	v_lshl_add_u32 v0, v130, 6, v0
	v_mul_lo_u32 v0, v0, s98
	v_lshl_add_u32 v236, v0, 1, v133
	s_lshl_b32 s28, s98, 6
	v_add_u32_e32 v237, s28, v236
	s_lshl_b32 s28, s98, 8
	v_add_u32_e32 v238, s28, v236
	v_add_u32_e32 v239, s28, v237
	s_lshr_b32 s25, s98, 6
	s_add_i32 s25, s25, -2
	v_and_b32_e32 v132, 31, v204
	v_lshrrev_b32_e32 v0, 2, v131
	v_lshl_add_u32 v0, v0, 6, v132
	v_lshlrev_b32_e32 v244, 7, v0
	v_and_b32_e32 v0, 3, v131
	v_lshl_add_u32 v0, v0, 5, v132
	v_lshlrev_b32_e32 v245, 7, v0
	v_bfe_u32 v0, v204, 5, 1
	v_bfe_u32 v130, v132, 1, 3
	v_or_b32_e32 v133, 0, v0
	v_xor_b32_e32 v133, v133, v130
	v_lshlrev_b32_e32 v240, 4, v133
	v_or_b32_e32 v133, 2, v0
	v_xor_b32_e32 v133, v133, v130
	v_lshlrev_b32_e32 v241, 4, v133
	v_or_b32_e32 v133, 4, v0
	v_xor_b32_e32 v133, v133, v130
	v_lshlrev_b32_e32 v242, 4, v133
	v_or_b32_e32 v133, 6, v0
	v_xor_b32_e32 v133, v133, v130
	v_lshlrev_b32_e32 v243, 4, v133
	v_add_u32_e32 v246, v245, v240
	v_add_u32_e32 v247, v245, v241
	v_add_u32_e32 v248, v245, v242
	v_add_u32_e32 v249, v245, v243
	v_add_u32_e32 v240, v244, v240
	v_add_u32_e32 v241, v244, v241
	v_add_u32_e32 v242, v244, v242
	v_add_u32_e32 v243, v244, v243
	v_lshlrev_b32_e32 v131, 10, v131
	s_nop 0
	v_readfirstlane_b32 s100, v131
	v_mov_b32_e32 v146, 0
	v_mov_b32_e32 v147, 0
	v_mov_b32_e32 v148, 0
	v_mov_b32_e32 v149, 0
	v_lshlrev_b32_e32 v130, 4, v204
	v_add_u32_e32 v132, 0x10000, v130
	s_mov_b64 exec, -1
	s_mov_b32 s11, 0
	s_mov_b32 s10, 0x10000
	s_waitcnt lgkmcnt(0)
	s_add_u32 m0, s100, 0x8000
	s_nop 0
	global_load_lds_dwordx4 v236, s[8:9]
	s_add_u32 m0, s100, 0xa000
	v_add_u32_e32 v236, 0x80, v236
	global_load_lds_dwordx4 v238, s[8:9]
	v_add_u32_e32 v238, 0x80, v238
	s_add_u32 m0, s100, 0x0
	s_nop 0
	global_load_lds_dwordx4 v232, s[6:7]
	s_add_u32 m0, s100, 0x2000
	v_add_u32_e32 v232, 0x80, v232
	global_load_lds_dwordx4 v234, s[6:7]
	v_add_u32_e32 v234, 0x80, v234
	s_add_u32 m0, s100, 0xc000
	s_nop 0
	global_load_lds_dwordx4 v237, s[8:9]
	s_add_u32 m0, s100, 0xe000
	v_add_u32_e32 v237, 0x80, v237
	global_load_lds_dwordx4 v239, s[8:9]
	v_add_u32_e32 v239, 0x80, v239
	s_add_u32 m0, s100, 0x4000
	s_nop 0
	global_load_lds_dwordx4 v233, s[6:7]
	s_add_u32 m0, s100, 0x6000
	v_add_u32_e32 v233, 0x80, v233
	global_load_lds_dwordx4 v235, s[6:7]
	v_add_u32_e32 v235, 0x80, v235
	s_cmp_eq_u32 s101, 1
	s_cbranch_scc0 .Lg8_m246_p0
	s_barrier
; #define MFMA(a, b, c) __builtin_amdgcn_mfma_f32_32x32x16_bf16((a), (b), (c), 0, 0, 0)
; template <bool SWAP>
; DI void gemm_mainloop(f32x16 (&acc)[4][2], const u16* __restrict__ A, int lda, int rlo, int rhi,
;                       const u16* __restrict__ B, int ldb, int K, char* lds, const u16* zero_line) {
;     ...
;   auto ldfrag = [&](const char* st, int ks, int buf) {
;     const int co = ((2 * ks + h) ^ sw) << 4;
; #pragma unroll
;     for (int mi = 0; mi < 4; ++mi) fa[buf][mi] = *(const bf16x8*)(st + arow_off + mi * 4096 + co);
; #pragma unroll
;     for (int ni = 0; ni < 2; ++ni) fb[buf][ni] = *(const bf16x8*)(st + brow_off + ni * 4096 + co);
;   };
;   auto mma = [&](int buf) {
; #pragma unroll
;     for (int mi = 0; mi < 4; ++mi)
; #pragma unroll
;       for (int ni = 0; ni < 2; ++ni)
;         acc[mi][ni] = SWAP ? MFMA(fb[buf][ni], fa[buf][mi], acc[mi][ni]) : MFMA(fa[buf][mi], fb[buf][ni], acc[mi][ni]);
;   };
;   auto pat_rd = [&]() {
; #pragma unroll
;     for (int g = 0; g < 6; ++g) {
;       __builtin_amdgcn_sched_group_barrier(0x100, 1, 0);
;       __builtin_amdgcn_sched_group_barrier(0x008, 1, 0);
;     }
;     __builtin_amdgcn_sched_group_barrier(0x008, 2, 0);
;   };
; #pragma unroll 2
;   for (int kt = 0; kt < nk; ++kt) {
;     const char* st = lds + (kt & 1) * 65536;
;     ldfrag(st, 0, 0);
;     mma(1);
;     pat_rd();
;     if (kt + 1 < nk) glds(kt + 1, (kt + 1) & 1);
;     ldfrag(st, 1, 1);
;     mma(0);
;     pat_rd();
;     ldfrag(st, 2, 0);
;     mma(1);
;     pat_rd();
;     ldfrag(st, 3, 1);
;     mma(0);
;     pat_rd();
;     asm volatile("s_waitcnt vmcnt(0)" ::: "memory");
;     __syncthreads();
;   }
.Lg8_m246_p0:
	s_waitcnt vmcnt(4)
	s_barrier
	s_add_u32 m0, s100, 0x18000
	s_nop 0
	global_load_lds_dwordx4 v236, s[8:9]
	s_add_u32 m0, s100, 0x1a000
	v_add_u32_e32 v236, 0x80, v236
	global_load_lds_dwordx4 v238, s[8:9]
	v_add_u32_e32 v238, 0x80, v238
	s_add_u32 m0, s100, 0x10000
	s_nop 0
	global_load_lds_dwordx4 v232, s[6:7]
	s_add_u32 m0, s100, 0x12000
	v_add_u32_e32 v232, 0x80, v232
	global_load_lds_dwordx4 v234, s[6:7]
	v_add_u32_e32 v234, 0x80, v234
	s_add_u32 m0, s100, 0x1c000
	s_nop 0
	global_load_lds_dwordx4 v237, s[8:9]
	s_add_u32 m0, s100, 0x1e000
	v_add_u32_e32 v237, 0x80, v237
	global_load_lds_dwordx4 v239, s[8:9]
	v_add_u32_e32 v239, 0x80, v239
	s_waitcnt vmcnt(6)
	s_barrier
	ds_read_b128 v[162:165], v246 offset:32768
	ds_read_b128 v[166:169], v247 offset:32768
	ds_read_b128 v[170:173], v248 offset:32768
	ds_read_b128 v[174:177], v249 offset:32768
.Lg8_m246:
	s_add_u32 m0, s100, 0x14000
	ds_read_b128 v[130:133], v240
	ds_read_b128 v[134:137], v241
	ds_read_b128 v[138:141], v242
	ds_read_b128 v[142:145], v243
	ds_read_b128 v[146:149], v240 offset:4096
	ds_read_b128 v[150:153], v241 offset:4096
	ds_read_b128 v[154:157], v242 offset:4096
	ds_read_b128 v[158:161], v243 offset:4096
	global_load_lds_dwordx4 v233, s[6:7]
	s_add_u32 m0, s100, 0x16000
	v_add_u32_e32 v233, 0x80, v233
	global_load_lds_dwordx4 v235, s[6:7]
	v_add_u32_e32 v235, 0x80, v235
	s_barrier
	s_waitcnt lgkmcnt(0)
	v_mfma_f32_32x32x16_bf16 v[114:129], v[162:165], v[130:133], v[114:129]
	v_mfma_f32_32x32x16_bf16 v[82:97], v[162:165], v[146:149], v[82:97]
	v_mfma_f32_32x32x16_bf16 v[114:129], v[166:169], v[134:137], v[114:129]
	v_mfma_f32_32x32x16_bf16 v[82:97], v[166:169], v[150:153], v[82:97]
	v_mfma_f32_32x32x16_bf16 v[114:129], v[170:173], v[138:141], v[114:129]
	v_mfma_f32_32x32x16_bf16 v[82:97], v[170:173], v[154:157], v[82:97]
	v_mfma_f32_32x32x16_bf16 v[114:129], v[174:177], v[142:145], v[114:129]
	v_mfma_f32_32x32x16_bf16 v[82:97], v[174:177], v[158:161], v[82:97]
	s_barrier
	s_add_u32 m0, s100, 0x8000
	ds_read_b128 v[180:183], v246 offset:49152
	ds_read_b128 v[186:189], v247 offset:49152
	ds_read_b128 v[190:193], v248 offset:49152
	ds_read_b128 v[194:197], v249 offset:49152
	global_load_lds_dwordx4 v236, s[8:9]
	s_add_u32 m0, s100, 0xa000
	v_add_u32_e32 v236, 0x80, v236
	global_load_lds_dwordx4 v238, s[8:9]
	v_add_u32_e32 v238, 0x80, v238
	s_barrier
	s_waitcnt lgkmcnt(0)
	v_mfma_f32_32x32x16_bf16 v[98:113], v[180:183], v[130:133], v[98:113]
	v_mfma_f32_32x32x16_bf16 v[66:81], v[180:183], v[146:149], v[66:81]
	v_mfma_f32_32x32x16_bf16 v[98:113], v[186:189], v[134:137], v[98:113]
	v_mfma_f32_32x32x16_bf16 v[66:81], v[186:189], v[150:153], v[66:81]
	v_mfma_f32_32x32x16_bf16 v[98:113], v[190:193], v[138:141], v[98:113]
	v_mfma_f32_32x32x16_bf16 v[66:81], v[190:193], v[154:157], v[66:81]
	v_mfma_f32_32x32x16_bf16 v[98:113], v[194:197], v[142:145], v[98:113]
	v_mfma_f32_32x32x16_bf16 v[66:81], v[194:197], v[158:161], v[66:81]
	s_barrier
	s_add_u32 m0, s100, 0x0
	ds_read_b128 v[130:133], v240 offset:16384
	ds_read_b128 v[134:137], v241 offset:16384
	ds_read_b128 v[138:141], v242 offset:16384
	ds_read_b128 v[142:145], v243 offset:16384
	ds_read_b128 v[146:149], v240 offset:20480
	ds_read_b128 v[150:153], v241 offset:20480
	ds_read_b128 v[154:157], v242 offset:20480
	ds_read_b128 v[158:161], v243 offset:20480
	global_load_lds_dwordx4 v232, s[6:7]
	s_add_u32 m0, s100, 0x2000
	v_add_u32_e32 v232, 0x80, v232
	global_load_lds_dwordx4 v234, s[6:7]
	v_add_u32_e32 v234, 0x80, v234
	s_waitcnt vmcnt(10)
	s_barrier
	s_waitcnt lgkmcnt(0)
	v_mfma_f32_32x32x16_bf16 v[50:65], v[162:165], v[130:133], v[50:65]
	v_mfma_f32_32x32x16_bf16 v[18:33], v[162:165], v[146:149], v[18:33]
	v_mfma_f32_32x32x16_bf16 v[50:65], v[166:169], v[134:137], v[50:65]
	v_mfma_f32_32x32x16_bf16 v[18:33], v[166:169], v[150:153], v[18:33]
	v_mfma_f32_32x32x16_bf16 v[50:65], v[170:173], v[138:141], v[50:65]
	v_mfma_f32_32x32x16_bf16 v[18:33], v[170:173], v[154:157], v[18:33]
	v_mfma_f32_32x32x16_bf16 v[50:65], v[174:177], v[142:145], v[50:65]
	v_mfma_f32_32x32x16_bf16 v[18:33], v[174:177], v[158:161], v[18:33]
	s_barrier
	s_add_u32 m0, s100, 0xc000
	v_add_u32_e32 v244, s10, v246
	v_add_u32_e32 v245, s10, v247
	ds_read_b128 v[162:165], v244 offset:32768
	ds_read_b128 v[166:169], v245 offset:32768
	v_add_u32_e32 v244, s10, v248
	v_add_u32_e32 v245, s10, v249
	ds_read_b128 v[170:173], v244 offset:32768
	ds_read_b128 v[174:177], v245 offset:32768
	global_load_lds_dwordx4 v237, s[8:9]
	s_add_u32 m0, s100, 0xe000
	v_add_u32_e32 v237, 0x80, v237
	global_load_lds_dwordx4 v239, s[8:9]
	v_add_u32_e32 v239, 0x80, v239
	s_waitcnt vmcnt(6)
	s_barrier
	s_waitcnt lgkmcnt(0)
	v_mfma_f32_32x32x16_bf16 v[34:49], v[180:183], v[130:133], v[34:49]
	v_mfma_f32_32x32x16_bf16 v[2:17], v[180:183], v[146:149], v[2:17]
	v_mfma_f32_32x32x16_bf16 v[34:49], v[186:189], v[134:137], v[34:49]
	v_mfma_f32_32x32x16_bf16 v[2:17], v[186:189], v[150:153], v[2:17]
	v_mfma_f32_32x32x16_bf16 v[34:49], v[190:193], v[138:141], v[34:49]
	v_mfma_f32_32x32x16_bf16 v[2:17], v[190:193], v[154:157], v[2:17]
	v_mfma_f32_32x32x16_bf16 v[34:49], v[194:197], v[142:145], v[34:49]
	v_mfma_f32_32x32x16_bf16 v[2:17], v[194:197], v[158:161], v[2:17]
	s_barrier
	s_add_u32 m0, s100, 0x4000
	v_add_u32_e32 v244, s10, v240
	v_add_u32_e32 v245, s10, v241
	ds_read_b128 v[130:133], v244
	ds_read_b128 v[134:137], v245
	ds_read_b128 v[146:149], v244 offset:4096
	ds_read_b128 v[150:153], v245 offset:4096
	v_add_u32_e32 v244, s10, v242
	v_add_u32_e32 v245, s10, v243
	ds_read_b128 v[138:141], v244
	ds_read_b128 v[142:145], v245
	ds_read_b128 v[154:157], v244 offset:4096
	ds_read_b128 v[158:161], v245 offset:4096
	global_load_lds_dwordx4 v233, s[6:7]
	s_add_u32 m0, s100, 0x6000
	v_add_u32_e32 v233, 0x80, v233
	global_load_lds_dwordx4 v235, s[6:7]
	v_add_u32_e32 v235, 0x80, v235
	s_barrier
; #define MFMA(a, b, c) __builtin_amdgcn_mfma_f32_32x32x16_bf16((a), (b), (c), 0, 0, 0)
; template <bool SWAP>
; DI void gemm_mainloop(f32x16 (&acc)[4][2], const u16* __restrict__ A, int lda, int rlo, int rhi,
;                       const u16* __restrict__ B, int ldb, int K, char* lds, const u16* zero_line) {
;     ...
;   auto ldfrag = [&](const char* st, int ks, int buf) {
;     const int co = ((2 * ks + h) ^ sw) << 4;
; #pragma unroll
;     for (int mi = 0; mi < 4; ++mi) fa[buf][mi] = *(const bf16x8*)(st + arow_off + mi * 4096 + co);
; #pragma unroll
;     for (int ni = 0; ni < 2; ++ni) fb[buf][ni] = *(const bf16x8*)(st + brow_off + ni * 4096 + co);
;   };
;   auto mma = [&](int buf) {
; #pragma unroll
;     for (int mi = 0; mi < 4; ++mi)
; #pragma unroll
;       for (int ni = 0; ni < 2; ++ni)
;         acc[mi][ni] = SWAP ? MFMA(fb[buf][ni], fa[buf][mi], acc[mi][ni]) : MFMA(fa[buf][mi], fb[buf][ni], acc[mi][ni]);
;   };
;   auto pat_rd = [&]() {
; #pragma unroll
;     for (int g = 0; g < 6; ++g) {
;       __builtin_amdgcn_sched_group_barrier(0x100, 1, 0);
;       __builtin_amdgcn_sched_group_barrier(0x008, 1, 0);
;     }
;     __builtin_amdgcn_sched_group_barrier(0x008, 2, 0);
;   };
; #pragma unroll 2
;   for (int kt = 0; kt < nk; ++kt) {
;     const char* st = lds + (kt & 1) * 65536;
;     ldfrag(st, 0, 0);
;     mma(1);
;     pat_rd();
;     if (kt + 1 < nk) glds(kt + 1, (kt + 1) & 1);
;     ldfrag(st, 1, 1);
;     mma(0);
;     pat_rd();
;     ldfrag(st, 2, 0);
;     mma(1);
;     pat_rd();
;     ldfrag(st, 3, 1);
;     mma(0);
;     pat_rd();
;     asm volatile("s_waitcnt vmcnt(0)" ::: "memory");
;     __syncthreads();
;   }
;   mma(1);
	s_waitcnt lgkmcnt(0)
	v_mfma_f32_32x32x16_bf16 v[114:129], v[162:165], v[130:133], v[114:129]
	v_mfma_f32_32x32x16_bf16 v[82:97], v[162:165], v[146:149], v[82:97]
	v_mfma_f32_32x32x16_bf16 v[114:129], v[166:169], v[134:137], v[114:129]
	v_mfma_f32_32x32x16_bf16 v[82:97], v[166:169], v[150:153], v[82:97]
	v_mfma_f32_32x32x16_bf16 v[114:129], v[170:173], v[138:141], v[114:129]
	v_mfma_f32_32x32x16_bf16 v[82:97], v[170:173], v[154:157], v[82:97]
	v_mfma_f32_32x32x16_bf16 v[114:129], v[174:177], v[142:145], v[114:129]
	v_mfma_f32_32x32x16_bf16 v[82:97], v[174:177], v[158:161], v[82:97]
	s_barrier
	s_add_u32 m0, s100, 0x18000
	v_add_u32_e32 v244, s10, v246
	v_add_u32_e32 v245, s10, v247
	ds_read_b128 v[180:183], v244 offset:49152
	ds_read_b128 v[186:189], v245 offset:49152
	v_add_u32_e32 v244, s10, v248
	v_add_u32_e32 v245, s10, v249
	ds_read_b128 v[190:193], v244 offset:49152
	ds_read_b128 v[194:197], v245 offset:49152
	global_load_lds_dwordx4 v236, s[8:9]
	s_add_u32 m0, s100, 0x1a000
	v_add_u32_e32 v236, 0x80, v236
	global_load_lds_dwordx4 v238, s[8:9]
	v_add_u32_e32 v238, 0x80, v238
	s_barrier
	s_waitcnt lgkmcnt(0)
	v_mfma_f32_32x32x16_bf16 v[98:113], v[180:183], v[130:133], v[98:113]
	v_mfma_f32_32x32x16_bf16 v[66:81], v[180:183], v[146:149], v[66:81]
	v_mfma_f32_32x32x16_bf16 v[98:113], v[186:189], v[134:137], v[98:113]
	v_mfma_f32_32x32x16_bf16 v[66:81], v[186:189], v[150:153], v[66:81]
	v_mfma_f32_32x32x16_bf16 v[98:113], v[190:193], v[138:141], v[98:113]
	v_mfma_f32_32x32x16_bf16 v[66:81], v[190:193], v[154:157], v[66:81]
	v_mfma_f32_32x32x16_bf16 v[98:113], v[194:197], v[142:145], v[98:113]
	v_mfma_f32_32x32x16_bf16 v[66:81], v[194:197], v[158:161], v[66:81]
	s_barrier
	s_add_u32 m0, s100, 0x10000
	v_add_u32_e32 v244, s10, v240
	v_add_u32_e32 v245, s10, v241
	ds_read_b128 v[130:133], v244 offset:16384
	ds_read_b128 v[134:137], v245 offset:16384
	ds_read_b128 v[146:149], v244 offset:20480
	ds_read_b128 v[150:153], v245 offset:20480
	v_add_u32_e32 v244, s10, v242
	v_add_u32_e32 v245, s10, v243
	ds_read_b128 v[138:141], v244 offset:16384
	ds_read_b128 v[142:145], v245 offset:16384
	ds_read_b128 v[154:157], v244 offset:20480
	ds_read_b128 v[158:161], v245 offset:20480
	global_load_lds_dwordx4 v232, s[6:7]
	s_add_u32 m0, s100, 0x12000
	v_add_u32_e32 v232, 0x80, v232
	global_load_lds_dwordx4 v234, s[6:7]
	v_add_u32_e32 v234, 0x80, v234
	s_waitcnt vmcnt(10)
	s_barrier
	s_waitcnt lgkmcnt(0)
	v_mfma_f32_32x32x16_bf16 v[50:65], v[162:165], v[130:133], v[50:65]
	v_mfma_f32_32x32x16_bf16 v[18:33], v[162:165], v[146:149], v[18:33]
	v_mfma_f32_32x32x16_bf16 v[50:65], v[166:169], v[134:137], v[50:65]
	v_mfma_f32_32x32x16_bf16 v[18:33], v[166:169], v[150:153], v[18:33]
	v_mfma_f32_32x32x16_bf16 v[50:65], v[170:173], v[138:141], v[50:65]
	v_mfma_f32_32x32x16_bf16 v[18:33], v[170:173], v[154:157], v[18:33]
	v_mfma_f32_32x32x16_bf16 v[50:65], v[174:177], v[142:145], v[50:65]
	v_mfma_f32_32x32x16_bf16 v[18:33], v[174:177], v[158:161], v[18:33]
	s_barrier
	s_add_u32 m0, s100, 0x1c000
	ds_read_b128 v[162:165], v246 offset:32768
	ds_read_b128 v[166:169], v247 offset:32768
	ds_read_b128 v[170:173], v248 offset:32768
	ds_read_b128 v[174:177], v249 offset:32768
	global_load_lds_dwordx4 v237, s[8:9]
	s_add_u32 m0, s100, 0x1e000
	v_add_u32_e32 v237, 0x80, v237
	global_load_lds_dwordx4 v239, s[8:9]
	v_add_u32_e32 v239, 0x80, v239
	s_waitcnt vmcnt(6)
	s_barrier
	s_waitcnt lgkmcnt(0)
	v_mfma_f32_32x32x16_bf16 v[34:49], v[180:183], v[130:133], v[34:49]
	v_mfma_f32_32x32x16_bf16 v[2:17], v[180:183], v[146:149], v[2:17]
	v_mfma_f32_32x32x16_bf16 v[34:49], v[186:189], v[134:137], v[34:49]
	v_mfma_f32_32x32x16_bf16 v[2:17], v[186:189], v[150:153], v[2:17]
	v_mfma_f32_32x32x16_bf16 v[34:49], v[190:193], v[138:141], v[34:49]
	v_mfma_f32_32x32x16_bf16 v[2:17], v[190:193], v[154:157], v[2:17]
	v_mfma_f32_32x32x16_bf16 v[34:49], v[194:197], v[142:145], v[34:49]
	v_mfma_f32_32x32x16_bf16 v[2:17], v[194:197], v[158:161], v[2:17]
	s_add_i32 s11, s11, 2
	s_cmp_lt_u32 s11, s25
	s_barrier
	s_cbranch_scc1 .Lg8_m246
	ds_read_b128 v[130:133], v240
	ds_read_b128 v[134:137], v241
	ds_read_b128 v[138:141], v242
	ds_read_b128 v[142:145], v243
	ds_read_b128 v[146:149], v240 offset:4096
	ds_read_b128 v[150:153], v241 offset:4096
	ds_read_b128 v[154:157], v242 offset:4096
	ds_read_b128 v[158:161], v243 offset:4096
	s_add_u32 m0, s100, 0x14000
	s_nop 0
	global_load_lds_dwordx4 v233, s[6:7]
	s_add_u32 m0, s100, 0x16000
	v_add_u32_e32 v233, 0x80, v233
	global_load_lds_dwordx4 v235, s[6:7]
	v_add_u32_e32 v235, 0x80, v235
	s_barrier
	s_waitcnt lgkmcnt(0)
	v_mfma_f32_32x32x16_bf16 v[114:129], v[162:165], v[130:133], v[114:129]
	v_mfma_f32_32x32x16_bf16 v[82:97], v[162:165], v[146:149], v[82:97]
	v_mfma_f32_32x32x16_bf16 v[114:129], v[166:169], v[134:137], v[114:129]
	v_mfma_f32_32x32x16_bf16 v[82:97], v[166:169], v[150:153], v[82:97]
	v_mfma_f32_32x32x16_bf16 v[114:129], v[170:173], v[138:141], v[114:129]
	v_mfma_f32_32x32x16_bf16 v[82:97], v[170:173], v[154:157], v[82:97]
	v_mfma_f32_32x32x16_bf16 v[114:129], v[174:177], v[142:145], v[114:129]
	v_mfma_f32_32x32x16_bf16 v[82:97], v[174:177], v[158:161], v[82:97]
	s_barrier
	ds_read_b128 v[180:183], v246 offset:49152
	ds_read_b128 v[186:189], v247 offset:49152
	ds_read_b128 v[190:193], v248 offset:49152
	ds_read_b128 v[194:197], v249 offset:49152
	s_barrier
; template <bool SWAP>
; DI void gemm_mainloop(f32x16 (&acc)[4][2], const u16* __restrict__ A, int lda, int rlo, int rhi,
;                       const u16* __restrict__ B, int ldb, int K, char* lds, const u16* zero_line) {
;     ...
; #pragma unroll 2
;   for (int kt = 0; kt < nk; ++kt) {
;     const char* st = lds + (kt & 1) * 65536;
;     ldfrag(st, 0, 0);
;     mma(1);
;     pat_rd();
;     if (kt + 1 < nk) glds(kt + 1, (kt + 1) & 1);
;     ldfrag(st, 1, 1);
;     mma(0);
;     pat_rd();
;     ldfrag(st, 2, 0);
;     mma(1);
;     pat_rd();
;     ldfrag(st, 3, 1);
;     mma(0);
;     pat_rd();
;     asm volatile("s_waitcnt vmcnt(0)" ::: "memory");
;     __syncthreads();
;   }
;   mma(1);
	s_waitcnt lgkmcnt(0)
	v_mfma_f32_32x32x16_bf16 v[98:113], v[180:183], v[130:133], v[98:113]
	v_mfma_f32_32x32x16_bf16 v[66:81], v[180:183], v[146:149], v[66:81]
	v_mfma_f32_32x32x16_bf16 v[98:113], v[186:189], v[134:137], v[98:113]
	v_mfma_f32_32x32x16_bf16 v[66:81], v[186:189], v[150:153], v[66:81]
	v_mfma_f32_32x32x16_bf16 v[98:113], v[190:193], v[138:141], v[98:113]
	v_mfma_f32_32x32x16_bf16 v[66:81], v[190:193], v[154:157], v[66:81]
	v_mfma_f32_32x32x16_bf16 v[98:113], v[194:197], v[142:145], v[98:113]
	v_mfma_f32_32x32x16_bf16 v[66:81], v[194:197], v[158:161], v[66:81]
	s_barrier
	ds_read_b128 v[130:133], v240 offset:16384
	ds_read_b128 v[134:137], v241 offset:16384
	ds_read_b128 v[138:141], v242 offset:16384
	ds_read_b128 v[142:145], v243 offset:16384
	ds_read_b128 v[146:149], v240 offset:20480
	ds_read_b128 v[150:153], v241 offset:20480
	ds_read_b128 v[154:157], v242 offset:20480
	ds_read_b128 v[158:161], v243 offset:20480
	s_waitcnt vmcnt(4)
	s_barrier
	s_waitcnt lgkmcnt(0)
	v_mfma_f32_32x32x16_bf16 v[50:65], v[162:165], v[130:133], v[50:65]
	v_mfma_f32_32x32x16_bf16 v[18:33], v[162:165], v[146:149], v[18:33]
	v_mfma_f32_32x32x16_bf16 v[50:65], v[166:169], v[134:137], v[50:65]
	v_mfma_f32_32x32x16_bf16 v[18:33], v[166:169], v[150:153], v[18:33]
	v_mfma_f32_32x32x16_bf16 v[50:65], v[170:173], v[138:141], v[50:65]
	v_mfma_f32_32x32x16_bf16 v[18:33], v[170:173], v[154:157], v[18:33]
	v_mfma_f32_32x32x16_bf16 v[50:65], v[174:177], v[142:145], v[50:65]
	v_mfma_f32_32x32x16_bf16 v[18:33], v[174:177], v[158:161], v[18:33]
	v_mfma_f32_32x32x16_bf16 v[34:49], v[180:183], v[130:133], v[34:49]
	v_mfma_f32_32x32x16_bf16 v[2:17], v[180:183], v[146:149], v[2:17]
	v_mfma_f32_32x32x16_bf16 v[34:49], v[186:189], v[134:137], v[34:49]
	v_mfma_f32_32x32x16_bf16 v[2:17], v[186:189], v[150:153], v[2:17]
	v_mfma_f32_32x32x16_bf16 v[34:49], v[190:193], v[138:141], v[34:49]
	v_mfma_f32_32x32x16_bf16 v[2:17], v[190:193], v[154:157], v[2:17]
	v_mfma_f32_32x32x16_bf16 v[34:49], v[194:197], v[142:145], v[34:49]
	v_mfma_f32_32x32x16_bf16 v[2:17], v[194:197], v[158:161], v[2:17]
	s_barrier
	v_add_u32_e32 v244, s10, v246
	v_add_u32_e32 v245, s10, v247
	ds_read_b128 v[162:165], v244 offset:32768
	ds_read_b128 v[166:169], v245 offset:32768
	v_add_u32_e32 v244, s10, v248
	v_add_u32_e32 v245, s10, v249
	ds_read_b128 v[170:173], v244 offset:32768
	ds_read_b128 v[174:177], v245 offset:32768
	v_add_u32_e32 v244, s10, v240
	v_add_u32_e32 v245, s10, v241
	ds_read_b128 v[130:133], v244
	ds_read_b128 v[134:137], v245
	ds_read_b128 v[146:149], v244 offset:4096
	ds_read_b128 v[150:153], v245 offset:4096
	v_add_u32_e32 v244, s10, v242
	v_add_u32_e32 v245, s10, v243
	ds_read_b128 v[138:141], v244
	ds_read_b128 v[142:145], v245
	ds_read_b128 v[154:157], v244 offset:4096
	ds_read_b128 v[158:161], v245 offset:4096
	s_waitcnt vmcnt(2)
	s_barrier
	s_waitcnt lgkmcnt(0)
	v_mfma_f32_32x32x16_bf16 v[114:129], v[162:165], v[130:133], v[114:129]
	v_mfma_f32_32x32x16_bf16 v[82:97], v[162:165], v[146:149], v[82:97]
	v_mfma_f32_32x32x16_bf16 v[114:129], v[166:169], v[134:137], v[114:129]
	v_mfma_f32_32x32x16_bf16 v[82:97], v[166:169], v[150:153], v[82:97]
	v_mfma_f32_32x32x16_bf16 v[114:129], v[170:173], v[138:141], v[114:129]
	v_mfma_f32_32x32x16_bf16 v[82:97], v[170:173], v[154:157], v[82:97]
	v_mfma_f32_32x32x16_bf16 v[114:129], v[174:177], v[142:145], v[114:129]
	v_mfma_f32_32x32x16_bf16 v[82:97], v[174:177], v[158:161], v[82:97]
	s_barrier
	v_add_u32_e32 v244, s10, v246
	v_add_u32_e32 v245, s10, v247
	ds_read_b128 v[180:183], v244 offset:49152
	ds_read_b128 v[186:189], v245 offset:49152
	v_add_u32_e32 v244, s10, v248
	v_add_u32_e32 v245, s10, v249
	ds_read_b128 v[190:193], v244 offset:49152
	ds_read_b128 v[194:197], v245 offset:49152
	s_waitcnt vmcnt(0)
	s_barrier
	s_waitcnt lgkmcnt(0)
	v_mfma_f32_32x32x16_bf16 v[98:113], v[180:183], v[130:133], v[98:113]
	v_mfma_f32_32x32x16_bf16 v[66:81], v[180:183], v[146:149], v[66:81]
	v_mfma_f32_32x32x16_bf16 v[98:113], v[186:189], v[134:137], v[98:113]
	v_mfma_f32_32x32x16_bf16 v[66:81], v[186:189], v[150:153], v[66:81]
	v_mfma_f32_32x32x16_bf16 v[98:113], v[190:193], v[138:141], v[98:113]
	v_mfma_f32_32x32x16_bf16 v[66:81], v[190:193], v[154:157], v[66:81]
	v_mfma_f32_32x32x16_bf16 v[98:113], v[194:197], v[142:145], v[98:113]
	v_mfma_f32_32x32x16_bf16 v[66:81], v[194:197], v[158:161], v[66:81]
	s_barrier
	v_add_u32_e32 v244, s10, v240
	v_add_u32_e32 v245, s10, v241
	ds_read_b128 v[130:133], v244 offset:16384
	ds_read_b128 v[134:137], v245 offset:16384
	ds_read_b128 v[146:149], v244 offset:20480
	ds_read_b128 v[150:153], v245 offset:20480
	v_add_u32_e32 v244, s10, v242
	v_add_u32_e32 v245, s10, v243
	ds_read_b128 v[138:141], v244 offset:16384
	ds_read_b128 v[142:145], v245 offset:16384
	ds_read_b128 v[154:157], v244 offset:20480
	ds_read_b128 v[158:161], v245 offset:20480
	s_barrier
	s_waitcnt lgkmcnt(0)
	v_mfma_f32_32x32x16_bf16 v[50:65], v[162:165], v[130:133], v[50:65]
	v_mfma_f32_32x32x16_bf16 v[18:33], v[162:165], v[146:149], v[18:33]
	v_mfma_f32_32x32x16_bf16 v[50:65], v[166:169], v[134:137], v[50:65]
	v_mfma_f32_32x32x16_bf16 v[18:33], v[166:169], v[150:153], v[18:33]
	v_mfma_f32_32x32x16_bf16 v[50:65], v[170:173], v[138:141], v[50:65]
	v_mfma_f32_32x32x16_bf16 v[18:33], v[170:173], v[154:157], v[18:33]
	v_mfma_f32_32x32x16_bf16 v[50:65], v[174:177], v[142:145], v[50:65]
	v_mfma_f32_32x32x16_bf16 v[18:33], v[174:177], v[158:161], v[18:33]
	v_mfma_f32_32x32x16_bf16 v[34:49], v[180:183], v[130:133], v[34:49]
	v_mfma_f32_32x32x16_bf16 v[2:17], v[180:183], v[146:149], v[2:17]
	v_mfma_f32_32x32x16_bf16 v[34:49], v[186:189], v[134:137], v[34:49]
	v_mfma_f32_32x32x16_bf16 v[2:17], v[186:189], v[150:153], v[2:17]
	v_mfma_f32_32x32x16_bf16 v[34:49], v[190:193], v[138:141], v[34:49]
	v_mfma_f32_32x32x16_bf16 v[2:17], v[190:193], v[154:157], v[2:17]
	v_mfma_f32_32x32x16_bf16 v[34:49], v[194:197], v[142:145], v[34:49]
	v_mfma_f32_32x32x16_bf16 v[2:17], v[194:197], v[158:161], v[2:17]
	s_barrier
	s_cmp_eq_u32 s101, 0
	s_cbranch_scc0 .Lg8_m246_p1
	s_barrier

; DI int opaque_tid() { int t = threadIdx.x; asm volatile("" : "+v"(t)); return t; }
; template <bool SWAP>
; DI void gemm_mainloop(f32x16 (&acc)[4][2], const u16* __restrict__ A, int lda, int rlo, int rhi,
;                       const u16* __restrict__ B, int ldb, int K, char* lds, const u16* zero_line) {
;   const int tid = opaque_tid(), lane = tid & 63, w = tid >> 6;
;   const int wm = w >> 2, wn = w & 3;
;   const int h = lane >> 5, r = lane & 31;
;   const int lr = tid >> 3, lc = tid & 7;
; #pragma unroll
;   for (int mi = 0; mi < 4; ++mi)
; #pragma unroll
;     for (int ni = 0; ni < 2; ++ni)
; #pragma unroll
;       for (int i = 0; i < 16; ++i) acc[mi][ni][i] = 0.f;
;   const int gch = (lc ^ ((lr >> 1) & 7)) * 8;
;   const u16* ap = A + (ptrdiff_t)lr * lda + gch;
;   const u16* bp = B + (ptrdiff_t)lr * ldb + gch;
;   const int nk = K >> 6;
;   typedef __attribute__((address_space(3))) unsigned lds_u32;
;   auto glds = [&](int kt, int st) {
;     char* as_ = lds + st * 65536 + tid * 16;
; #pragma unroll
;     for (int i = 0; i < 4; ++i) {
;       const int rr = lr + 64 * i;
;       const u16* srca = (rr >= rlo && rr < rhi) ? (ap + (ptrdiff_t)(64 * i) * lda + kt * 64) : (zero_line + lc * 8);
; template <int EPI>
; DI void phase_gemm(const Params& p, const GemmArgs& ga, char* lds) {
;     ...
;   for (int it = 0; it * (int)gridDim.x < total; ++it) {
;     const int lt = logical_index(it);
;     if (lt >= total) continue;
;     int mt, nt;
;     tile_mn(lt, Mt, ga.Nt, mt, nt);
;     int bb, tokbase, S, pos0, rlo = 0, rhi = 256;
;     if (EPI == EPI_UP) {
;       bb = 0; tokbase = 0; S = NTOK;
;       pos0 = 254 * mt - 1;
;       rlo = (mt == 0) ? 1 : 0;
;       rhi = NTOK - pos0; if (rhi > 256) rhi = 256;
;     } else {
;       seq_of_token(mt * 256, bb, tokbase, S);
;       pos0 = mt * 256 - tokbase;
;     }
;     const u16* A = ga.A + (ptrdiff_t)(tokbase + pos0) * ga.lda;
;     const u16* B = ga.Bt + (size_t)(nt * 256) * ga.K;
;     f32x16 acc[4][2];
;     bool swap;
;     if (EPI == EPI_M) swap = true;
;     else if (EPI == EPI_UP) swap = true;
;     else if (EPI == EPI_QKV1) swap = (nt < 8);
;     else swap = !(nt == 4 || nt == 5);
;     if (swap) gemm_mainloop<true>(acc, A, ga.lda, rlo, rhi, B, ga.K, ga.K, lds, (const u16*)(p.ws + OFF_ZERO));
;     else gemm_mainloop<false>(acc, A, ga.lda, rlo, rhi, B, ga.K, ga.K, lds, (const u16*)(p.ws + OFF_ZERO));
.LBB0_315:
	s_add_i32 s6, s6, s25
	s_cmpk_gt_i32 s6, 0x6bf
	s_cbranch_scc1 .LBB0_314
	s_mul_hi_i32 s7, s6, 0x38e38e39
	s_lshr_b32 s8, s7, 31
	s_ashr_i32 s29, s7, 4
	s_add_i32 s29, s29, s8
	s_mul_i32 s7, s29, 0xffffffb8
	s_add_i32 s6, s7, s6
	s_ashr_i32 s8, s6, 31
	s_lshr_b32 s8, s8, 29
	s_lshl_b32 s7, s29, 3
	s_add_i32 s8, s6, s8
	s_add_i32 s6, s6, s7
	s_and_b32 s30, s8, -8
	s_sub_i32 s28, s6, s30
	s_lshl_b32 s12, s28, 8
	s_ashr_i32 s13, s12, 31
	s_ashr_i32 s9, s8, 3
	s_lshl_b64 s[6:7], s[12:13], 11
	s_add_u32 s14, s90, s6
	s_addc_u32 s15, s91, s7
	s_lshl_b32 s16, s9, 8
	s_ashr_i32 s17, s16, 31
	s_lshl_b64 s[6:7], s[16:17], 11
	s_add_u32 s20, s70, s6
	s_addc_u32 s21, s71, s7
	s_and_b32 s6, s9, -2
	s_cmp_lg_u32 s6, 4
	s_cselect_b64 s[18:19], -1, 0
	s_cmp_eq_u32 s6, 4
	s_mov_b64 s[6:7], -1
	s_cbranch_scc1 .LBB0_322
	s_waitcnt vmcnt(5)
	v_mov_b32_e32 v10, v204
	s_nop 0
	v_ashrrev_i32_e32 v2, 3, v10
	v_lshrrev_b32_e32 v13, 1, v2
	v_xor_b32_e32 v0, v13, v10
	v_ashrrev_i32_e32 v3, 31, v2
	v_lshlrev_b64 v[4:5], 11, v[2:3]
	v_lshlrev_b32_e32 v0, 4, v0
	v_and_b32_e32 v12, 31, v10
	v_lshl_add_u64 v[6:7], s[14:15], 0, v[4:5]
	v_and_b32_e32 v0, 0x70, v0
	v_lshl_add_u64 v[8:9], s[20:21], 0, v[4:5]
	s_waitcnt vmcnt(4)
	v_lshrrev_b32_e32 v14, 1, v10
	v_lshl_add_u64 v[6:7], v[6:7], 0, v[0:1]
	v_lshl_add_u64 v[164:165], v[8:9], 0, v[0:1]
	v_and_or_b32 v0, v14, s51, v12
	v_lshlrev_b32_e32 v161, 7, v0
	v_lshlrev_b32_e32 v0, 7, v10
	v_lshlrev_b32_e32 v174, 4, v10
	v_and_b32_e32 v163, 0x6f80, v0
	v_and_b32_e32 v0, 0x70, v174
	v_add_u32_e32 v175, 0x8000, v174
	v_lshl_add_u64 v[166:167], s[80:81], 0, v[0:1]
	v_cmp_gt_u32_e32 vcc, s50, v2
	v_readfirstlane_b32 s6, v174
	s_mov_b32 m0, s6
	v_cndmask_b32_e32 v9, v167, v7, vcc
	v_cndmask_b32_e32 v8, v166, v6, vcc
	v_readfirstlane_b32 s6, v175
	v_add_u32_e32 v0, 64, v2
	s_barrier
	s_mov_b32 m0, s6
	s_mov_b64 s[10:11], 0x20000
	v_cmp_gt_u32_e64 s[6:7], s50, v0
	v_add_u32_e32 v0, 0x2000, v174
	v_lshl_add_u64 v[8:9], v[6:7], 0, s[10:11]
	v_readfirstlane_b32 s8, v0
	v_add_u32_e32 v176, 0xa000, v174
	v_cndmask_b32_e64 v9, v167, v9, s[6:7]
	v_cndmask_b32_e64 v8, v166, v8, s[6:7]
	s_mov_b32 m0, s8
	v_readfirstlane_b32 s8, v176
	v_lshl_add_u64 v[8:9], v[164:165], 0, s[10:11]
	s_mov_b32 m0, s8
	v_add_u32_e32 v3, 0x80, v2
	s_mov_b64 s[22:23], 0x40000
	v_add_u32_e32 v177, 0x4000, v174
	v_lshl_add_u64 v[8:9], v[6:7], 0, s[22:23]
	v_cmp_gt_u32_e64 s[8:9], s50, v3
	v_readfirstlane_b32 s10, v177
	v_add_u32_e32 v178, 0xc000, v174
	v_cndmask_b32_e64 v9, v167, v9, s[8:9]
	v_cndmask_b32_e64 v8, v166, v8, s[8:9]
	s_mov_b32 m0, s10
	v_readfirstlane_b32 s10, v178
	v_lshl_add_u64 v[8:9], v[164:165], 0, s[22:23]
	s_mov_b32 m0, s10
	s_mov_b64 s[22:23], 0x60000
	v_add_u32_e32 v8, 0xc0, v2
	v_add_u32_e32 v179, 0x6000, v174
	v_lshl_add_u64 v[2:3], v[6:7], 0, s[22:23]
	v_cmp_gt_u32_e64 s[10:11], s50, v8
	v_readfirstlane_b32 s17, v179
	v_add_u32_e32 v180, 0xe000, v174
	v_cndmask_b32_e64 v3, v167, v3, s[10:11]
	v_cndmask_b32_e64 v2, v166, v2, s[10:11]
	s_mov_b32 m0, s17
	v_readfirstlane_b32 s17, v180
	v_lshl_add_u64 v[2:3], v[164:165], 0, s[22:23]
	s_mov_b32 m0, s17
	v_bfe_u32 v11, v10, 5, 1
	s_sub_i32 s17, s26, s30
	s_lshl_b32 s22, s29, 6
	v_bfe_u32 v15, v10, 1, 3
	v_bitop3_b32 v2, v14, v11, 7 bitop3:0x6c
	s_sub_i32 s17, s17, s22
	v_lshlrev_b32_e32 v181, 4, v2
	v_bitop3_b32 v2, v11, v15, 2 bitop3:0x36
	s_lshl_b32 s22, s17, 8
	v_lshlrev_b32_e32 v182, 4, v2
	v_bitop3_b32 v2, v11, v15, 4 bitop3:0x36
	s_ashr_i32 s23, s22, 31
	v_lshlrev_b32_e32 v183, 4, v2
	v_bitop3_b32 v2, v11, v15, 6 bitop3:0x36
	s_lshl_b64 s[22:23], s[22:23], 11
	v_lshlrev_b32_e32 v186, 4, v2
	v_lshl_add_u64 v[2:3], v[4:5], 0, s[22:23]
	v_bitop3_b32 v4, v13, 7, v10 bitop3:0x48
	s_waitcnt vmcnt(0)
	v_lshl_or_b32 v2, v4, 4, v2
	v_lshl_add_u64 v[168:169], s[70:71], 0, v[2:3]
	v_mov_b32_e32 v130, 0
	v_mov_b32_e32 v2, 0
	s_mov_b32 s13, 1
	v_add_u32_e32 v187, 0x10000, v174
	v_add_u32_e32 v192, 0x18000, v174
	v_add_u32_e32 v193, 0x12000, v174
	v_add_u32_e32 v194, 0x1a000, v174
	v_add_u32_e32 v195, 0x14000, v174
	v_add_u32_e32 v196, 0x1c000, v174
	v_add_u32_e32 v197, 0x16000, v174
	v_add_u32_e32 v198, 0x1e000, v174
	v_add_u32_e32 v199, 0x10000, v161
	v_or_b32_e32 v200, 0x10000, v163
	s_mov_b64 s[22:23], 0
	v_mov_b32_e32 v3, v2
	v_mov_b32_e32 v4, v2
	v_mov_b32_e32 v5, v2
	v_mov_b32_e32 v6, v2
	v_mov_b32_e32 v7, v2
	v_mov_b32_e32 v8, v2
	v_mov_b32_e32 v9, v2
	v_mov_b32_e32 v10, v2
	v_mov_b32_e32 v11, v2
	v_mov_b32_e32 v12, v2
	v_mov_b32_e32 v13, v2
	v_mov_b32_e32 v14, v2
	v_mov_b32_e32 v15, v2
	v_mov_b32_e32 v16, v2
	v_mov_b32_e32 v17, v2
	v_mov_b32_e32 v34, v2
	v_mov_b32_e32 v35, v2
	v_mov_b32_e32 v36, v2
	v_mov_b32_e32 v37, v2
	v_mov_b32_e32 v38, v2
	v_mov_b32_e32 v39, v2
	v_mov_b32_e32 v40, v2
	v_mov_b32_e32 v41, v2
	v_mov_b32_e32 v42, v2
	v_mov_b32_e32 v43, v2
	v_mov_b32_e32 v44, v2
	v_mov_b32_e32 v45, v2
	v_mov_b32_e32 v46, v2
	v_mov_b32_e32 v47, v2
	v_mov_b32_e32 v48, v2
	v_mov_b32_e32 v49, v2
	s_waitcnt vmcnt(0)
; template <bool SWAP>
; DI void gemm_mainloop(f32x16 (&acc)[4][2], const u16* __restrict__ A, int lda, int rlo, int rhi,
;                       const u16* __restrict__ B, int ldb, int K, char* lds, const u16* zero_line) {
;     ...
; #pragma unroll
;   for (int mi = 0; mi < 4; ++mi)
; #pragma unroll
;     for (int ni = 0; ni < 2; ++ni)
; #pragma unroll
;       for (int i = 0; i < 16; ++i) acc[mi][ni][i] = 0.f;
;   const int gch = (lc ^ ((lr >> 1) & 7)) * 8;
;   const u16* ap = A + (ptrdiff_t)lr * lda + gch;
;   const u16* bp = B + (ptrdiff_t)lr * ldb + gch;
;   const int nk = K >> 6;
;   typedef __attribute__((address_space(3))) unsigned lds_u32;
;   auto glds = [&](int kt, int st) {
;     char* as_ = lds + st * 65536 + tid * 16;
; #pragma unroll
;     for (int i = 0; i < 4; ++i) {
;       const int rr = lr + 64 * i;
;       const u16* srca = (rr >= rlo && rr < rhi) ? (ap + (ptrdiff_t)(64 * i) * lda + kt * 64) : (zero_line + lc * 8);
;       __builtin_amdgcn_global_load_lds((const unsigned*)srca, (lds_u32*)(as_ + i * 8192), 16, 0, 0);
;       __builtin_amdgcn_global_load_lds((const unsigned*)(bp + (ptrdiff_t)(64 * i) * ldb + kt * 64), (lds_u32*)(as_ + 32768 + i * 8192), 16, 0, 0);
;     }
;   };
;   const int sw = (r >> 1) & 7;
;   const int arow_off = (wm * 128 + r) * 128;
;   const int brow_off = 32768 + (wn * 64 + r) * 128;
;   __syncthreads();
;   glds(0, 0);
;   asm volatile("s_waitcnt vmcnt(0)" ::: "memory");
;   __syncthreads();
	v_mov_b32_e32 v18, v2
	v_mov_b32_e32 v19, v2
	v_mov_b32_e32 v20, v2
	v_mov_b32_e32 v21, v2
	v_mov_b32_e32 v22, v2
	v_mov_b32_e32 v23, v2
	v_mov_b32_e32 v24, v2
	v_mov_b32_e32 v25, v2
	v_mov_b32_e32 v26, v2
	v_mov_b32_e32 v27, v2
	v_mov_b32_e32 v28, v2
	v_mov_b32_e32 v29, v2
	v_mov_b32_e32 v30, v2
	v_mov_b32_e32 v31, v2
	v_mov_b32_e32 v32, v2
	v_mov_b32_e32 v33, v2
	v_mov_b32_e32 v66, v2
	v_mov_b32_e32 v67, v2
	v_mov_b32_e32 v68, v2
	v_mov_b32_e32 v69, v2
	v_mov_b32_e32 v70, v2
	v_mov_b32_e32 v71, v2
	v_mov_b32_e32 v72, v2
	v_mov_b32_e32 v73, v2
	v_mov_b32_e32 v74, v2
	v_mov_b32_e32 v75, v2
	v_mov_b32_e32 v76, v2
	v_mov_b32_e32 v77, v2
	v_mov_b32_e32 v78, v2
	v_mov_b32_e32 v79, v2
	v_mov_b32_e32 v80, v2
	v_mov_b32_e32 v81, v2
	v_mov_b32_e32 v50, v2
	v_mov_b32_e32 v51, v2
	v_mov_b32_e32 v52, v2
	v_mov_b32_e32 v53, v2
	v_mov_b32_e32 v54, v2
	v_mov_b32_e32 v55, v2
	v_mov_b32_e32 v56, v2
	v_mov_b32_e32 v57, v2
	v_mov_b32_e32 v58, v2
	v_mov_b32_e32 v59, v2
	v_mov_b32_e32 v60, v2
	v_mov_b32_e32 v61, v2
	v_mov_b32_e32 v62, v2
	v_mov_b32_e32 v63, v2
	v_mov_b32_e32 v64, v2
	v_mov_b32_e32 v65, v2
	v_mov_b32_e32 v98, v2
	v_mov_b32_e32 v99, v2
	v_mov_b32_e32 v100, v2
	v_mov_b32_e32 v101, v2
	v_mov_b32_e32 v102, v2
	v_mov_b32_e32 v103, v2
	v_mov_b32_e32 v104, v2
	v_mov_b32_e32 v105, v2
	v_mov_b32_e32 v106, v2
	v_mov_b32_e32 v107, v2
	v_mov_b32_e32 v108, v2
	v_mov_b32_e32 v109, v2
	v_mov_b32_e32 v110, v2
	v_mov_b32_e32 v111, v2
	v_mov_b32_e32 v112, v2
	v_mov_b32_e32 v113, v2
	v_mov_b32_e32 v82, v2
	v_mov_b32_e32 v83, v2
	v_mov_b32_e32 v84, v2
	v_mov_b32_e32 v85, v2
	v_mov_b32_e32 v86, v2
	v_mov_b32_e32 v87, v2
	v_mov_b32_e32 v88, v2
	v_mov_b32_e32 v89, v2
	v_mov_b32_e32 v90, v2
	v_mov_b32_e32 v91, v2
	v_mov_b32_e32 v92, v2
	v_mov_b32_e32 v93, v2
	v_mov_b32_e32 v94, v2
	v_mov_b32_e32 v95, v2
	v_mov_b32_e32 v96, v2
	v_mov_b32_e32 v97, v2
	v_mov_b32_e32 v114, v2
	v_mov_b32_e32 v115, v2
	v_mov_b32_e32 v116, v2
	v_mov_b32_e32 v117, v2
	v_mov_b32_e32 v118, v2
	v_mov_b32_e32 v119, v2
	v_mov_b32_e32 v120, v2
	v_mov_b32_e32 v121, v2
	v_mov_b32_e32 v122, v2
	v_mov_b32_e32 v123, v2
	v_mov_b32_e32 v124, v2
	v_mov_b32_e32 v125, v2
	v_mov_b32_e32 v126, v2
	v_mov_b32_e32 v127, v2
	v_mov_b32_e32 v128, v2
	v_mov_b32_e32 v129, v2
	v_mov_b32_e32 v131, v130
	v_mov_b32_e32 v132, v130
	v_mov_b32_e32 v133, v130
	v_mov_b32_e32 v134, v130
	v_mov_b32_e32 v135, v130
	v_mov_b32_e32 v136, v130
	v_mov_b32_e32 v137, v130
	v_mov_b32_e32 v138, v130
	v_mov_b32_e32 v139, v130
	v_mov_b32_e32 v140, v130
	v_mov_b32_e32 v141, v130
	v_mov_b32_e32 v146, v130
	v_mov_b32_e32 v147, v130
	v_mov_b32_e32 v148, v130
	v_mov_b32_e32 v149, v130
	v_mov_b32_e32 v142, v130
	v_mov_b32_e32 v143, v130
	v_mov_b32_e32 v144, v130
	v_mov_b32_e32 v145, v130
	v_mov_b32_e32 v150, v130
	v_mov_b32_e32 v151, v130
	v_mov_b32_e32 v152, v130
	v_mov_b32_e32 v153, v130
	s_waitcnt lgkmcnt(0)
	s_barrier
	s_ashr_i32 s7, s12, 31
	s_mov_b32 s6, s12
	s_lshl_b64 s[6:7], s[6:7], 11
	s_add_u32 s6, s90, s6
	s_addc_u32 s7, s91, s7
	s_ashr_i32 s9, s16, 31
	s_mov_b32 s8, s16
	s_lshl_b64 s[8:9], s[8:9], 11
	s_add_u32 s8, s70, s8
	s_addc_u32 s9, s71, s9
	v_and_b32_e32 v130, 63, v204
	v_lshrrev_b32_e32 v131, 6, v204
	v_lshrrev_b32_e32 v132, 3, v204
	v_lshrrev_b32_e32 v0, 4, v130
	v_lshl_add_u32 v0, v131, 2, v0
	v_xor_b32_e32 v0, v0, v130
	v_and_b32_e32 v0, 7, v0
	v_lshlrev_b32_e32 v133, 4, v0
	v_lshl_add_u32 v240, v132, 11, v133
	v_add_u32_e32 v241, 0x20000, v240
	v_add_u32_e32 v242, 0x40000, v240
	v_add_u32_e32 v243, 0x60000, v240
	v_and_b32_e32 v0, 31, v132
	v_lshrrev_b32_e32 v130, 5, v132
	v_lshl_add_u32 v0, v130, 6, v0
	v_lshl_add_u32 v244, v0, 11, v133
	v_add_u32_e32 v245, 0x10000, v244
	v_add_u32_e32 v246, 0x40000, v244
	v_add_u32_e32 v247, 0x50000, v244
	v_and_b32_e32 v132, 31, v204
	v_lshrrev_b32_e32 v0, 2, v131
	v_lshl_add_u32 v0, v0, 6, v132
	v_lshlrev_b32_e32 v166, 7, v0
	v_and_b32_e32 v0, 3, v131
	v_lshl_add_u32 v0, v0, 5, v132
	v_lshlrev_b32_e32 v249, 7, v0
	v_bfe_u32 v0, v204, 5, 1
	v_bfe_u32 v130, v132, 1, 3
	v_or_b32_e32 v133, 0, v0
	v_xor_b32_e32 v133, v133, v130
	v_lshlrev_b32_e32 v161, 4, v133
	v_or_b32_e32 v133, 2, v0
	v_xor_b32_e32 v133, v133, v130
	v_lshlrev_b32_e32 v163, 4, v133
	v_or_b32_e32 v133, 4, v0
	v_xor_b32_e32 v133, v133, v130
	v_lshlrev_b32_e32 v164, 4, v133
	v_or_b32_e32 v133, 6, v0
	v_xor_b32_e32 v133, v133, v130
	v_lshlrev_b32_e32 v165, 4, v133
	v_add_u32_e32 v248, v249, v161
	v_add_u32_e32 v186, v249, v163
	v_add_u32_e32 v187, v249, v164
	v_add_u32_e32 v249, v249, v165
	v_add_u32_e32 v161, v166, v161
	v_add_u32_e32 v163, v166, v163
	v_add_u32_e32 v164, v166, v164
	v_add_u32_e32 v165, v166, v165
	v_lshlrev_b32_e32 v131, 10, v131
	s_nop 0
	v_readfirstlane_b32 s100, v131
	v_mov_b32_e32 v146, 0
	v_mov_b32_e32 v147, 0
	v_mov_b32_e32 v148, 0
	v_mov_b32_e32 v149, 0
	v_lshlrev_b32_e32 v130, 4, v204
	v_add_u32_e32 v132, 0x10000, v130
	s_mov_b64 exec, -1
	s_mov_b32 s11, 0
	s_mov_b32 s10, 0x10000
	s_waitcnt lgkmcnt(0)
	s_add_u32 m0, s100, 0x8000
	s_nop 0
	global_load_lds_dwordx4 v244, s[8:9]
	s_add_u32 m0, s100, 0xa000
	v_add_u32_e32 v244, 0x80, v244
	global_load_lds_dwordx4 v246, s[8:9]
	v_add_u32_e32 v246, 0x80, v246
	s_add_u32 m0, s100, 0x0
	s_nop 0
	global_load_lds_dwordx4 v240, s[6:7]
	s_add_u32 m0, s100, 0x2000
	v_add_u32_e32 v240, 0x80, v240
	global_load_lds_dwordx4 v242, s[6:7]
	v_add_u32_e32 v242, 0x80, v242
	s_add_u32 m0, s100, 0xc000
	s_nop 0
	global_load_lds_dwordx4 v245, s[8:9]
	s_add_u32 m0, s100, 0xe000
	v_add_u32_e32 v245, 0x80, v245
	global_load_lds_dwordx4 v247, s[8:9]
	v_add_u32_e32 v247, 0x80, v247
	s_add_u32 m0, s100, 0x4000
	s_nop 0
	global_load_lds_dwordx4 v241, s[6:7]
	s_add_u32 m0, s100, 0x6000
	v_add_u32_e32 v241, 0x80, v241
	global_load_lds_dwordx4 v243, s[6:7]
	v_add_u32_e32 v243, 0x80, v243
	s_cmp_eq_u32 s101, 1
	s_cbranch_scc0 .Lg8_ia_p0
	s_barrier
; #define MFMA(a, b, c) __builtin_amdgcn_mfma_f32_32x32x16_bf16((a), (b), (c), 0, 0, 0)
; template <bool SWAP>
; DI void gemm_mainloop(f32x16 (&acc)[4][2], const u16* __restrict__ A, int lda, int rlo, int rhi,
;                       const u16* __restrict__ B, int ldb, int K, char* lds, const u16* zero_line) {
;     ...
;   auto ldfrag = [&](const char* st, int ks, int buf) {
;     const int co = ((2 * ks + h) ^ sw) << 4;
; #pragma unroll
;     for (int mi = 0; mi < 4; ++mi) fa[buf][mi] = *(const bf16x8*)(st + arow_off + mi * 4096 + co);
; #pragma unroll
;     for (int ni = 0; ni < 2; ++ni) fb[buf][ni] = *(const bf16x8*)(st + brow_off + ni * 4096 + co);
;   };
;   auto mma = [&](int buf) {
; #pragma unroll
;     for (int mi = 0; mi < 4; ++mi)
; #pragma unroll
;       for (int ni = 0; ni < 2; ++ni)
;         acc[mi][ni] = SWAP ? MFMA(fb[buf][ni], fa[buf][mi], acc[mi][ni]) : MFMA(fa[buf][mi], fb[buf][ni], acc[mi][ni]);
;   };
;   auto pat_rd = [&]() {
; #pragma unroll
;     for (int g = 0; g < 6; ++g) {
;       __builtin_amdgcn_sched_group_barrier(0x100, 1, 0);
;       __builtin_amdgcn_sched_group_barrier(0x008, 1, 0);
;     }
;     __builtin_amdgcn_sched_group_barrier(0x008, 2, 0);
;   };
; #pragma unroll 2
;   for (int kt = 0; kt < nk; ++kt) {
;     const char* st = lds + (kt & 1) * 65536;
;     ldfrag(st, 0, 0);
;     mma(1);
;     pat_rd();
;     if (kt + 1 < nk) glds(kt + 1, (kt + 1) & 1);
;     ldfrag(st, 1, 1);
;     mma(0);
;     pat_rd();
;     ldfrag(st, 2, 0);
;     mma(1);
;     pat_rd();
;     ldfrag(st, 3, 1);
;     mma(0);
;     pat_rd();
;     asm volatile("s_waitcnt vmcnt(0)" ::: "memory");
;     __syncthreads();
;   }
.Lg8_ia_p0:
	s_waitcnt vmcnt(4)
	s_barrier
	s_add_u32 m0, s100, 0x18000
	s_nop 0
	global_load_lds_dwordx4 v244, s[8:9]
	s_add_u32 m0, s100, 0x1a000
	v_add_u32_e32 v244, 0x80, v244
	global_load_lds_dwordx4 v246, s[8:9]
	v_add_u32_e32 v246, 0x80, v246
	s_add_u32 m0, s100, 0x10000
	s_nop 0
	global_load_lds_dwordx4 v240, s[6:7]
	s_add_u32 m0, s100, 0x12000
	v_add_u32_e32 v240, 0x80, v240
	global_load_lds_dwordx4 v242, s[6:7]
	v_add_u32_e32 v242, 0x80, v242
	s_add_u32 m0, s100, 0x1c000
	s_nop 0
	global_load_lds_dwordx4 v245, s[8:9]
	s_add_u32 m0, s100, 0x1e000
	v_add_u32_e32 v245, 0x80, v245
	global_load_lds_dwordx4 v247, s[8:9]
	v_add_u32_e32 v247, 0x80, v247
	s_waitcnt vmcnt(6)
	s_barrier
	ds_read_b128 v[176:179], v248 offset:32768
	ds_read_b128 v[180:183], v186 offset:32768
	ds_read_b128 v[192:195], v187 offset:32768
	ds_read_b128 v[196:199], v249 offset:32768
.Lg8_ia:
	s_add_u32 m0, s100, 0x14000
	ds_read_b128 v[130:133], v161
	ds_read_b128 v[134:137], v163
	ds_read_b128 v[138:141], v164
	ds_read_b128 v[142:145], v165
	ds_read_b128 v[146:149], v161 offset:4096
	ds_read_b128 v[150:153], v163 offset:4096
	ds_read_b128 v[168:171], v164 offset:4096
	ds_read_b128 v[172:175], v165 offset:4096
	global_load_lds_dwordx4 v241, s[6:7]
	s_add_u32 m0, s100, 0x16000
	v_add_u32_e32 v241, 0x80, v241
	global_load_lds_dwordx4 v243, s[6:7]
	v_add_u32_e32 v243, 0x80, v243
	s_barrier
	s_waitcnt lgkmcnt(0)
	v_mfma_f32_32x32x16_bf16 v[114:129], v[176:179], v[130:133], v[114:129]
	v_mfma_f32_32x32x16_bf16 v[98:113], v[176:179], v[146:149], v[98:113]
	v_mfma_f32_32x32x16_bf16 v[114:129], v[180:183], v[134:137], v[114:129]
	v_mfma_f32_32x32x16_bf16 v[98:113], v[180:183], v[150:153], v[98:113]
	v_mfma_f32_32x32x16_bf16 v[114:129], v[192:195], v[138:141], v[114:129]
	v_mfma_f32_32x32x16_bf16 v[98:113], v[192:195], v[168:171], v[98:113]
	v_mfma_f32_32x32x16_bf16 v[114:129], v[196:199], v[142:145], v[114:129]
	v_mfma_f32_32x32x16_bf16 v[98:113], v[196:199], v[172:175], v[98:113]
	s_barrier
	s_add_u32 m0, s100, 0x8000
	ds_read_b128 v[200:203], v248 offset:49152
	ds_read_b128 v[228:231], v186 offset:49152
	ds_read_b128 v[232:235], v187 offset:49152
	ds_read_b128 v[236:239], v249 offset:49152
	global_load_lds_dwordx4 v244, s[8:9]
	s_add_u32 m0, s100, 0xa000
	v_add_u32_e32 v244, 0x80, v244
	global_load_lds_dwordx4 v246, s[8:9]
	v_add_u32_e32 v246, 0x80, v246
	s_barrier
	s_waitcnt lgkmcnt(0)
	v_mfma_f32_32x32x16_bf16 v[82:97], v[200:203], v[130:133], v[82:97]
	v_mfma_f32_32x32x16_bf16 v[50:65], v[200:203], v[146:149], v[50:65]
	v_mfma_f32_32x32x16_bf16 v[82:97], v[228:231], v[134:137], v[82:97]
	v_mfma_f32_32x32x16_bf16 v[50:65], v[228:231], v[150:153], v[50:65]
	v_mfma_f32_32x32x16_bf16 v[82:97], v[232:235], v[138:141], v[82:97]
	v_mfma_f32_32x32x16_bf16 v[50:65], v[232:235], v[168:171], v[50:65]
	v_mfma_f32_32x32x16_bf16 v[82:97], v[236:239], v[142:145], v[82:97]
	v_mfma_f32_32x32x16_bf16 v[50:65], v[236:239], v[172:175], v[50:65]
	s_barrier
	s_add_u32 m0, s100, 0x0
	ds_read_b128 v[130:133], v161 offset:16384
	ds_read_b128 v[134:137], v163 offset:16384
	ds_read_b128 v[138:141], v164 offset:16384
	ds_read_b128 v[142:145], v165 offset:16384
	ds_read_b128 v[146:149], v161 offset:20480
	ds_read_b128 v[150:153], v163 offset:20480
	ds_read_b128 v[168:171], v164 offset:20480
	ds_read_b128 v[172:175], v165 offset:20480
	global_load_lds_dwordx4 v240, s[6:7]
	s_add_u32 m0, s100, 0x2000
	v_add_u32_e32 v240, 0x80, v240
	global_load_lds_dwordx4 v242, s[6:7]
	v_add_u32_e32 v242, 0x80, v242
	s_waitcnt vmcnt(10)
	s_barrier
	s_waitcnt lgkmcnt(0)
	v_mfma_f32_32x32x16_bf16 v[66:81], v[176:179], v[130:133], v[66:81]
	v_mfma_f32_32x32x16_bf16 v[34:49], v[176:179], v[146:149], v[34:49]
	v_mfma_f32_32x32x16_bf16 v[66:81], v[180:183], v[134:137], v[66:81]
	v_mfma_f32_32x32x16_bf16 v[34:49], v[180:183], v[150:153], v[34:49]
	v_mfma_f32_32x32x16_bf16 v[66:81], v[192:195], v[138:141], v[66:81]
	v_mfma_f32_32x32x16_bf16 v[34:49], v[192:195], v[168:171], v[34:49]
	v_mfma_f32_32x32x16_bf16 v[66:81], v[196:199], v[142:145], v[66:81]
	v_mfma_f32_32x32x16_bf16 v[34:49], v[196:199], v[172:175], v[34:49]
	s_barrier
	s_add_u32 m0, s100, 0xc000
	v_add_u32_e32 v166, s10, v248
	ds_read_b128 v[176:179], v166 offset:32768
	v_add_u32_e32 v166, s10, v186
	ds_read_b128 v[180:183], v166 offset:32768
	v_add_u32_e32 v166, s10, v187
	ds_read_b128 v[192:195], v166 offset:32768
	v_add_u32_e32 v166, s10, v249
	ds_read_b128 v[196:199], v166 offset:32768
	global_load_lds_dwordx4 v245, s[8:9]
	s_add_u32 m0, s100, 0xe000
	v_add_u32_e32 v245, 0x80, v245
	global_load_lds_dwordx4 v247, s[8:9]
	v_add_u32_e32 v247, 0x80, v247
	s_waitcnt vmcnt(6)
	s_barrier
	s_waitcnt lgkmcnt(0)
	v_mfma_f32_32x32x16_bf16 v[18:33], v[200:203], v[130:133], v[18:33]
	v_mfma_f32_32x32x16_bf16 v[2:17], v[200:203], v[146:149], v[2:17]
	v_mfma_f32_32x32x16_bf16 v[18:33], v[228:231], v[134:137], v[18:33]
	v_mfma_f32_32x32x16_bf16 v[2:17], v[228:231], v[150:153], v[2:17]
	v_mfma_f32_32x32x16_bf16 v[18:33], v[232:235], v[138:141], v[18:33]
	v_mfma_f32_32x32x16_bf16 v[2:17], v[232:235], v[168:171], v[2:17]
	v_mfma_f32_32x32x16_bf16 v[18:33], v[236:239], v[142:145], v[18:33]
	v_mfma_f32_32x32x16_bf16 v[2:17], v[236:239], v[172:175], v[2:17]
	s_barrier
	s_add_u32 m0, s100, 0x4000
	v_add_u32_e32 v166, s10, v161
	ds_read_b128 v[130:133], v166
	ds_read_b128 v[146:149], v166 offset:4096
	v_add_u32_e32 v166, s10, v163
	ds_read_b128 v[134:137], v166
	ds_read_b128 v[150:153], v166 offset:4096
	v_add_u32_e32 v166, s10, v164
	ds_read_b128 v[138:141], v166
	ds_read_b128 v[168:171], v166 offset:4096
	v_add_u32_e32 v166, s10, v165
	ds_read_b128 v[142:145], v166
	ds_read_b128 v[172:175], v166 offset:4096
	global_load_lds_dwordx4 v241, s[6:7]
	s_add_u32 m0, s100, 0x6000
	v_add_u32_e32 v241, 0x80, v241
	global_load_lds_dwordx4 v243, s[6:7]
	v_add_u32_e32 v243, 0x80, v243
	s_barrier
; #define MFMA(a, b, c) __builtin_amdgcn_mfma_f32_32x32x16_bf16((a), (b), (c), 0, 0, 0)
; template <bool SWAP>
; DI void gemm_mainloop(f32x16 (&acc)[4][2], const u16* __restrict__ A, int lda, int rlo, int rhi,
;                       const u16* __restrict__ B, int ldb, int K, char* lds, const u16* zero_line) {
;     ...
;   auto ldfrag = [&](const char* st, int ks, int buf) {
;     const int co = ((2 * ks + h) ^ sw) << 4;
; #pragma unroll
;     for (int mi = 0; mi < 4; ++mi) fa[buf][mi] = *(const bf16x8*)(st + arow_off + mi * 4096 + co);
; #pragma unroll
;     for (int ni = 0; ni < 2; ++ni) fb[buf][ni] = *(const bf16x8*)(st + brow_off + ni * 4096 + co);
;   };
;   auto mma = [&](int buf) {
; #pragma unroll
;     for (int mi = 0; mi < 4; ++mi)
; #pragma unroll
;       for (int ni = 0; ni < 2; ++ni)
;         acc[mi][ni] = SWAP ? MFMA(fb[buf][ni], fa[buf][mi], acc[mi][ni]) : MFMA(fa[buf][mi], fb[buf][ni], acc[mi][ni]);
;   };
;   auto pat_rd = [&]() {
; #pragma unroll
;     for (int g = 0; g < 6; ++g) {
;       __builtin_amdgcn_sched_group_barrier(0x100, 1, 0);
;       __builtin_amdgcn_sched_group_barrier(0x008, 1, 0);
;     }
;     __builtin_amdgcn_sched_group_barrier(0x008, 2, 0);
;   };
; #pragma unroll 2
;   for (int kt = 0; kt < nk; ++kt) {
;     const char* st = lds + (kt & 1) * 65536;
;     ldfrag(st, 0, 0);
;     mma(1);
;     pat_rd();
;     if (kt + 1 < nk) glds(kt + 1, (kt + 1) & 1);
;     ldfrag(st, 1, 1);
;     mma(0);
;     pat_rd();
;     ldfrag(st, 2, 0);
;     mma(1);
;     pat_rd();
;     ldfrag(st, 3, 1);
;     mma(0);
;     pat_rd();
;     asm volatile("s_waitcnt vmcnt(0)" ::: "memory");
;     __syncthreads();
;   }
;   mma(1);
	s_waitcnt lgkmcnt(0)
	v_mfma_f32_32x32x16_bf16 v[114:129], v[176:179], v[130:133], v[114:129]
	v_mfma_f32_32x32x16_bf16 v[98:113], v[176:179], v[146:149], v[98:113]
	v_mfma_f32_32x32x16_bf16 v[114:129], v[180:183], v[134:137], v[114:129]
	v_mfma_f32_32x32x16_bf16 v[98:113], v[180:183], v[150:153], v[98:113]
	v_mfma_f32_32x32x16_bf16 v[114:129], v[192:195], v[138:141], v[114:129]
	v_mfma_f32_32x32x16_bf16 v[98:113], v[192:195], v[168:171], v[98:113]
	v_mfma_f32_32x32x16_bf16 v[114:129], v[196:199], v[142:145], v[114:129]
	v_mfma_f32_32x32x16_bf16 v[98:113], v[196:199], v[172:175], v[98:113]
	s_barrier
	s_add_u32 m0, s100, 0x18000
	v_add_u32_e32 v166, s10, v248
	ds_read_b128 v[200:203], v166 offset:49152
	v_add_u32_e32 v166, s10, v186
	ds_read_b128 v[228:231], v166 offset:49152
	v_add_u32_e32 v166, s10, v187
	ds_read_b128 v[232:235], v166 offset:49152
	v_add_u32_e32 v166, s10, v249
	ds_read_b128 v[236:239], v166 offset:49152
	global_load_lds_dwordx4 v244, s[8:9]
	s_add_u32 m0, s100, 0x1a000
	v_add_u32_e32 v244, 0x80, v244
	global_load_lds_dwordx4 v246, s[8:9]
	v_add_u32_e32 v246, 0x80, v246
	s_barrier
	s_waitcnt lgkmcnt(0)
	v_mfma_f32_32x32x16_bf16 v[82:97], v[200:203], v[130:133], v[82:97]
	v_mfma_f32_32x32x16_bf16 v[50:65], v[200:203], v[146:149], v[50:65]
	v_mfma_f32_32x32x16_bf16 v[82:97], v[228:231], v[134:137], v[82:97]
	v_mfma_f32_32x32x16_bf16 v[50:65], v[228:231], v[150:153], v[50:65]
	v_mfma_f32_32x32x16_bf16 v[82:97], v[232:235], v[138:141], v[82:97]
	v_mfma_f32_32x32x16_bf16 v[50:65], v[232:235], v[168:171], v[50:65]
	v_mfma_f32_32x32x16_bf16 v[82:97], v[236:239], v[142:145], v[82:97]
	v_mfma_f32_32x32x16_bf16 v[50:65], v[236:239], v[172:175], v[50:65]
	s_barrier
	s_add_u32 m0, s100, 0x10000
	v_add_u32_e32 v166, s10, v161
	ds_read_b128 v[130:133], v166 offset:16384
	ds_read_b128 v[146:149], v166 offset:20480
	v_add_u32_e32 v166, s10, v163
	ds_read_b128 v[134:137], v166 offset:16384
	ds_read_b128 v[150:153], v166 offset:20480
	v_add_u32_e32 v166, s10, v164
	ds_read_b128 v[138:141], v166 offset:16384
	ds_read_b128 v[168:171], v166 offset:20480
	v_add_u32_e32 v166, s10, v165
	ds_read_b128 v[142:145], v166 offset:16384
	ds_read_b128 v[172:175], v166 offset:20480
	global_load_lds_dwordx4 v240, s[6:7]
	s_add_u32 m0, s100, 0x12000
	v_add_u32_e32 v240, 0x80, v240
	global_load_lds_dwordx4 v242, s[6:7]
	v_add_u32_e32 v242, 0x80, v242
	s_waitcnt vmcnt(10)
	s_barrier
	s_waitcnt lgkmcnt(0)
	v_mfma_f32_32x32x16_bf16 v[66:81], v[176:179], v[130:133], v[66:81]
	v_mfma_f32_32x32x16_bf16 v[34:49], v[176:179], v[146:149], v[34:49]
	v_mfma_f32_32x32x16_bf16 v[66:81], v[180:183], v[134:137], v[66:81]
	v_mfma_f32_32x32x16_bf16 v[34:49], v[180:183], v[150:153], v[34:49]
	v_mfma_f32_32x32x16_bf16 v[66:81], v[192:195], v[138:141], v[66:81]
	v_mfma_f32_32x32x16_bf16 v[34:49], v[192:195], v[168:171], v[34:49]
	v_mfma_f32_32x32x16_bf16 v[66:81], v[196:199], v[142:145], v[66:81]
	v_mfma_f32_32x32x16_bf16 v[34:49], v[196:199], v[172:175], v[34:49]
	s_barrier
	s_add_u32 m0, s100, 0x1c000
	ds_read_b128 v[176:179], v248 offset:32768
	ds_read_b128 v[180:183], v186 offset:32768
	ds_read_b128 v[192:195], v187 offset:32768
	ds_read_b128 v[196:199], v249 offset:32768
	global_load_lds_dwordx4 v245, s[8:9]
	s_add_u32 m0, s100, 0x1e000
	v_add_u32_e32 v245, 0x80, v245
	global_load_lds_dwordx4 v247, s[8:9]
	v_add_u32_e32 v247, 0x80, v247
	s_waitcnt vmcnt(6)
	s_barrier
	s_waitcnt lgkmcnt(0)
	v_mfma_f32_32x32x16_bf16 v[18:33], v[200:203], v[130:133], v[18:33]
	v_mfma_f32_32x32x16_bf16 v[2:17], v[200:203], v[146:149], v[2:17]
	v_mfma_f32_32x32x16_bf16 v[18:33], v[228:231], v[134:137], v[18:33]
	v_mfma_f32_32x32x16_bf16 v[2:17], v[228:231], v[150:153], v[2:17]
	v_mfma_f32_32x32x16_bf16 v[18:33], v[232:235], v[138:141], v[18:33]
	v_mfma_f32_32x32x16_bf16 v[2:17], v[232:235], v[168:171], v[2:17]
	v_mfma_f32_32x32x16_bf16 v[18:33], v[236:239], v[142:145], v[18:33]
	v_mfma_f32_32x32x16_bf16 v[2:17], v[236:239], v[172:175], v[2:17]
	s_add_i32 s11, s11, 2
	s_cmp_lt_u32 s11, 14
	s_barrier
	s_cbranch_scc1 .Lg8_ia
	ds_read_b128 v[130:133], v161
	ds_read_b128 v[134:137], v163
	ds_read_b128 v[138:141], v164
	ds_read_b128 v[142:145], v165
	ds_read_b128 v[146:149], v161 offset:4096
	ds_read_b128 v[150:153], v163 offset:4096
	ds_read_b128 v[168:171], v164 offset:4096
	ds_read_b128 v[172:175], v165 offset:4096
	s_add_u32 m0, s100, 0x14000
	s_nop 0
	global_load_lds_dwordx4 v241, s[6:7]
	s_add_u32 m0, s100, 0x16000
	v_add_u32_e32 v241, 0x80, v241
	global_load_lds_dwordx4 v243, s[6:7]
	v_add_u32_e32 v243, 0x80, v243
	s_barrier
	s_waitcnt lgkmcnt(0)
	v_mfma_f32_32x32x16_bf16 v[114:129], v[176:179], v[130:133], v[114:129]
	v_mfma_f32_32x32x16_bf16 v[98:113], v[176:179], v[146:149], v[98:113]
	v_mfma_f32_32x32x16_bf16 v[114:129], v[180:183], v[134:137], v[114:129]
	v_mfma_f32_32x32x16_bf16 v[98:113], v[180:183], v[150:153], v[98:113]
	v_mfma_f32_32x32x16_bf16 v[114:129], v[192:195], v[138:141], v[114:129]
	v_mfma_f32_32x32x16_bf16 v[98:113], v[192:195], v[168:171], v[98:113]
	v_mfma_f32_32x32x16_bf16 v[114:129], v[196:199], v[142:145], v[114:129]
	v_mfma_f32_32x32x16_bf16 v[98:113], v[196:199], v[172:175], v[98:113]
	s_barrier
	ds_read_b128 v[200:203], v248 offset:49152
	ds_read_b128 v[228:231], v186 offset:49152
	ds_read_b128 v[232:235], v187 offset:49152
	ds_read_b128 v[236:239], v249 offset:49152
	s_barrier
; template <bool SWAP>
; DI void gemm_mainloop(f32x16 (&acc)[4][2], const u16* __restrict__ A, int lda, int rlo, int rhi,
;                       const u16* __restrict__ B, int ldb, int K, char* lds, const u16* zero_line) {
;     ...
; #pragma unroll 2
;   for (int kt = 0; kt < nk; ++kt) {
;     const char* st = lds + (kt & 1) * 65536;
;     ldfrag(st, 0, 0);
;     mma(1);
;     pat_rd();
;     if (kt + 1 < nk) glds(kt + 1, (kt + 1) & 1);
;     ldfrag(st, 1, 1);
;     mma(0);
;     pat_rd();
;     ldfrag(st, 2, 0);
;     mma(1);
;     pat_rd();
;     ldfrag(st, 3, 1);
;     mma(0);
;     pat_rd();
;     asm volatile("s_waitcnt vmcnt(0)" ::: "memory");
;     __syncthreads();
;   }
;   mma(1);
	s_waitcnt lgkmcnt(0)
	v_mfma_f32_32x32x16_bf16 v[82:97], v[200:203], v[130:133], v[82:97]
	v_mfma_f32_32x32x16_bf16 v[50:65], v[200:203], v[146:149], v[50:65]
	v_mfma_f32_32x32x16_bf16 v[82:97], v[228:231], v[134:137], v[82:97]
	v_mfma_f32_32x32x16_bf16 v[50:65], v[228:231], v[150:153], v[50:65]
	v_mfma_f32_32x32x16_bf16 v[82:97], v[232:235], v[138:141], v[82:97]
	v_mfma_f32_32x32x16_bf16 v[50:65], v[232:235], v[168:171], v[50:65]
	v_mfma_f32_32x32x16_bf16 v[82:97], v[236:239], v[142:145], v[82:97]
	v_mfma_f32_32x32x16_bf16 v[50:65], v[236:239], v[172:175], v[50:65]
	s_barrier
	ds_read_b128 v[130:133], v161 offset:16384
	ds_read_b128 v[134:137], v163 offset:16384
	ds_read_b128 v[138:141], v164 offset:16384
	ds_read_b128 v[142:145], v165 offset:16384
	ds_read_b128 v[146:149], v161 offset:20480
	ds_read_b128 v[150:153], v163 offset:20480
	ds_read_b128 v[168:171], v164 offset:20480
	ds_read_b128 v[172:175], v165 offset:20480
	s_waitcnt vmcnt(4)
	s_barrier
	s_waitcnt lgkmcnt(0)
	v_mfma_f32_32x32x16_bf16 v[66:81], v[176:179], v[130:133], v[66:81]
	v_mfma_f32_32x32x16_bf16 v[34:49], v[176:179], v[146:149], v[34:49]
	v_mfma_f32_32x32x16_bf16 v[66:81], v[180:183], v[134:137], v[66:81]
	v_mfma_f32_32x32x16_bf16 v[34:49], v[180:183], v[150:153], v[34:49]
	v_mfma_f32_32x32x16_bf16 v[66:81], v[192:195], v[138:141], v[66:81]
	v_mfma_f32_32x32x16_bf16 v[34:49], v[192:195], v[168:171], v[34:49]
	v_mfma_f32_32x32x16_bf16 v[66:81], v[196:199], v[142:145], v[66:81]
	v_mfma_f32_32x32x16_bf16 v[34:49], v[196:199], v[172:175], v[34:49]
	v_mfma_f32_32x32x16_bf16 v[18:33], v[200:203], v[130:133], v[18:33]
	v_mfma_f32_32x32x16_bf16 v[2:17], v[200:203], v[146:149], v[2:17]
	v_mfma_f32_32x32x16_bf16 v[18:33], v[228:231], v[134:137], v[18:33]
	v_mfma_f32_32x32x16_bf16 v[2:17], v[228:231], v[150:153], v[2:17]
	v_mfma_f32_32x32x16_bf16 v[18:33], v[232:235], v[138:141], v[18:33]
	v_mfma_f32_32x32x16_bf16 v[2:17], v[232:235], v[168:171], v[2:17]
	v_mfma_f32_32x32x16_bf16 v[18:33], v[236:239], v[142:145], v[18:33]
	v_mfma_f32_32x32x16_bf16 v[2:17], v[236:239], v[172:175], v[2:17]
	s_barrier
	v_add_u32_e32 v166, s10, v248
	ds_read_b128 v[176:179], v166 offset:32768
	v_add_u32_e32 v166, s10, v186
	ds_read_b128 v[180:183], v166 offset:32768
	v_add_u32_e32 v166, s10, v187
	ds_read_b128 v[192:195], v166 offset:32768
	v_add_u32_e32 v166, s10, v249
	ds_read_b128 v[196:199], v166 offset:32768
	v_add_u32_e32 v166, s10, v161
	ds_read_b128 v[130:133], v166
	ds_read_b128 v[146:149], v166 offset:4096
	v_add_u32_e32 v166, s10, v163
	ds_read_b128 v[134:137], v166
	ds_read_b128 v[150:153], v166 offset:4096
	v_add_u32_e32 v166, s10, v164
	ds_read_b128 v[138:141], v166
	ds_read_b128 v[168:171], v166 offset:4096
	v_add_u32_e32 v166, s10, v165
	ds_read_b128 v[142:145], v166
	ds_read_b128 v[172:175], v166 offset:4096
	s_waitcnt vmcnt(2)
	s_barrier
	s_waitcnt lgkmcnt(0)
	v_mfma_f32_32x32x16_bf16 v[114:129], v[176:179], v[130:133], v[114:129]
	v_mfma_f32_32x32x16_bf16 v[98:113], v[176:179], v[146:149], v[98:113]
	v_mfma_f32_32x32x16_bf16 v[114:129], v[180:183], v[134:137], v[114:129]
	v_mfma_f32_32x32x16_bf16 v[98:113], v[180:183], v[150:153], v[98:113]
	v_mfma_f32_32x32x16_bf16 v[114:129], v[192:195], v[138:141], v[114:129]
	v_mfma_f32_32x32x16_bf16 v[98:113], v[192:195], v[168:171], v[98:113]
	v_mfma_f32_32x32x16_bf16 v[114:129], v[196:199], v[142:145], v[114:129]
	v_mfma_f32_32x32x16_bf16 v[98:113], v[196:199], v[172:175], v[98:113]
	s_barrier
	v_add_u32_e32 v166, s10, v248
	ds_read_b128 v[200:203], v166 offset:49152
	v_add_u32_e32 v166, s10, v186
	ds_read_b128 v[228:231], v166 offset:49152
	v_add_u32_e32 v166, s10, v187
	ds_read_b128 v[232:235], v166 offset:49152
	v_add_u32_e32 v166, s10, v249
	ds_read_b128 v[236:239], v166 offset:49152
	s_waitcnt vmcnt(0)
	s_barrier
	s_waitcnt lgkmcnt(0)
	v_mfma_f32_32x32x16_bf16 v[82:97], v[200:203], v[130:133], v[82:97]
	v_mfma_f32_32x32x16_bf16 v[50:65], v[200:203], v[146:149], v[50:65]
	v_mfma_f32_32x32x16_bf16 v[82:97], v[228:231], v[134:137], v[82:97]
	v_mfma_f32_32x32x16_bf16 v[50:65], v[228:231], v[150:153], v[50:65]
	v_mfma_f32_32x32x16_bf16 v[82:97], v[232:235], v[138:141], v[82:97]
	v_mfma_f32_32x32x16_bf16 v[50:65], v[232:235], v[168:171], v[50:65]
	v_mfma_f32_32x32x16_bf16 v[82:97], v[236:239], v[142:145], v[82:97]
	v_mfma_f32_32x32x16_bf16 v[50:65], v[236:239], v[172:175], v[50:65]
	s_barrier
	v_add_u32_e32 v166, s10, v161
	ds_read_b128 v[130:133], v166 offset:16384
	ds_read_b128 v[146:149], v166 offset:20480
	v_add_u32_e32 v166, s10, v163
	ds_read_b128 v[134:137], v166 offset:16384
	ds_read_b128 v[150:153], v166 offset:20480
	v_add_u32_e32 v166, s10, v164
	ds_read_b128 v[138:141], v166 offset:16384
	ds_read_b128 v[168:171], v166 offset:20480
	v_add_u32_e32 v166, s10, v165
	ds_read_b128 v[142:145], v166 offset:16384
	ds_read_b128 v[172:175], v166 offset:20480
	s_barrier
	s_waitcnt lgkmcnt(0)
	v_mfma_f32_32x32x16_bf16 v[66:81], v[176:179], v[130:133], v[66:81]
	v_mfma_f32_32x32x16_bf16 v[34:49], v[176:179], v[146:149], v[34:49]
	v_mfma_f32_32x32x16_bf16 v[66:81], v[180:183], v[134:137], v[66:81]
	v_mfma_f32_32x32x16_bf16 v[34:49], v[180:183], v[150:153], v[34:49]
	v_mfma_f32_32x32x16_bf16 v[66:81], v[192:195], v[138:141], v[66:81]
	v_mfma_f32_32x32x16_bf16 v[34:49], v[192:195], v[168:171], v[34:49]
	v_mfma_f32_32x32x16_bf16 v[66:81], v[196:199], v[142:145], v[66:81]
	v_mfma_f32_32x32x16_bf16 v[34:49], v[196:199], v[172:175], v[34:49]
	v_mfma_f32_32x32x16_bf16 v[18:33], v[200:203], v[130:133], v[18:33]
	v_mfma_f32_32x32x16_bf16 v[2:17], v[200:203], v[146:149], v[2:17]
	v_mfma_f32_32x32x16_bf16 v[18:33], v[228:231], v[134:137], v[18:33]
	v_mfma_f32_32x32x16_bf16 v[2:17], v[228:231], v[150:153], v[2:17]
	v_mfma_f32_32x32x16_bf16 v[18:33], v[232:235], v[138:141], v[18:33]
	v_mfma_f32_32x32x16_bf16 v[2:17], v[232:235], v[168:171], v[2:17]
	v_mfma_f32_32x32x16_bf16 v[18:33], v[236:239], v[142:145], v[18:33]
	v_mfma_f32_32x32x16_bf16 v[2:17], v[236:239], v[172:175], v[2:17]
	s_barrier
	s_cmp_eq_u32 s101, 0
	s_cbranch_scc0 .Lg8_ia_p1
	s_barrier

; DI int opaque_tid() { int t = threadIdx.x; asm volatile("" : "+v"(t)); return t; }
; template <bool SWAP>
; DI void gemm_mainloop(f32x16 (&acc)[4][2], const u16* __restrict__ A, int lda, int rlo, int rhi,
;                       const u16* __restrict__ B, int ldb, int K, char* lds, const u16* zero_line) {
;   const int tid = opaque_tid(), lane = tid & 63, w = tid >> 6;
;   const int wm = w >> 2, wn = w & 3;
;   const int h = lane >> 5, r = lane & 31;
;   const int lr = tid >> 3, lc = tid & 7;
; #pragma unroll
;   for (int mi = 0; mi < 4; ++mi)
; #pragma unroll
;     for (int ni = 0; ni < 2; ++ni)
; #pragma unroll
;       for (int i = 0; i < 16; ++i) acc[mi][ni][i] = 0.f;
;   const int gch = (lc ^ ((lr >> 1) & 7)) * 8;
;   const u16* ap = A + (ptrdiff_t)lr * lda + gch;
;   const u16* bp = B + (ptrdiff_t)lr * ldb + gch;
;   const int nk = K >> 6;
;   typedef __attribute__((address_space(3))) unsigned lds_u32;
;   auto glds = [&](int kt, int st) {
;     char* as_ = lds + st * 65536 + tid * 16;
; #pragma unroll
;     for (int i = 0; i < 4; ++i) {
;       const int rr = lr + 64 * i;
;       const u16* srca = (rr >= rlo && rr < rhi) ? (ap + (ptrdiff_t)(64 * i) * lda + kt * 64) : (zero_line + lc * 8);
;       __builtin_amdgcn_global_load_lds((const unsigned*)srca, (lds_u32*)(as_ + i * 8192), 16, 0, 0);
;       __builtin_amdgcn_global_load_lds((const unsigned*)(bp + (ptrdiff_t)(64 * i) * ldb + kt * 64), (lds_u32*)(as_ + 32768 + i * 8192), 16, 0, 0);
;     }
;   };
;   const int sw = (r >> 1) & 7;
;   const int arow_off = (wm * 128 + r) * 128;
;   const int brow_off = 32768 + (wn * 64 + r) * 128;
;   __syncthreads();
;   glds(0, 0);
;   asm volatile("s_waitcnt vmcnt(0)" ::: "memory");
;   __syncthreads();
.LBB0_322:
	s_and_b64 vcc, exec, s[6:7]
	s_cbranch_vccz .LBB0_328
	s_waitcnt vmcnt(5)
	s_nop 8
	v_mov_b32_e32 v10, v204
	s_nop 0
	v_ashrrev_i32_e32 v2, 3, v10
	v_lshrrev_b32_e32 v13, 1, v2
	v_xor_b32_e32 v0, v13, v10
	v_ashrrev_i32_e32 v3, 31, v2
	v_lshlrev_b64 v[4:5], 11, v[2:3]
	v_lshlrev_b32_e32 v0, 4, v0
	v_and_b32_e32 v12, 31, v10
	v_lshl_add_u64 v[6:7], s[14:15], 0, v[4:5]
	v_and_b32_e32 v0, 0x70, v0
	v_lshl_add_u64 v[8:9], s[20:21], 0, v[4:5]
	s_waitcnt vmcnt(4)
	v_lshrrev_b32_e32 v14, 1, v10
	v_lshl_add_u64 v[6:7], v[6:7], 0, v[0:1]
	v_lshl_add_u64 v[164:165], v[8:9], 0, v[0:1]
	v_and_or_b32 v0, v14, s51, v12
	v_lshlrev_b32_e32 v161, 7, v0
	v_lshlrev_b32_e32 v0, 7, v10
	v_lshlrev_b32_e32 v174, 4, v10
	v_and_b32_e32 v163, 0x6f80, v0
	v_and_b32_e32 v0, 0x70, v174
	v_add_u32_e32 v175, 0x8000, v174
	v_lshl_add_u64 v[166:167], s[80:81], 0, v[0:1]
	v_cmp_gt_u32_e32 vcc, s50, v2
	v_readfirstlane_b32 s6, v174
	s_mov_b32 m0, s6
	v_cndmask_b32_e32 v9, v167, v7, vcc
	v_cndmask_b32_e32 v8, v166, v6, vcc
	v_readfirstlane_b32 s6, v175
	v_add_u32_e32 v0, 64, v2
	s_barrier
	s_mov_b32 m0, s6
	s_mov_b64 s[10:11], 0x20000
	v_cmp_gt_u32_e64 s[6:7], s50, v0
	v_add_u32_e32 v0, 0x2000, v174
	v_lshl_add_u64 v[8:9], v[6:7], 0, s[10:11]
	v_readfirstlane_b32 s8, v0
	v_add_u32_e32 v176, 0xa000, v174
	v_cndmask_b32_e64 v9, v167, v9, s[6:7]
	v_cndmask_b32_e64 v8, v166, v8, s[6:7]
	s_mov_b32 m0, s8
	v_readfirstlane_b32 s8, v176
	v_lshl_add_u64 v[8:9], v[164:165], 0, s[10:11]
	s_mov_b32 m0, s8
	v_add_u32_e32 v3, 0x80, v2
	s_mov_b64 s[14:15], 0x40000
	v_add_u32_e32 v177, 0x4000, v174
	v_lshl_add_u64 v[8:9], v[6:7], 0, s[14:15]
	v_cmp_gt_u32_e64 s[8:9], s50, v3
	v_readfirstlane_b32 s10, v177
	v_add_u32_e32 v178, 0xc000, v174
	v_cndmask_b32_e64 v9, v167, v9, s[8:9]
	v_cndmask_b32_e64 v8, v166, v8, s[8:9]
	s_mov_b32 m0, s10
	v_readfirstlane_b32 s10, v178
	v_lshl_add_u64 v[8:9], v[164:165], 0, s[14:15]
	s_mov_b32 m0, s10
	s_mov_b64 s[20:21], 0x60000
	v_add_u32_e32 v8, 0xc0, v2
	v_add_u32_e32 v179, 0x6000, v174
	v_lshl_add_u64 v[2:3], v[6:7], 0, s[20:21]
	v_cmp_gt_u32_e64 s[10:11], s50, v8
	v_readfirstlane_b32 s14, v179
	v_add_u32_e32 v180, 0xe000, v174
	v_cndmask_b32_e64 v3, v167, v3, s[10:11]
	v_cndmask_b32_e64 v2, v166, v2, s[10:11]
	s_mov_b32 m0, s14
	v_readfirstlane_b32 s14, v180
	v_lshl_add_u64 v[2:3], v[164:165], 0, s[20:21]
	s_mov_b32 m0, s14
	v_bfe_u32 v11, v10, 5, 1
	s_sub_i32 s14, s26, s30
	s_lshl_b32 s15, s29, 6
	v_bfe_u32 v15, v10, 1, 3
	v_bitop3_b32 v2, v14, v11, 7 bitop3:0x6c
	s_sub_i32 s14, s14, s15
	v_lshlrev_b32_e32 v181, 4, v2
	v_bitop3_b32 v2, v11, v15, 2 bitop3:0x36
	s_lshl_b32 s14, s14, 8
	v_lshlrev_b32_e32 v182, 4, v2
	v_bitop3_b32 v2, v11, v15, 4 bitop3:0x36
	s_ashr_i32 s15, s14, 31
	v_lshlrev_b32_e32 v183, 4, v2
	v_bitop3_b32 v2, v11, v15, 6 bitop3:0x36
	s_lshl_b64 s[14:15], s[14:15], 11
	v_lshlrev_b32_e32 v186, 4, v2
	v_lshl_add_u64 v[2:3], v[4:5], 0, s[14:15]
	v_bitop3_b32 v4, v13, 7, v10 bitop3:0x48
	s_waitcnt vmcnt(0)
	v_lshl_or_b32 v2, v4, 4, v2
	v_lshl_add_u64 v[168:169], s[70:71], 0, v[2:3]
	v_mov_b32_e32 v130, 0
	v_mov_b32_e32 v2, 0
	s_mov_b32 s13, 1
	v_add_u32_e32 v187, 0x10000, v174
	v_add_u32_e32 v192, 0x18000, v174
	v_add_u32_e32 v193, 0x12000, v174
	v_add_u32_e32 v194, 0x1a000, v174
	v_add_u32_e32 v195, 0x14000, v174
	v_add_u32_e32 v196, 0x1c000, v174
	v_add_u32_e32 v197, 0x16000, v174
	v_add_u32_e32 v198, 0x1e000, v174
	v_add_u32_e32 v199, 0x10000, v161
	v_or_b32_e32 v200, 0x10000, v163
	s_mov_b64 s[14:15], 0
	v_mov_b32_e32 v3, v2
	v_mov_b32_e32 v4, v2
	v_mov_b32_e32 v5, v2
	v_mov_b32_e32 v6, v2
	v_mov_b32_e32 v7, v2
	v_mov_b32_e32 v8, v2
	v_mov_b32_e32 v9, v2
	v_mov_b32_e32 v10, v2
	v_mov_b32_e32 v11, v2
	v_mov_b32_e32 v12, v2
	v_mov_b32_e32 v13, v2
	v_mov_b32_e32 v14, v2
	v_mov_b32_e32 v15, v2
	v_mov_b32_e32 v16, v2
	v_mov_b32_e32 v17, v2
	v_mov_b32_e32 v34, v2
	v_mov_b32_e32 v35, v2
	v_mov_b32_e32 v36, v2
	v_mov_b32_e32 v37, v2
	v_mov_b32_e32 v38, v2
	v_mov_b32_e32 v39, v2
	v_mov_b32_e32 v40, v2
	v_mov_b32_e32 v41, v2
	v_mov_b32_e32 v42, v2
	v_mov_b32_e32 v43, v2
	v_mov_b32_e32 v44, v2
	v_mov_b32_e32 v45, v2
	v_mov_b32_e32 v46, v2
	v_mov_b32_e32 v47, v2
	v_mov_b32_e32 v48, v2
	v_mov_b32_e32 v49, v2
	s_waitcnt vmcnt(0)
; DI int opaque_tid() { int t = threadIdx.x; asm volatile("" : "+v"(t)); return t; }
; template <bool SWAP>
; DI void gemm_mainloop(f32x16 (&acc)[4][2], const u16* __restrict__ A, int lda, int rlo, int rhi,
;                       const u16* __restrict__ B, int ldb, int K, char* lds, const u16* zero_line) {
;   const int tid = opaque_tid(), lane = tid & 63, w = tid >> 6;
;   const int wm = w >> 2, wn = w & 3;
;   const int h = lane >> 5, r = lane & 31;
;   const int lr = tid >> 3, lc = tid & 7;
; #pragma unroll
;   for (int mi = 0; mi < 4; ++mi)
; #pragma unroll
;     for (int ni = 0; ni < 2; ++ni)
; #pragma unroll
;       for (int i = 0; i < 16; ++i) acc[mi][ni][i] = 0.f;
;   const int gch = (lc ^ ((lr >> 1) & 7)) * 8;
;   const u16* ap = A + (ptrdiff_t)lr * lda + gch;
;   const u16* bp = B + (ptrdiff_t)lr * ldb + gch;
;   const int nk = K >> 6;
;   typedef __attribute__((address_space(3))) unsigned lds_u32;
;   auto glds = [&](int kt, int st) {
;     char* as_ = lds + st * 65536 + tid * 16;
; #pragma unroll
;     for (int i = 0; i < 4; ++i) {
;       const int rr = lr + 64 * i;
;       const u16* srca = (rr >= rlo && rr < rhi) ? (ap + (ptrdiff_t)(64 * i) * lda + kt * 64) : (zero_line + lc * 8);
;       __builtin_amdgcn_global_load_lds((const unsigned*)srca, (lds_u32*)(as_ + i * 8192), 16, 0, 0);
;       __builtin_amdgcn_global_load_lds((const unsigned*)(bp + (ptrdiff_t)(64 * i) * ldb + kt * 64), (lds_u32*)(as_ + 32768 + i * 8192), 16, 0, 0);
;     }
;   };
;   const int sw = (r >> 1) & 7;
;   const int arow_off = (wm * 128 + r) * 128;
;   const int brow_off = 32768 + (wn * 64 + r) * 128;
;   __syncthreads();
;   glds(0, 0);
;   asm volatile("s_waitcnt vmcnt(0)" ::: "memory");
;   __syncthreads();
	v_mov_b32_e32 v18, v2
	v_mov_b32_e32 v19, v2
	v_mov_b32_e32 v20, v2
	v_mov_b32_e32 v21, v2
	v_mov_b32_e32 v22, v2
	v_mov_b32_e32 v23, v2
	v_mov_b32_e32 v24, v2
	v_mov_b32_e32 v25, v2
	v_mov_b32_e32 v26, v2
	v_mov_b32_e32 v27, v2
	v_mov_b32_e32 v28, v2
	v_mov_b32_e32 v29, v2
	v_mov_b32_e32 v30, v2
	v_mov_b32_e32 v31, v2
	v_mov_b32_e32 v32, v2
	v_mov_b32_e32 v33, v2
	v_mov_b32_e32 v66, v2
	v_mov_b32_e32 v67, v2
	v_mov_b32_e32 v68, v2
	v_mov_b32_e32 v69, v2
	v_mov_b32_e32 v70, v2
	v_mov_b32_e32 v71, v2
	v_mov_b32_e32 v72, v2
	v_mov_b32_e32 v73, v2
	v_mov_b32_e32 v74, v2
	v_mov_b32_e32 v75, v2
	v_mov_b32_e32 v76, v2
	v_mov_b32_e32 v77, v2
	v_mov_b32_e32 v78, v2
	v_mov_b32_e32 v79, v2
	v_mov_b32_e32 v80, v2
	v_mov_b32_e32 v81, v2
	v_mov_b32_e32 v50, v2
	v_mov_b32_e32 v51, v2
	v_mov_b32_e32 v52, v2
	v_mov_b32_e32 v53, v2
	v_mov_b32_e32 v54, v2
	v_mov_b32_e32 v55, v2
	v_mov_b32_e32 v56, v2
	v_mov_b32_e32 v57, v2
	v_mov_b32_e32 v58, v2
	v_mov_b32_e32 v59, v2
	v_mov_b32_e32 v60, v2
	v_mov_b32_e32 v61, v2
	v_mov_b32_e32 v62, v2
	v_mov_b32_e32 v63, v2
	v_mov_b32_e32 v64, v2
	v_mov_b32_e32 v65, v2
	v_mov_b32_e32 v98, v2
	v_mov_b32_e32 v99, v2
	v_mov_b32_e32 v100, v2
	v_mov_b32_e32 v101, v2
	v_mov_b32_e32 v102, v2
	v_mov_b32_e32 v103, v2
	v_mov_b32_e32 v104, v2
	v_mov_b32_e32 v105, v2
	v_mov_b32_e32 v106, v2
	v_mov_b32_e32 v107, v2
	v_mov_b32_e32 v108, v2
	v_mov_b32_e32 v109, v2
	v_mov_b32_e32 v110, v2
	v_mov_b32_e32 v111, v2
	v_mov_b32_e32 v112, v2
	v_mov_b32_e32 v113, v2
	v_mov_b32_e32 v82, v2
	v_mov_b32_e32 v83, v2
	v_mov_b32_e32 v84, v2
	v_mov_b32_e32 v85, v2
	v_mov_b32_e32 v86, v2
	v_mov_b32_e32 v87, v2
	v_mov_b32_e32 v88, v2
	v_mov_b32_e32 v89, v2
	v_mov_b32_e32 v90, v2
	v_mov_b32_e32 v91, v2
	v_mov_b32_e32 v92, v2
	v_mov_b32_e32 v93, v2
	v_mov_b32_e32 v94, v2
	v_mov_b32_e32 v95, v2
	v_mov_b32_e32 v96, v2
	v_mov_b32_e32 v97, v2
	v_mov_b32_e32 v114, v2
	v_mov_b32_e32 v115, v2
	v_mov_b32_e32 v116, v2
	v_mov_b32_e32 v117, v2
	v_mov_b32_e32 v118, v2
	v_mov_b32_e32 v119, v2
	v_mov_b32_e32 v120, v2
	v_mov_b32_e32 v121, v2
	v_mov_b32_e32 v122, v2
	v_mov_b32_e32 v123, v2
	v_mov_b32_e32 v124, v2
	v_mov_b32_e32 v125, v2
	v_mov_b32_e32 v126, v2
	v_mov_b32_e32 v127, v2
	v_mov_b32_e32 v128, v2
	v_mov_b32_e32 v129, v2
	v_mov_b32_e32 v131, v130
	v_mov_b32_e32 v132, v130
	v_mov_b32_e32 v133, v130
	v_mov_b32_e32 v134, v130
	v_mov_b32_e32 v135, v130
	v_mov_b32_e32 v136, v130
	v_mov_b32_e32 v137, v130
	v_mov_b32_e32 v138, v130
	v_mov_b32_e32 v139, v130
	v_mov_b32_e32 v140, v130
	v_mov_b32_e32 v141, v130
	v_mov_b32_e32 v146, v130
	v_mov_b32_e32 v147, v130
	v_mov_b32_e32 v148, v130
	v_mov_b32_e32 v149, v130
	v_mov_b32_e32 v142, v130
	v_mov_b32_e32 v143, v130
	v_mov_b32_e32 v144, v130
	v_mov_b32_e32 v145, v130
	v_mov_b32_e32 v150, v130
	v_mov_b32_e32 v151, v130
	v_mov_b32_e32 v152, v130
	v_mov_b32_e32 v153, v130
	s_waitcnt lgkmcnt(0)
	s_barrier
	s_ashr_i32 s7, s12, 31
	s_mov_b32 s6, s12
	s_lshl_b64 s[6:7], s[6:7], 11
	s_add_u32 s6, s90, s6
	s_addc_u32 s7, s91, s7
	s_ashr_i32 s9, s16, 31
	s_mov_b32 s8, s16
	s_lshl_b64 s[8:9], s[8:9], 11
	s_add_u32 s8, s70, s8
	s_addc_u32 s9, s71, s9
	v_and_b32_e32 v130, 63, v204
	v_lshrrev_b32_e32 v131, 6, v204
	v_lshrrev_b32_e32 v132, 3, v204
	v_lshrrev_b32_e32 v0, 4, v130
	v_lshl_add_u32 v0, v131, 2, v0
	v_xor_b32_e32 v0, v0, v130
	v_and_b32_e32 v0, 7, v0
	v_lshlrev_b32_e32 v133, 4, v0
	v_lshl_add_u32 v240, v132, 11, v133
	v_add_u32_e32 v241, 0x20000, v240
	v_add_u32_e32 v242, 0x40000, v240
	v_add_u32_e32 v243, 0x60000, v240
	v_and_b32_e32 v0, 31, v132
	v_lshrrev_b32_e32 v130, 5, v132
	v_lshl_add_u32 v0, v130, 6, v0
	v_lshl_add_u32 v244, v0, 11, v133
	v_add_u32_e32 v245, 0x10000, v244
	v_add_u32_e32 v246, 0x40000, v244
	v_add_u32_e32 v247, 0x50000, v244
	v_and_b32_e32 v132, 31, v204
	v_lshrrev_b32_e32 v0, 2, v131
	v_lshl_add_u32 v0, v0, 6, v132
	v_lshlrev_b32_e32 v166, 7, v0
	v_and_b32_e32 v0, 3, v131
	v_lshl_add_u32 v0, v0, 5, v132
	v_lshlrev_b32_e32 v249, 7, v0
	v_bfe_u32 v0, v204, 5, 1
	v_bfe_u32 v130, v132, 1, 3
	v_or_b32_e32 v133, 0, v0
	v_xor_b32_e32 v133, v133, v130
	v_lshlrev_b32_e32 v161, 4, v133
	v_or_b32_e32 v133, 2, v0
	v_xor_b32_e32 v133, v133, v130
	v_lshlrev_b32_e32 v163, 4, v133
	v_or_b32_e32 v133, 4, v0
	v_xor_b32_e32 v133, v133, v130
	v_lshlrev_b32_e32 v164, 4, v133
	v_or_b32_e32 v133, 6, v0
	v_xor_b32_e32 v133, v133, v130
	v_lshlrev_b32_e32 v165, 4, v133
	v_add_u32_e32 v248, v249, v161
	v_add_u32_e32 v186, v249, v163
	v_add_u32_e32 v187, v249, v164
	v_add_u32_e32 v249, v249, v165
	v_add_u32_e32 v161, v166, v161
	v_add_u32_e32 v163, v166, v163
	v_add_u32_e32 v164, v166, v164
	v_add_u32_e32 v165, v166, v165
	v_lshlrev_b32_e32 v131, 10, v131
	s_nop 0
	v_readfirstlane_b32 s100, v131
	v_mov_b32_e32 v146, 0
	v_mov_b32_e32 v147, 0
	v_mov_b32_e32 v148, 0
	v_mov_b32_e32 v149, 0
	v_lshlrev_b32_e32 v130, 4, v204
	v_add_u32_e32 v132, 0x10000, v130
	s_mov_b64 exec, -1
	s_mov_b32 s11, 0
	s_mov_b32 s10, 0x10000
	s_waitcnt lgkmcnt(0)
	s_add_u32 m0, s100, 0x8000
	s_nop 0
	global_load_lds_dwordx4 v244, s[8:9]
	s_add_u32 m0, s100, 0xa000
	v_add_u32_e32 v244, 0x80, v244
	global_load_lds_dwordx4 v246, s[8:9]
	v_add_u32_e32 v246, 0x80, v246
	s_add_u32 m0, s100, 0x0
	s_nop 0
	global_load_lds_dwordx4 v240, s[6:7]
	s_add_u32 m0, s100, 0x2000
	v_add_u32_e32 v240, 0x80, v240
	global_load_lds_dwordx4 v242, s[6:7]
	v_add_u32_e32 v242, 0x80, v242
	s_add_u32 m0, s100, 0xc000
	s_nop 0
	global_load_lds_dwordx4 v245, s[8:9]
	s_add_u32 m0, s100, 0xe000
	v_add_u32_e32 v245, 0x80, v245
	global_load_lds_dwordx4 v247, s[8:9]
	v_add_u32_e32 v247, 0x80, v247
	s_add_u32 m0, s100, 0x4000
	s_nop 0
	global_load_lds_dwordx4 v241, s[6:7]
	s_add_u32 m0, s100, 0x6000
	v_add_u32_e32 v241, 0x80, v241
	global_load_lds_dwordx4 v243, s[6:7]
	v_add_u32_e32 v243, 0x80, v243
	s_cmp_eq_u32 s101, 1
	s_cbranch_scc0 .Lg8_ib_p0
	s_barrier

; #define MFMA(a, b, c) __builtin_amdgcn_mfma_f32_32x32x16_bf16((a), (b), (c), 0, 0, 0)
; template <bool SWAP>
; DI void gemm_mainloop(f32x16 (&acc)[4][2], const u16* __restrict__ A, int lda, int rlo, int rhi,
;                       const u16* __restrict__ B, int ldb, int K, char* lds, const u16* zero_line) {
;     ...
;   auto ldfrag = [&](const char* st, int ks, int buf) {
;     const int co = ((2 * ks + h) ^ sw) << 4;
; #pragma unroll
;     for (int mi = 0; mi < 4; ++mi) fa[buf][mi] = *(const bf16x8*)(st + arow_off + mi * 4096 + co);
; #pragma unroll
;     for (int ni = 0; ni < 2; ++ni) fb[buf][ni] = *(const bf16x8*)(st + brow_off + ni * 4096 + co);
;   };
;   auto mma = [&](int buf) {
; #pragma unroll
;     for (int mi = 0; mi < 4; ++mi)
; #pragma unroll
;       for (int ni = 0; ni < 2; ++ni)
;         acc[mi][ni] = SWAP ? MFMA(fb[buf][ni], fa[buf][mi], acc[mi][ni]) : MFMA(fa[buf][mi], fb[buf][ni], acc[mi][ni]);
;   };
;   auto pat_rd = [&]() {
; #pragma unroll
;     for (int g = 0; g < 6; ++g) {
;       __builtin_amdgcn_sched_group_barrier(0x100, 1, 0);
;       __builtin_amdgcn_sched_group_barrier(0x008, 1, 0);
;     }
;     __builtin_amdgcn_sched_group_barrier(0x008, 2, 0);
;   };
; #pragma unroll 2
;   for (int kt = 0; kt < nk; ++kt) {
;     const char* st = lds + (kt & 1) * 65536;
;     ldfrag(st, 0, 0);
;     mma(1);
;     pat_rd();
;     if (kt + 1 < nk) glds(kt + 1, (kt + 1) & 1);
;     ldfrag(st, 1, 1);
;     mma(0);
;     pat_rd();
;     ldfrag(st, 2, 0);
;     mma(1);
;     pat_rd();
;     ldfrag(st, 3, 1);
;     mma(0);
;     pat_rd();
;     asm volatile("s_waitcnt vmcnt(0)" ::: "memory");
;     __syncthreads();
.Lg8_ib:
	s_add_u32 m0, s100, 0x14000
	ds_read_b128 v[130:133], v161
	ds_read_b128 v[134:137], v163
	ds_read_b128 v[138:141], v164
	ds_read_b128 v[142:145], v165
	ds_read_b128 v[146:149], v161 offset:4096
	ds_read_b128 v[150:153], v163 offset:4096
	ds_read_b128 v[168:171], v164 offset:4096
	ds_read_b128 v[172:175], v165 offset:4096
	global_load_lds_dwordx4 v241, s[6:7]
	s_add_u32 m0, s100, 0x16000
	v_add_u32_e32 v241, 0x80, v241
	global_load_lds_dwordx4 v243, s[6:7]
	v_add_u32_e32 v243, 0x80, v243
	s_barrier
	s_waitcnt lgkmcnt(0)
	v_mfma_f32_32x32x16_bf16 v[114:129], v[130:133], v[176:179], v[114:129]
	v_mfma_f32_32x32x16_bf16 v[98:113], v[146:149], v[176:179], v[98:113]
	v_mfma_f32_32x32x16_bf16 v[114:129], v[134:137], v[180:183], v[114:129]
	v_mfma_f32_32x32x16_bf16 v[98:113], v[150:153], v[180:183], v[98:113]
	v_mfma_f32_32x32x16_bf16 v[114:129], v[138:141], v[192:195], v[114:129]
	v_mfma_f32_32x32x16_bf16 v[98:113], v[168:171], v[192:195], v[98:113]
	v_mfma_f32_32x32x16_bf16 v[114:129], v[142:145], v[196:199], v[114:129]
	v_mfma_f32_32x32x16_bf16 v[98:113], v[172:175], v[196:199], v[98:113]
	s_barrier
	s_add_u32 m0, s100, 0x8000
	ds_read_b128 v[200:203], v248 offset:49152
	ds_read_b128 v[228:231], v186 offset:49152
	ds_read_b128 v[232:235], v187 offset:49152
	ds_read_b128 v[236:239], v249 offset:49152
	global_load_lds_dwordx4 v244, s[8:9]
	s_add_u32 m0, s100, 0xa000
	v_add_u32_e32 v244, 0x80, v244
	global_load_lds_dwordx4 v246, s[8:9]
	v_add_u32_e32 v246, 0x80, v246
	s_barrier
	s_waitcnt lgkmcnt(0)
	v_mfma_f32_32x32x16_bf16 v[82:97], v[130:133], v[200:203], v[82:97]
	v_mfma_f32_32x32x16_bf16 v[50:65], v[146:149], v[200:203], v[50:65]
	v_mfma_f32_32x32x16_bf16 v[82:97], v[134:137], v[228:231], v[82:97]
	v_mfma_f32_32x32x16_bf16 v[50:65], v[150:153], v[228:231], v[50:65]
	v_mfma_f32_32x32x16_bf16 v[82:97], v[138:141], v[232:235], v[82:97]
	v_mfma_f32_32x32x16_bf16 v[50:65], v[168:171], v[232:235], v[50:65]
	v_mfma_f32_32x32x16_bf16 v[82:97], v[142:145], v[236:239], v[82:97]
	v_mfma_f32_32x32x16_bf16 v[50:65], v[172:175], v[236:239], v[50:65]
	s_barrier
	s_add_u32 m0, s100, 0x0
	ds_read_b128 v[130:133], v161 offset:16384
	ds_read_b128 v[134:137], v163 offset:16384
	ds_read_b128 v[138:141], v164 offset:16384
	ds_read_b128 v[142:145], v165 offset:16384
	ds_read_b128 v[146:149], v161 offset:20480
	ds_read_b128 v[150:153], v163 offset:20480
	ds_read_b128 v[168:171], v164 offset:20480
	ds_read_b128 v[172:175], v165 offset:20480
	global_load_lds_dwordx4 v240, s[6:7]
	s_add_u32 m0, s100, 0x2000
	v_add_u32_e32 v240, 0x80, v240
	global_load_lds_dwordx4 v242, s[6:7]
	v_add_u32_e32 v242, 0x80, v242
	s_waitcnt vmcnt(10)
	s_barrier
	s_waitcnt lgkmcnt(0)
	v_mfma_f32_32x32x16_bf16 v[66:81], v[130:133], v[176:179], v[66:81]
	v_mfma_f32_32x32x16_bf16 v[34:49], v[146:149], v[176:179], v[34:49]
	v_mfma_f32_32x32x16_bf16 v[66:81], v[134:137], v[180:183], v[66:81]
	v_mfma_f32_32x32x16_bf16 v[34:49], v[150:153], v[180:183], v[34:49]
	v_mfma_f32_32x32x16_bf16 v[66:81], v[138:141], v[192:195], v[66:81]
	v_mfma_f32_32x32x16_bf16 v[34:49], v[168:171], v[192:195], v[34:49]
	v_mfma_f32_32x32x16_bf16 v[66:81], v[142:145], v[196:199], v[66:81]
	v_mfma_f32_32x32x16_bf16 v[34:49], v[172:175], v[196:199], v[34:49]
	s_barrier
	s_add_u32 m0, s100, 0xc000
	v_add_u32_e32 v166, s10, v248
	ds_read_b128 v[176:179], v166 offset:32768
	v_add_u32_e32 v166, s10, v186
	ds_read_b128 v[180:183], v166 offset:32768
	v_add_u32_e32 v166, s10, v187
	ds_read_b128 v[192:195], v166 offset:32768
	v_add_u32_e32 v166, s10, v249
	ds_read_b128 v[196:199], v166 offset:32768
	global_load_lds_dwordx4 v245, s[8:9]
	s_add_u32 m0, s100, 0xe000
	v_add_u32_e32 v245, 0x80, v245
	global_load_lds_dwordx4 v247, s[8:9]
	v_add_u32_e32 v247, 0x80, v247
	s_waitcnt vmcnt(6)
	s_barrier
	s_waitcnt lgkmcnt(0)
	v_mfma_f32_32x32x16_bf16 v[18:33], v[130:133], v[200:203], v[18:33]
	v_mfma_f32_32x32x16_bf16 v[2:17], v[146:149], v[200:203], v[2:17]
	v_mfma_f32_32x32x16_bf16 v[18:33], v[134:137], v[228:231], v[18:33]
	v_mfma_f32_32x32x16_bf16 v[2:17], v[150:153], v[228:231], v[2:17]
	v_mfma_f32_32x32x16_bf16 v[18:33], v[138:141], v[232:235], v[18:33]
	v_mfma_f32_32x32x16_bf16 v[2:17], v[168:171], v[232:235], v[2:17]
	v_mfma_f32_32x32x16_bf16 v[18:33], v[142:145], v[236:239], v[18:33]
	v_mfma_f32_32x32x16_bf16 v[2:17], v[172:175], v[236:239], v[2:17]
	s_barrier
	s_add_u32 m0, s100, 0x4000
	v_add_u32_e32 v166, s10, v161
	ds_read_b128 v[130:133], v166
	ds_read_b128 v[146:149], v166 offset:4096
	v_add_u32_e32 v166, s10, v163
	ds_read_b128 v[134:137], v166
	ds_read_b128 v[150:153], v166 offset:4096
	v_add_u32_e32 v166, s10, v164
	ds_read_b128 v[138:141], v166
	ds_read_b128 v[168:171], v166 offset:4096
	v_add_u32_e32 v166, s10, v165
	ds_read_b128 v[142:145], v166
	ds_read_b128 v[172:175], v166 offset:4096
	global_load_lds_dwordx4 v241, s[6:7]
	s_add_u32 m0, s100, 0x6000
	v_add_u32_e32 v241, 0x80, v241
	global_load_lds_dwordx4 v243, s[6:7]
	v_add_u32_e32 v243, 0x80, v243
	s_barrier
	s_waitcnt lgkmcnt(0)
	v_mfma_f32_32x32x16_bf16 v[114:129], v[130:133], v[176:179], v[114:129]
	v_mfma_f32_32x32x16_bf16 v[98:113], v[146:149], v[176:179], v[98:113]
	v_mfma_f32_32x32x16_bf16 v[114:129], v[134:137], v[180:183], v[114:129]
	v_mfma_f32_32x32x16_bf16 v[98:113], v[150:153], v[180:183], v[98:113]
	v_mfma_f32_32x32x16_bf16 v[114:129], v[138:141], v[192:195], v[114:129]
	v_mfma_f32_32x32x16_bf16 v[98:113], v[168:171], v[192:195], v[98:113]
	v_mfma_f32_32x32x16_bf16 v[114:129], v[142:145], v[196:199], v[114:129]
	v_mfma_f32_32x32x16_bf16 v[98:113], v[172:175], v[196:199], v[98:113]
	s_barrier
; template <bool SWAP>
; DI void gemm_mainloop(f32x16 (&acc)[4][2], const u16* __restrict__ A, int lda, int rlo, int rhi,
;                       const u16* __restrict__ B, int ldb, int K, char* lds, const u16* zero_line) {
;     ...
; #pragma unroll 2
;   for (int kt = 0; kt < nk; ++kt) {
;     const char* st = lds + (kt & 1) * 65536;
;     ldfrag(st, 0, 0);
;     mma(1);
;     pat_rd();
;     if (kt + 1 < nk) glds(kt + 1, (kt + 1) & 1);
;     ldfrag(st, 1, 1);
;     mma(0);
;     pat_rd();
;     ldfrag(st, 2, 0);
;     mma(1);
;     pat_rd();
;     ldfrag(st, 3, 1);
;     mma(0);
;     pat_rd();
;     asm volatile("s_waitcnt vmcnt(0)" ::: "memory");
;     __syncthreads();
;   }
;   mma(1);
; }
	s_add_u32 m0, s100, 0x18000
	v_add_u32_e32 v166, s10, v248
	ds_read_b128 v[200:203], v166 offset:49152
	v_add_u32_e32 v166, s10, v186
	ds_read_b128 v[228:231], v166 offset:49152
	v_add_u32_e32 v166, s10, v187
	ds_read_b128 v[232:235], v166 offset:49152
	v_add_u32_e32 v166, s10, v249
	ds_read_b128 v[236:239], v166 offset:49152
	global_load_lds_dwordx4 v244, s[8:9]
	s_add_u32 m0, s100, 0x1a000
	v_add_u32_e32 v244, 0x80, v244
	global_load_lds_dwordx4 v246, s[8:9]
	v_add_u32_e32 v246, 0x80, v246
	s_barrier
	s_waitcnt lgkmcnt(0)
	v_mfma_f32_32x32x16_bf16 v[82:97], v[130:133], v[200:203], v[82:97]
	v_mfma_f32_32x32x16_bf16 v[50:65], v[146:149], v[200:203], v[50:65]
	v_mfma_f32_32x32x16_bf16 v[82:97], v[134:137], v[228:231], v[82:97]
	v_mfma_f32_32x32x16_bf16 v[50:65], v[150:153], v[228:231], v[50:65]
	v_mfma_f32_32x32x16_bf16 v[82:97], v[138:141], v[232:235], v[82:97]
	v_mfma_f32_32x32x16_bf16 v[50:65], v[168:171], v[232:235], v[50:65]
	v_mfma_f32_32x32x16_bf16 v[82:97], v[142:145], v[236:239], v[82:97]
	v_mfma_f32_32x32x16_bf16 v[50:65], v[172:175], v[236:239], v[50:65]
	s_barrier
	s_add_u32 m0, s100, 0x10000
	v_add_u32_e32 v166, s10, v161
	ds_read_b128 v[130:133], v166 offset:16384
	ds_read_b128 v[146:149], v166 offset:20480
	v_add_u32_e32 v166, s10, v163
	ds_read_b128 v[134:137], v166 offset:16384
	ds_read_b128 v[150:153], v166 offset:20480
	v_add_u32_e32 v166, s10, v164
	ds_read_b128 v[138:141], v166 offset:16384
	ds_read_b128 v[168:171], v166 offset:20480
	v_add_u32_e32 v166, s10, v165
	ds_read_b128 v[142:145], v166 offset:16384
	ds_read_b128 v[172:175], v166 offset:20480
	global_load_lds_dwordx4 v240, s[6:7]
	s_add_u32 m0, s100, 0x12000
	v_add_u32_e32 v240, 0x80, v240
	global_load_lds_dwordx4 v242, s[6:7]
	v_add_u32_e32 v242, 0x80, v242
	s_waitcnt vmcnt(10)
	s_barrier
	s_waitcnt lgkmcnt(0)
	v_mfma_f32_32x32x16_bf16 v[66:81], v[130:133], v[176:179], v[66:81]
	v_mfma_f32_32x32x16_bf16 v[34:49], v[146:149], v[176:179], v[34:49]
	v_mfma_f32_32x32x16_bf16 v[66:81], v[134:137], v[180:183], v[66:81]
	v_mfma_f32_32x32x16_bf16 v[34:49], v[150:153], v[180:183], v[34:49]
	v_mfma_f32_32x32x16_bf16 v[66:81], v[138:141], v[192:195], v[66:81]
	v_mfma_f32_32x32x16_bf16 v[34:49], v[168:171], v[192:195], v[34:49]
	v_mfma_f32_32x32x16_bf16 v[66:81], v[142:145], v[196:199], v[66:81]
	v_mfma_f32_32x32x16_bf16 v[34:49], v[172:175], v[196:199], v[34:49]
	s_barrier
	s_add_u32 m0, s100, 0x1c000
	ds_read_b128 v[176:179], v248 offset:32768
	ds_read_b128 v[180:183], v186 offset:32768
	ds_read_b128 v[192:195], v187 offset:32768
	ds_read_b128 v[196:199], v249 offset:32768
	global_load_lds_dwordx4 v245, s[8:9]
	s_add_u32 m0, s100, 0x1e000
	v_add_u32_e32 v245, 0x80, v245
	global_load_lds_dwordx4 v247, s[8:9]
	v_add_u32_e32 v247, 0x80, v247
	s_waitcnt vmcnt(6)
	s_barrier
	s_waitcnt lgkmcnt(0)
	v_mfma_f32_32x32x16_bf16 v[18:33], v[130:133], v[200:203], v[18:33]
	v_mfma_f32_32x32x16_bf16 v[2:17], v[146:149], v[200:203], v[2:17]
	v_mfma_f32_32x32x16_bf16 v[18:33], v[134:137], v[228:231], v[18:33]
	v_mfma_f32_32x32x16_bf16 v[2:17], v[150:153], v[228:231], v[2:17]
	v_mfma_f32_32x32x16_bf16 v[18:33], v[138:141], v[232:235], v[18:33]
	v_mfma_f32_32x32x16_bf16 v[2:17], v[168:171], v[232:235], v[2:17]
	v_mfma_f32_32x32x16_bf16 v[18:33], v[142:145], v[236:239], v[18:33]
	v_mfma_f32_32x32x16_bf16 v[2:17], v[172:175], v[236:239], v[2:17]
	s_add_i32 s11, s11, 2
	s_cmp_lt_u32 s11, 14
	s_barrier
	s_cbranch_scc1 .Lg8_ib
	ds_read_b128 v[130:133], v161
	ds_read_b128 v[134:137], v163
	ds_read_b128 v[138:141], v164
	ds_read_b128 v[142:145], v165
	ds_read_b128 v[146:149], v161 offset:4096
	ds_read_b128 v[150:153], v163 offset:4096
	ds_read_b128 v[168:171], v164 offset:4096
	ds_read_b128 v[172:175], v165 offset:4096
	s_add_u32 m0, s100, 0x14000
	s_nop 0
	global_load_lds_dwordx4 v241, s[6:7]
	s_add_u32 m0, s100, 0x16000
	v_add_u32_e32 v241, 0x80, v241
	global_load_lds_dwordx4 v243, s[6:7]
	v_add_u32_e32 v243, 0x80, v243
	s_barrier
	s_waitcnt lgkmcnt(0)
	v_mfma_f32_32x32x16_bf16 v[114:129], v[130:133], v[176:179], v[114:129]
	v_mfma_f32_32x32x16_bf16 v[98:113], v[146:149], v[176:179], v[98:113]
	v_mfma_f32_32x32x16_bf16 v[114:129], v[134:137], v[180:183], v[114:129]
	v_mfma_f32_32x32x16_bf16 v[98:113], v[150:153], v[180:183], v[98:113]
	v_mfma_f32_32x32x16_bf16 v[114:129], v[138:141], v[192:195], v[114:129]
	v_mfma_f32_32x32x16_bf16 v[98:113], v[168:171], v[192:195], v[98:113]
	v_mfma_f32_32x32x16_bf16 v[114:129], v[142:145], v[196:199], v[114:129]
	v_mfma_f32_32x32x16_bf16 v[98:113], v[172:175], v[196:199], v[98:113]
	s_barrier
	ds_read_b128 v[200:203], v248 offset:49152
	ds_read_b128 v[228:231], v186 offset:49152
	ds_read_b128 v[232:235], v187 offset:49152
	ds_read_b128 v[236:239], v249 offset:49152
	s_barrier
	s_waitcnt lgkmcnt(0)
	v_mfma_f32_32x32x16_bf16 v[82:97], v[130:133], v[200:203], v[82:97]
	v_mfma_f32_32x32x16_bf16 v[50:65], v[146:149], v[200:203], v[50:65]
	v_mfma_f32_32x32x16_bf16 v[82:97], v[134:137], v[228:231], v[82:97]
	v_mfma_f32_32x32x16_bf16 v[50:65], v[150:153], v[228:231], v[50:65]
	v_mfma_f32_32x32x16_bf16 v[82:97], v[138:141], v[232:235], v[82:97]
	v_mfma_f32_32x32x16_bf16 v[50:65], v[168:171], v[232:235], v[50:65]
	v_mfma_f32_32x32x16_bf16 v[82:97], v[142:145], v[236:239], v[82:97]
	v_mfma_f32_32x32x16_bf16 v[50:65], v[172:175], v[236:239], v[50:65]
	s_barrier
; #define MFMA(a, b, c) __builtin_amdgcn_mfma_f32_32x32x16_bf16((a), (b), (c), 0, 0, 0)
; template <bool SWAP>
; DI void gemm_mainloop(f32x16 (&acc)[4][2], const u16* __restrict__ A, int lda, int rlo, int rhi,
;                       const u16* __restrict__ B, int ldb, int K, char* lds, const u16* zero_line) {
;     ...
;   auto mma = [&](int buf) {
; #pragma unroll
;     for (int mi = 0; mi < 4; ++mi)
; #pragma unroll
;       for (int ni = 0; ni < 2; ++ni)
;         acc[mi][ni] = SWAP ? MFMA(fb[buf][ni], fa[buf][mi], acc[mi][ni]) : MFMA(fa[buf][mi], fb[buf][ni], acc[mi][ni]);
;   };
;   auto pat_rd = [&]() {
; #pragma unroll
;     for (int g = 0; g < 6; ++g) {
;       __builtin_amdgcn_sched_group_barrier(0x100, 1, 0);
;       __builtin_amdgcn_sched_group_barrier(0x008, 1, 0);
;     }
;     __builtin_amdgcn_sched_group_barrier(0x008, 2, 0);
;   };
; #pragma unroll 2
;   for (int kt = 0; kt < nk; ++kt) {
;     const char* st = lds + (kt & 1) * 65536;
;     ldfrag(st, 0, 0);
;     mma(1);
;     pat_rd();
;     if (kt + 1 < nk) glds(kt + 1, (kt + 1) & 1);
;     ldfrag(st, 1, 1);
;     mma(0);
;     pat_rd();
;     ldfrag(st, 2, 0);
;     mma(1);
;     pat_rd();
;     ldfrag(st, 3, 1);
;     mma(0);
;     pat_rd();
;     asm volatile("s_waitcnt vmcnt(0)" ::: "memory");
;     __syncthreads();
;   }
;   mma(1);
	ds_read_b128 v[130:133], v161 offset:16384
	ds_read_b128 v[134:137], v163 offset:16384
	ds_read_b128 v[138:141], v164 offset:16384
	ds_read_b128 v[142:145], v165 offset:16384
	ds_read_b128 v[146:149], v161 offset:20480
	ds_read_b128 v[150:153], v163 offset:20480
	ds_read_b128 v[168:171], v164 offset:20480
	ds_read_b128 v[172:175], v165 offset:20480
	s_waitcnt vmcnt(4)
	s_barrier
	s_waitcnt lgkmcnt(0)
	v_mfma_f32_32x32x16_bf16 v[66:81], v[130:133], v[176:179], v[66:81]
	v_mfma_f32_32x32x16_bf16 v[34:49], v[146:149], v[176:179], v[34:49]
	v_mfma_f32_32x32x16_bf16 v[66:81], v[134:137], v[180:183], v[66:81]
	v_mfma_f32_32x32x16_bf16 v[34:49], v[150:153], v[180:183], v[34:49]
	v_mfma_f32_32x32x16_bf16 v[66:81], v[138:141], v[192:195], v[66:81]
	v_mfma_f32_32x32x16_bf16 v[34:49], v[168:171], v[192:195], v[34:49]
	v_mfma_f32_32x32x16_bf16 v[66:81], v[142:145], v[196:199], v[66:81]
	v_mfma_f32_32x32x16_bf16 v[34:49], v[172:175], v[196:199], v[34:49]
	v_mfma_f32_32x32x16_bf16 v[18:33], v[130:133], v[200:203], v[18:33]
	v_mfma_f32_32x32x16_bf16 v[2:17], v[146:149], v[200:203], v[2:17]
	v_mfma_f32_32x32x16_bf16 v[18:33], v[134:137], v[228:231], v[18:33]
	v_mfma_f32_32x32x16_bf16 v[2:17], v[150:153], v[228:231], v[2:17]
	v_mfma_f32_32x32x16_bf16 v[18:33], v[138:141], v[232:235], v[18:33]
	v_mfma_f32_32x32x16_bf16 v[2:17], v[168:171], v[232:235], v[2:17]
	v_mfma_f32_32x32x16_bf16 v[18:33], v[142:145], v[236:239], v[18:33]
	v_mfma_f32_32x32x16_bf16 v[2:17], v[172:175], v[236:239], v[2:17]
	s_barrier
	v_add_u32_e32 v166, s10, v248
	ds_read_b128 v[176:179], v166 offset:32768
	v_add_u32_e32 v166, s10, v186
	ds_read_b128 v[180:183], v166 offset:32768
	v_add_u32_e32 v166, s10, v187
	ds_read_b128 v[192:195], v166 offset:32768
	v_add_u32_e32 v166, s10, v249
	ds_read_b128 v[196:199], v166 offset:32768
	v_add_u32_e32 v166, s10, v161
	ds_read_b128 v[130:133], v166
	ds_read_b128 v[146:149], v166 offset:4096
	v_add_u32_e32 v166, s10, v163
	ds_read_b128 v[134:137], v166
	ds_read_b128 v[150:153], v166 offset:4096
	v_add_u32_e32 v166, s10, v164
	ds_read_b128 v[138:141], v166
	ds_read_b128 v[168:171], v166 offset:4096
	v_add_u32_e32 v166, s10, v165
	ds_read_b128 v[142:145], v166
	ds_read_b128 v[172:175], v166 offset:4096
	s_waitcnt vmcnt(2)
	s_barrier
	s_waitcnt lgkmcnt(0)
	v_mfma_f32_32x32x16_bf16 v[114:129], v[130:133], v[176:179], v[114:129]
	v_mfma_f32_32x32x16_bf16 v[98:113], v[146:149], v[176:179], v[98:113]
	v_mfma_f32_32x32x16_bf16 v[114:129], v[134:137], v[180:183], v[114:129]
	v_mfma_f32_32x32x16_bf16 v[98:113], v[150:153], v[180:183], v[98:113]
	v_mfma_f32_32x32x16_bf16 v[114:129], v[138:141], v[192:195], v[114:129]
	v_mfma_f32_32x32x16_bf16 v[98:113], v[168:171], v[192:195], v[98:113]
	v_mfma_f32_32x32x16_bf16 v[114:129], v[142:145], v[196:199], v[114:129]
	v_mfma_f32_32x32x16_bf16 v[98:113], v[172:175], v[196:199], v[98:113]
	s_barrier
	v_add_u32_e32 v166, s10, v248
	ds_read_b128 v[200:203], v166 offset:49152
	v_add_u32_e32 v166, s10, v186
	ds_read_b128 v[228:231], v166 offset:49152
	v_add_u32_e32 v166, s10, v187
	ds_read_b128 v[232:235], v166 offset:49152
	v_add_u32_e32 v166, s10, v249
	ds_read_b128 v[236:239], v166 offset:49152
	s_waitcnt vmcnt(0)
	s_barrier
	s_waitcnt lgkmcnt(0)
	v_mfma_f32_32x32x16_bf16 v[82:97], v[130:133], v[200:203], v[82:97]
	v_mfma_f32_32x32x16_bf16 v[50:65], v[146:149], v[200:203], v[50:65]
	v_mfma_f32_32x32x16_bf16 v[82:97], v[134:137], v[228:231], v[82:97]
	v_mfma_f32_32x32x16_bf16 v[50:65], v[150:153], v[228:231], v[50:65]
	v_mfma_f32_32x32x16_bf16 v[82:97], v[138:141], v[232:235], v[82:97]
	v_mfma_f32_32x32x16_bf16 v[50:65], v[168:171], v[232:235], v[50:65]
	v_mfma_f32_32x32x16_bf16 v[82:97], v[142:145], v[236:239], v[82:97]
	v_mfma_f32_32x32x16_bf16 v[50:65], v[172:175], v[236:239], v[50:65]
	s_barrier
	v_add_u32_e32 v166, s10, v161
	ds_read_b128 v[130:133], v166 offset:16384
	ds_read_b128 v[146:149], v166 offset:20480
	v_add_u32_e32 v166, s10, v163
	ds_read_b128 v[134:137], v166 offset:16384
	ds_read_b128 v[150:153], v166 offset:20480
	v_add_u32_e32 v166, s10, v164
	ds_read_b128 v[138:141], v166 offset:16384
	ds_read_b128 v[168:171], v166 offset:20480
	v_add_u32_e32 v166, s10, v165
	ds_read_b128 v[142:145], v166 offset:16384
	ds_read_b128 v[172:175], v166 offset:20480
	s_barrier
	s_waitcnt lgkmcnt(0)
	v_mfma_f32_32x32x16_bf16 v[66:81], v[130:133], v[176:179], v[66:81]
	v_mfma_f32_32x32x16_bf16 v[34:49], v[146:149], v[176:179], v[34:49]
	v_mfma_f32_32x32x16_bf16 v[66:81], v[134:137], v[180:183], v[66:81]
	v_mfma_f32_32x32x16_bf16 v[34:49], v[150:153], v[180:183], v[34:49]
	v_mfma_f32_32x32x16_bf16 v[66:81], v[138:141], v[192:195], v[66:81]
	v_mfma_f32_32x32x16_bf16 v[34:49], v[168:171], v[192:195], v[34:49]
	v_mfma_f32_32x32x16_bf16 v[66:81], v[142:145], v[196:199], v[66:81]
	v_mfma_f32_32x32x16_bf16 v[34:49], v[172:175], v[196:199], v[34:49]
	v_mfma_f32_32x32x16_bf16 v[18:33], v[130:133], v[200:203], v[18:33]
	v_mfma_f32_32x32x16_bf16 v[2:17], v[146:149], v[200:203], v[2:17]
	v_mfma_f32_32x32x16_bf16 v[18:33], v[134:137], v[228:231], v[18:33]
	v_mfma_f32_32x32x16_bf16 v[2:17], v[150:153], v[228:231], v[2:17]
	v_mfma_f32_32x32x16_bf16 v[18:33], v[138:141], v[232:235], v[18:33]
	v_mfma_f32_32x32x16_bf16 v[2:17], v[168:171], v[232:235], v[2:17]
	v_mfma_f32_32x32x16_bf16 v[18:33], v[142:145], v[236:239], v[18:33]
	v_mfma_f32_32x32x16_bf16 v[2:17], v[172:175], v[236:239], v[2:17]
	s_barrier
	s_cmp_eq_u32 s101, 0
	s_cbranch_scc0 .Lg8_ib_p1
	s_barrier
